# GEMM loops: all 16 LDS-DMA address adds per iteration folded into saddr+voffset form (two SGPR bases precomputed per iteration for the second half-tile), on top of setprio/barrier-edge edit and f8f6f4
# speedup vs baseline: 1.0155x; 1.0036x over previous
; #define PG8_STAGE(bufoff, gbase, voff) do { _Pragma("unroll") for (int _i = 0; _i < 2; ++_i) \
;         __builtin_amdgcn_global_load_lds((const unsigned*)((const char*)(gbase) + (voff)[_i]), (LAS unsigned*)(lds + (bufoff) + ldsw + _i * 8192), 16, 0, 0); } while (0)
; #define PG8_LDA(dst, b, h) do { _Pragma("unroll") for (int m = 0; m < 4; ++m) _Pragma("unroll") for (int k = 0; k < 2; ++k) dst[m][k] = *(const LAS bf16x8*)(lds + PG8_SA(b, h) + aoff + m * 2048 + k * 1024); } while (0)
; #define PG8_LDB(dst, b, h) do { _Pragma("unroll") for (int n = 0; n < 2; ++n) _Pragma("unroll") for (int k = 0; k < 2; ++k) dst[n][k] = *(const LAS bf16x8*)(lds + PG8_SB(b, h) + boff + n * 2048 + k * 1024); } while (0)
; #define PG8_WAIT_V(n) asm volatile("s_waitcnt vmcnt(" #n ")" ::: "memory")
; #define PG8_WAIT_L(n) asm volatile("s_waitcnt lgkmcnt(" #n ")" ::: "memory")
; #define PG8_BAR __builtin_amdgcn_s_barrier()
; #define PG8_SCHED __builtin_amdgcn_sched_barrier(0)
; template <class Epi, bool FP8 = false>
; __device__ __forceinline__ void gemm_phase(LAS unsigned char* lds, const Gemm g, const StaticOrder& S_, const Epi& E, const int tid) {
;     ...
;             const bool last = (t == nt - 2);
;             const char* a1 = cA + (size_t)(t + 1) * kstep;
;             const char* a2 = last ? nA : cA + (size_t)(t + 2) * kstep; const char* b2 = last ? nB : cB + (size_t)(t + 2) * kstep;
;             const char* a3 = a2 + kstep; const char* b3 = b2 + kstep;
;             PG8_LDB(B0, 0, 0); PG8_LDB(B1, 0, 1); PG8_SCHED; PG8_LDA(At, 0, 0); PG8_STAGE(PG8_SA(1, 1), a1 + hstepA, voffA);
;             PG8_WAIT_V(8); PG8_WAIT_L(0); PG8_BAR; PG8_MMA(0, 0, At, B0); PG8_MMA(0, 1, At, B1); PG8_BAR; PG8_SCHED;
;             PG8_LDA(At, 0, 1); PG8_STAGE(PG8_SB(0, 0), b2, voffB); PG8_STAGE(PG8_SB(0, 1), b2 + hstepB, voffB); PG8_STAGE(PG8_SA(0, 0), a2, voffA);
;             PG8_WAIT_V(8); PG8_WAIT_L(0); PG8_BAR; PG8_MMA(1, 0, At, B0); PG8_MMA(1, 1, At, B1); PG8_BAR; PG8_SCHED;
.LBB0_233:
	ds_read_b128 v[150:153], v147
	ds_read_b128 v[154:157], v147 offset:1024
	ds_read_b128 v[158:161], v147 offset:2048
	ds_read_b128 v[162:165], v147 offset:3072
	ds_read_b128 v[166:169], v148
	ds_read_b128 v[170:173], v148 offset:1024
	ds_read_b128 v[174:177], v148 offset:2048
	ds_read_b128 v[178:181], v148 offset:3072
	s_add_u32 s44, s30, 0xfff80080
	s_addc_u32 s45, s31, -1
	s_cmp_eq_u32 s70, 28
	s_cselect_b32 s47, s17, s45
	s_cselect_b32 s46, s43, s44
	s_cselect_b32 s45, s15, s69
	s_cselect_b32 s44, s66, s68
	s_add_i32 m0, s29, 0xc000
	ds_read_b128 v[182:185], v149
	ds_read_b128 v[186:189], v149 offset:1024
	ds_read_b128 v[190:193], v149 offset:2048
	ds_read_b128 v[194:197], v149 offset:3072
	ds_read_b128 v[198:201], v149 offset:4096
	ds_read_b128 v[202:205], v149 offset:5120
	ds_read_b128 v[206:209], v149 offset:6144
	ds_read_b128 v[210:213], v149 offset:7168
	global_load_lds_dwordx4 v136, s[30:31]
	s_add_i32 m0, s29, 0xe000
	s_nop 0
	global_load_lds_dwordx4 v138, s[30:31]
	s_waitcnt vmcnt(8)
	s_waitcnt lgkmcnt(0)
	s_setprio 1
	s_barrier
	v_mfma_f32_16x16x32_bf16 v[124:127], v[150:153], v[182:185], v[124:127]
	v_mfma_f32_16x16x32_bf16 v[120:123], v[158:161], v[182:185], v[120:123]
	v_mfma_f32_16x16x32_bf16 v[108:111], v[150:153], v[190:193], v[108:111]
	v_mfma_f32_16x16x32_bf16 v[104:107], v[158:161], v[190:193], v[104:107]
	v_mfma_f32_16x16x32_bf16 v[92:95], v[150:153], v[198:201], v[92:95]
	v_mfma_f32_16x16x32_bf16 v[88:91], v[158:161], v[198:201], v[88:91]
	v_mfma_f32_16x16x32_bf16 v[76:79], v[150:153], v[206:209], v[76:79]
	v_mfma_f32_16x16x32_bf16 v[72:75], v[158:161], v[206:209], v[72:75]
	v_mfma_f32_16x16x32_bf16 v[124:127], v[154:157], v[186:189], v[124:127]
	v_mfma_f32_16x16x32_bf16 v[120:123], v[162:165], v[186:189], v[120:123]
	v_mfma_f32_16x16x32_bf16 v[108:111], v[154:157], v[194:197], v[108:111]
	v_mfma_f32_16x16x32_bf16 v[104:107], v[162:165], v[194:197], v[104:107]
	v_mfma_f32_16x16x32_bf16 v[92:95], v[154:157], v[202:205], v[92:95]
	v_mfma_f32_16x16x32_bf16 v[88:91], v[162:165], v[202:205], v[88:91]
	v_mfma_f32_16x16x32_bf16 v[76:79], v[154:157], v[210:213], v[76:79]
	v_mfma_f32_16x16x32_bf16 v[72:75], v[162:165], v[210:213], v[72:75]
	v_mfma_f32_16x16x32_bf16 v[116:119], v[166:169], v[182:185], v[116:119]
	v_mfma_f32_16x16x32_bf16 v[112:115], v[174:177], v[182:185], v[112:115]
	v_mfma_f32_16x16x32_bf16 v[100:103], v[166:169], v[190:193], v[100:103]
	v_mfma_f32_16x16x32_bf16 v[96:99], v[174:177], v[190:193], v[96:99]
	v_mfma_f32_16x16x32_bf16 v[84:87], v[166:169], v[198:201], v[84:87]
	v_mfma_f32_16x16x32_bf16 v[80:83], v[174:177], v[198:201], v[80:83]
	v_mfma_f32_16x16x32_bf16 v[68:71], v[166:169], v[206:209], v[68:71]
	v_mfma_f32_16x16x32_bf16 v[64:67], v[174:177], v[206:209], v[64:67]
	v_mfma_f32_16x16x32_bf16 v[116:119], v[170:173], v[186:189], v[116:119]
	v_mfma_f32_16x16x32_bf16 v[112:115], v[178:181], v[186:189], v[112:115]
	v_mfma_f32_16x16x32_bf16 v[100:103], v[170:173], v[194:197], v[100:103]
	v_mfma_f32_16x16x32_bf16 v[96:99], v[178:181], v[194:197], v[96:99]
	v_mfma_f32_16x16x32_bf16 v[84:87], v[170:173], v[202:205], v[84:87]
	v_mfma_f32_16x16x32_bf16 v[80:83], v[178:181], v[202:205], v[80:83]
	v_mfma_f32_16x16x32_bf16 v[68:71], v[170:173], v[210:213], v[68:71]
	v_mfma_f32_16x16x32_bf16 v[64:67], v[178:181], v[210:213], v[64:67]
	s_setprio 0
	s_barrier
	s_add_u32 s98, s44, s10
	s_addc_u32 s99, s45, s11
	s_add_u32 s100, s46, s10
	s_addc_u32 s101, s47, s11
	s_add_i32 s71, s61, s51
	s_mov_b32 m0, s71
	ds_read_b128 v[182:185], v149 offset:16384
	ds_read_b128 v[186:189], v149 offset:17408
	ds_read_b128 v[190:193], v149 offset:18432
	ds_read_b128 v[194:197], v149 offset:19456
	ds_read_b128 v[198:201], v149 offset:20480
	ds_read_b128 v[202:205], v149 offset:21504
	ds_read_b128 v[206:209], v149 offset:22528
	ds_read_b128 v[210:213], v149 offset:23552
	global_load_lds_dwordx4 v128, s[44:45]
	s_add_i32 m0, s71, 0x2000
	s_add_u32 s72, s44, 0x80000
	s_addc_u32 s73, s45, 0
	s_add_i32 s71, s62, s51
	global_load_lds_dwordx4 v130, s[44:45]
	s_mov_b32 m0, s71
	s_nop 0
	global_load_lds_dwordx4 v128, s[72:73]
	s_add_i32 m0, s71, 0x2000
	s_nop 0
	global_load_lds_dwordx4 v130, s[72:73]
	s_mov_b32 m0, s29
	s_nop 0
	global_load_lds_dwordx4 v134, s[46:47]
	s_mov_b32 m0, s54
	s_nop 0
	global_load_lds_dwordx4 v132, s[46:47]
	s_waitcnt vmcnt(8)
	s_waitcnt lgkmcnt(0)
	s_setprio 1
	s_barrier
	v_mfma_f32_16x16x32_bf16 v[60:63], v[150:153], v[182:185], v[60:63]
	v_mfma_f32_16x16x32_bf16 v[56:59], v[158:161], v[182:185], v[56:59]
	v_mfma_f32_16x16x32_bf16 v[44:47], v[150:153], v[190:193], v[44:47]
	v_mfma_f32_16x16x32_bf16 v[40:43], v[158:161], v[190:193], v[40:43]
	v_mfma_f32_16x16x32_bf16 v[28:31], v[150:153], v[198:201], v[28:31]
	v_mfma_f32_16x16x32_bf16 v[24:27], v[158:161], v[198:201], v[24:27]
	v_mfma_f32_16x16x32_bf16 v[12:15], v[150:153], v[206:209], v[12:15]
	v_mfma_f32_16x16x32_bf16 v[8:11], v[158:161], v[206:209], v[8:11]
	v_mfma_f32_16x16x32_bf16 v[60:63], v[154:157], v[186:189], v[60:63]
	v_mfma_f32_16x16x32_bf16 v[56:59], v[162:165], v[186:189], v[56:59]
	v_mfma_f32_16x16x32_bf16 v[44:47], v[154:157], v[194:197], v[44:47]
	v_mfma_f32_16x16x32_bf16 v[40:43], v[162:165], v[194:197], v[40:43]
	v_mfma_f32_16x16x32_bf16 v[28:31], v[154:157], v[202:205], v[28:31]
	v_mfma_f32_16x16x32_bf16 v[24:27], v[162:165], v[202:205], v[24:27]
	v_mfma_f32_16x16x32_bf16 v[12:15], v[154:157], v[210:213], v[12:15]
	v_mfma_f32_16x16x32_bf16 v[8:11], v[162:165], v[210:213], v[8:11]
	v_mfma_f32_16x16x32_bf16 v[52:55], v[166:169], v[182:185], v[52:55]
	v_mfma_f32_16x16x32_bf16 v[48:51], v[174:177], v[182:185], v[48:51]
	v_mfma_f32_16x16x32_bf16 v[36:39], v[166:169], v[190:193], v[36:39]
	v_mfma_f32_16x16x32_bf16 v[32:35], v[174:177], v[190:193], v[32:35]
	v_mfma_f32_16x16x32_bf16 v[20:23], v[166:169], v[198:201], v[20:23]
	v_mfma_f32_16x16x32_bf16 v[16:19], v[174:177], v[198:201], v[16:19]
	v_mfma_f32_16x16x32_bf16 v[4:7], v[166:169], v[206:209], v[4:7]
	v_mfma_f32_16x16x32_bf16 v[0:3], v[174:177], v[206:209], v[0:3]
	v_mfma_f32_16x16x32_bf16 v[52:55], v[170:173], v[186:189], v[52:55]
	v_mfma_f32_16x16x32_bf16 v[48:51], v[178:181], v[186:189], v[48:51]
	v_mfma_f32_16x16x32_bf16 v[36:39], v[170:173], v[194:197], v[36:39]
	v_mfma_f32_16x16x32_bf16 v[32:35], v[178:181], v[194:197], v[32:35]
	v_mfma_f32_16x16x32_bf16 v[20:23], v[170:173], v[202:205], v[20:23]
	v_mfma_f32_16x16x32_bf16 v[16:19], v[178:181], v[202:205], v[16:19]
	v_mfma_f32_16x16x32_bf16 v[4:7], v[170:173], v[210:213], v[4:7]
	v_mfma_f32_16x16x32_bf16 v[0:3], v[178:181], v[210:213], v[0:3]
	s_setprio 0
	s_barrier
; #define PG8_STAGE(bufoff, gbase, voff) do { _Pragma("unroll") for (int _i = 0; _i < 2; ++_i) \
;         __builtin_amdgcn_global_load_lds((const unsigned*)((const char*)(gbase) + (voff)[_i]), (LAS unsigned*)(lds + (bufoff) + ldsw + _i * 8192), 16, 0, 0); } while (0)
; #define PG8_LDA(dst, b, h) do { _Pragma("unroll") for (int m = 0; m < 4; ++m) _Pragma("unroll") for (int k = 0; k < 2; ++k) dst[m][k] = *(const LAS bf16x8*)(lds + PG8_SA(b, h) + aoff + m * 2048 + k * 1024); } while (0)
; #define PG8_LDB(dst, b, h) do { _Pragma("unroll") for (int n = 0; n < 2; ++n) _Pragma("unroll") for (int k = 0; k < 2; ++k) dst[n][k] = *(const LAS bf16x8*)(lds + PG8_SB(b, h) + boff + n * 2048 + k * 1024); } while (0)
; #define PG8_WAIT_V(n) asm volatile("s_waitcnt vmcnt(" #n ")" ::: "memory")
; #define PG8_WAIT_L(n) asm volatile("s_waitcnt lgkmcnt(" #n ")" ::: "memory")
; #define PG8_BAR __builtin_amdgcn_s_barrier()
; #define PG8_SCHED __builtin_amdgcn_sched_barrier(0)
; template <class Epi, bool FP8 = false>
; __device__ __forceinline__ void gemm_phase(LAS unsigned char* lds, const Gemm g, const StaticOrder& S_, const Epi& E, const int tid) {
;     ...
;             PG8_LDB(B0, 1, 0); PG8_LDB(B1, 1, 1); PG8_SCHED; PG8_LDA(At, 1, 0); PG8_STAGE(PG8_SA(0, 1), a2 + hstepA, voffA);
;             PG8_WAIT_V(8); PG8_WAIT_L(0); PG8_BAR; PG8_MMA(0, 0, At, B0); PG8_MMA(0, 1, At, B1); PG8_BAR; PG8_SCHED;
;             PG8_LDA(At, 1, 1); PG8_STAGE(PG8_SB(1, 0), b3, voffB); PG8_STAGE(PG8_SB(1, 1), b3 + hstepB, voffB); PG8_STAGE(PG8_SA(1, 0), a3, voffA);
;             PG8_WAIT_V(8); PG8_WAIT_L(0); PG8_BAR; PG8_MMA(1, 0, At, B0); PG8_MMA(1, 1, At, B1); PG8_BAR; PG8_SCHED;
;         }
;         if (wr == 0) PG8_BAR;
	s_add_i32 s71, 0, 0x18000
	s_add_i32 s72, 0, 0x1c000
	v_add_u32_e32 v162, s71, v145
	v_add_u32_e32 v178, s72, v145
	ds_read_b128 v[150:153], v162
	ds_read_b128 v[154:157], v162 offset:1024
	ds_read_b128 v[158:161], v162 offset:2048
	ds_read_b128 v[162:165], v162 offset:3072
	ds_read_b128 v[166:169], v178
	ds_read_b128 v[170:173], v178 offset:1024
	ds_read_b128 v[174:177], v178 offset:2048
	ds_read_b128 v[178:181], v178 offset:3072
	s_add_u32 s46, s46, 0x80000
	s_addc_u32 s47, s47, 0
	s_mov_b32 m0, s55
	ds_read_b128 v[182:185], v149 offset:32768
	ds_read_b128 v[186:189], v149 offset:33792
	ds_read_b128 v[190:193], v149 offset:34816
	ds_read_b128 v[194:197], v149 offset:35840
	ds_read_b128 v[198:201], v149 offset:36864
	ds_read_b128 v[202:205], v149 offset:37888
	ds_read_b128 v[206:209], v149 offset:38912
	ds_read_b128 v[210:213], v149 offset:39936
	global_load_lds_dwordx4 v134, s[46:47]
	s_mov_b32 m0, s56
	s_nop 0
	global_load_lds_dwordx4 v132, s[46:47]
	s_waitcnt vmcnt(8)
	s_waitcnt lgkmcnt(0)
	s_setprio 1
	s_barrier
	v_mfma_f32_16x16x32_bf16 v[124:127], v[150:153], v[182:185], v[124:127]
	v_mfma_f32_16x16x32_bf16 v[120:123], v[158:161], v[182:185], v[120:123]
	v_mfma_f32_16x16x32_bf16 v[108:111], v[150:153], v[190:193], v[108:111]
	v_mfma_f32_16x16x32_bf16 v[104:107], v[158:161], v[190:193], v[104:107]
	v_mfma_f32_16x16x32_bf16 v[92:95], v[150:153], v[198:201], v[92:95]
	v_mfma_f32_16x16x32_bf16 v[88:91], v[158:161], v[198:201], v[88:91]
	v_mfma_f32_16x16x32_bf16 v[76:79], v[150:153], v[206:209], v[76:79]
	v_mfma_f32_16x16x32_bf16 v[72:75], v[158:161], v[206:209], v[72:75]
	v_mfma_f32_16x16x32_bf16 v[124:127], v[154:157], v[186:189], v[124:127]
	v_mfma_f32_16x16x32_bf16 v[120:123], v[162:165], v[186:189], v[120:123]
	v_mfma_f32_16x16x32_bf16 v[108:111], v[154:157], v[194:197], v[108:111]
	v_mfma_f32_16x16x32_bf16 v[104:107], v[162:165], v[194:197], v[104:107]
	v_mfma_f32_16x16x32_bf16 v[92:95], v[154:157], v[202:205], v[92:95]
	v_mfma_f32_16x16x32_bf16 v[88:91], v[162:165], v[202:205], v[88:91]
	v_mfma_f32_16x16x32_bf16 v[76:79], v[154:157], v[210:213], v[76:79]
	v_mfma_f32_16x16x32_bf16 v[72:75], v[162:165], v[210:213], v[72:75]
	v_mfma_f32_16x16x32_bf16 v[116:119], v[166:169], v[182:185], v[116:119]
	v_mfma_f32_16x16x32_bf16 v[112:115], v[174:177], v[182:185], v[112:115]
	v_mfma_f32_16x16x32_bf16 v[100:103], v[166:169], v[190:193], v[100:103]
	v_mfma_f32_16x16x32_bf16 v[96:99], v[174:177], v[190:193], v[96:99]
	v_mfma_f32_16x16x32_bf16 v[84:87], v[166:169], v[198:201], v[84:87]
	v_mfma_f32_16x16x32_bf16 v[80:83], v[174:177], v[198:201], v[80:83]
	v_mfma_f32_16x16x32_bf16 v[68:71], v[166:169], v[206:209], v[68:71]
	v_mfma_f32_16x16x32_bf16 v[64:67], v[174:177], v[206:209], v[64:67]
	v_mfma_f32_16x16x32_bf16 v[116:119], v[170:173], v[186:189], v[116:119]
	v_mfma_f32_16x16x32_bf16 v[112:115], v[178:181], v[186:189], v[112:115]
	v_mfma_f32_16x16x32_bf16 v[100:103], v[170:173], v[194:197], v[100:103]
	v_mfma_f32_16x16x32_bf16 v[96:99], v[178:181], v[194:197], v[96:99]
	v_mfma_f32_16x16x32_bf16 v[84:87], v[170:173], v[202:205], v[84:87]
	v_mfma_f32_16x16x32_bf16 v[80:83], v[178:181], v[202:205], v[80:83]
	v_mfma_f32_16x16x32_bf16 v[68:71], v[170:173], v[210:213], v[68:71]
	v_mfma_f32_16x16x32_bf16 v[64:67], v[178:181], v[210:213], v[64:67]
	s_setprio 0
	s_barrier
	s_add_i32 s46, s71, s51
	s_mov_b32 m0, s46
	ds_read_b128 v[182:185], v149 offset:49152
	ds_read_b128 v[186:189], v149 offset:50176
	ds_read_b128 v[190:193], v149 offset:51200
	ds_read_b128 v[194:197], v149 offset:52224
	ds_read_b128 v[198:201], v149 offset:53248
	ds_read_b128 v[202:205], v149 offset:54272
	ds_read_b128 v[206:209], v149 offset:55296
	ds_read_b128 v[210:213], v149 offset:56320
	global_load_lds_dwordx4 v128, s[98:99]
	s_add_i32 m0, s46, 0x2000
	s_add_u32 s44, s44, 0x80080
	s_addc_u32 s45, s45, 0
	s_add_i32 s46, s72, s51
	global_load_lds_dwordx4 v130, s[98:99]
	s_mov_b32 m0, s46
	s_nop 0
	global_load_lds_dwordx4 v128, s[44:45]
	s_add_i32 m0, s46, 0x2000
	s_nop 0
	global_load_lds_dwordx4 v130, s[44:45]
	s_mov_b32 m0, s58
	s_nop 0
	global_load_lds_dwordx4 v134, s[100:101]
	s_mov_b32 m0, s59
	s_nop 0
	global_load_lds_dwordx4 v132, s[100:101]
	s_waitcnt vmcnt(8)
	s_waitcnt lgkmcnt(0)
	s_setprio 1
	s_barrier
	v_mfma_f32_16x16x32_bf16 v[60:63], v[150:153], v[182:185], v[60:63]
	v_mfma_f32_16x16x32_bf16 v[56:59], v[158:161], v[182:185], v[56:59]
	v_mfma_f32_16x16x32_bf16 v[44:47], v[150:153], v[190:193], v[44:47]
	v_mfma_f32_16x16x32_bf16 v[40:43], v[158:161], v[190:193], v[40:43]
	v_mfma_f32_16x16x32_bf16 v[28:31], v[150:153], v[198:201], v[28:31]
	v_mfma_f32_16x16x32_bf16 v[24:27], v[158:161], v[198:201], v[24:27]
	v_mfma_f32_16x16x32_bf16 v[12:15], v[150:153], v[206:209], v[12:15]
	v_mfma_f32_16x16x32_bf16 v[8:11], v[158:161], v[206:209], v[8:11]
	v_mfma_f32_16x16x32_bf16 v[60:63], v[154:157], v[186:189], v[60:63]
	v_mfma_f32_16x16x32_bf16 v[56:59], v[162:165], v[186:189], v[56:59]
	v_mfma_f32_16x16x32_bf16 v[44:47], v[154:157], v[194:197], v[44:47]
	v_mfma_f32_16x16x32_bf16 v[40:43], v[162:165], v[194:197], v[40:43]
	v_mfma_f32_16x16x32_bf16 v[28:31], v[154:157], v[202:205], v[28:31]
	v_mfma_f32_16x16x32_bf16 v[24:27], v[162:165], v[202:205], v[24:27]
	v_mfma_f32_16x16x32_bf16 v[12:15], v[154:157], v[210:213], v[12:15]
	v_mfma_f32_16x16x32_bf16 v[8:11], v[162:165], v[210:213], v[8:11]
	v_mfma_f32_16x16x32_bf16 v[52:55], v[166:169], v[182:185], v[52:55]
	v_mfma_f32_16x16x32_bf16 v[48:51], v[174:177], v[182:185], v[48:51]
	v_mfma_f32_16x16x32_bf16 v[36:39], v[166:169], v[190:193], v[36:39]
	v_mfma_f32_16x16x32_bf16 v[32:35], v[174:177], v[190:193], v[32:35]
	v_mfma_f32_16x16x32_bf16 v[20:23], v[166:169], v[198:201], v[20:23]
	v_mfma_f32_16x16x32_bf16 v[16:19], v[174:177], v[198:201], v[16:19]
	v_mfma_f32_16x16x32_bf16 v[4:7], v[166:169], v[206:209], v[4:7]
	v_mfma_f32_16x16x32_bf16 v[0:3], v[174:177], v[206:209], v[0:3]
	v_mfma_f32_16x16x32_bf16 v[52:55], v[170:173], v[186:189], v[52:55]
	v_mfma_f32_16x16x32_bf16 v[48:51], v[178:181], v[186:189], v[48:51]
	v_mfma_f32_16x16x32_bf16 v[36:39], v[170:173], v[194:197], v[36:39]
	v_mfma_f32_16x16x32_bf16 v[32:35], v[178:181], v[194:197], v[32:35]
	v_mfma_f32_16x16x32_bf16 v[20:23], v[170:173], v[202:205], v[20:23]
	v_mfma_f32_16x16x32_bf16 v[16:19], v[178:181], v[202:205], v[16:19]
	v_mfma_f32_16x16x32_bf16 v[4:7], v[170:173], v[210:213], v[4:7]
	v_mfma_f32_16x16x32_bf16 v[0:3], v[178:181], v[210:213], v[0:3]
	s_setprio 0
	s_barrier
	s_add_i32 s70, s70, 2
	s_add_u32 s30, s30, 0x100
	s_addc_u32 s31, s31, 0
	s_add_u32 s68, s68, 0x100
	s_addc_u32 s69, s69, 0
	s_cmp_gt_u32 s70, 29
	s_cbranch_scc0 .LBB0_233
	s_and_b64 vcc, exec, s[12:13]
	s_cbranch_vccz .LBB0_236
	s_barrier

; #define PG8_STAGE(bufoff, gbase, voff) do { _Pragma("unroll") for (int _i = 0; _i < 2; ++_i) \
;         __builtin_amdgcn_global_load_lds((const unsigned*)((const char*)(gbase) + (voff)[_i]), (LAS unsigned*)(lds + (bufoff) + ldsw + _i * 8192), 16, 0, 0); } while (0)
; #define PG8_LDA(dst, b, h) do { _Pragma("unroll") for (int m = 0; m < 4; ++m) _Pragma("unroll") for (int k = 0; k < 2; ++k) dst[m][k] = *(const LAS bf16x8*)(lds + PG8_SA(b, h) + aoff + m * 2048 + k * 1024); } while (0)
; #define PG8_LDB(dst, b, h) do { _Pragma("unroll") for (int n = 0; n < 2; ++n) _Pragma("unroll") for (int k = 0; k < 2; ++k) dst[n][k] = *(const LAS bf16x8*)(lds + PG8_SB(b, h) + boff + n * 2048 + k * 1024); } while (0)
; #define PG8_WAIT_V(n) asm volatile("s_waitcnt vmcnt(" #n ")" ::: "memory")
; #define PG8_WAIT_L(n) asm volatile("s_waitcnt lgkmcnt(" #n ")" ::: "memory")
; #define PG8_BAR __builtin_amdgcn_s_barrier()
; #define PG8_SCHED __builtin_amdgcn_sched_barrier(0)
; template <class Epi, bool FP8 = false>
; __device__ __forceinline__ void gemm_phase(LAS unsigned char* lds, const Gemm g, const StaticOrder& S_, const Epi& E, const int tid) {
;     ...
;             const bool last = (t == nt - 2);
;             const char* a1 = cA + (size_t)(t + 1) * kstep;
;             const char* a2 = last ? nA : cA + (size_t)(t + 2) * kstep; const char* b2 = last ? nB : cB + (size_t)(t + 2) * kstep;
;             const char* a3 = a2 + kstep; const char* b3 = b2 + kstep;
;             PG8_LDB(B0, 0, 0); PG8_LDB(B1, 0, 1); PG8_SCHED; PG8_LDA(At, 0, 0); PG8_STAGE(PG8_SA(1, 1), a1 + hstepA, voffA);
;             PG8_WAIT_V(8); PG8_WAIT_L(0); PG8_BAR; PG8_MMA(0, 0, At, B0); PG8_MMA(0, 1, At, B1); PG8_BAR; PG8_SCHED;
;             PG8_LDA(At, 0, 1); PG8_STAGE(PG8_SB(0, 0), b2, voffB); PG8_STAGE(PG8_SB(0, 1), b2 + hstepB, voffB); PG8_STAGE(PG8_SA(0, 0), a2, voffA);
;             PG8_WAIT_V(8); PG8_WAIT_L(0); PG8_BAR; PG8_MMA(1, 0, At, B0); PG8_MMA(1, 1, At, B1); PG8_BAR; PG8_SCHED;
.LBB0_319:
	ds_read_b128 v[150:153], v146
	ds_read_b128 v[154:157], v146 offset:1024
	ds_read_b128 v[158:161], v146 offset:2048
	ds_read_b128 v[162:165], v146 offset:3072
	ds_read_b128 v[166:169], v147
	ds_read_b128 v[170:173], v147 offset:1024
	ds_read_b128 v[174:177], v147 offset:2048
	ds_read_b128 v[178:181], v147 offset:3072
	s_add_u32 s50, s48, 0x100
	s_addc_u32 s51, s49, 0
	s_cmpk_eq_i32 s77, 0x54
	s_cselect_b32 s55, s7, s51
	s_cselect_b32 s54, s6, s50
	s_cselect_b32 s53, s45, s76
	s_cselect_b32 s52, s44, s75
	s_add_i32 m0, s60, 0xc000
	ds_read_b128 v[182:185], v148
	ds_read_b128 v[186:189], v148 offset:1024
	ds_read_b128 v[190:193], v148 offset:2048
	ds_read_b128 v[194:197], v148 offset:3072
	ds_read_b128 v[198:201], v148 offset:4096
	ds_read_b128 v[202:205], v148 offset:5120
	ds_read_b128 v[206:209], v148 offset:6144
	ds_read_b128 v[210:213], v148 offset:7168
	global_load_lds_dwordx4 v132, s[48:49]
	s_add_i32 m0, s60, 0xe000
	s_nop 0
	global_load_lds_dwordx4 v134, s[48:49]
	s_waitcnt vmcnt(8)
	s_waitcnt lgkmcnt(0)
	s_setprio 1
	s_barrier
	v_mfma_f32_16x16x32_bf16 v[124:127], v[150:153], v[182:185], v[124:127]
	v_mfma_f32_16x16x32_bf16 v[120:123], v[158:161], v[182:185], v[120:123]
	v_mfma_f32_16x16x32_bf16 v[112:115], v[150:153], v[190:193], v[112:115]
	v_mfma_f32_16x16x32_bf16 v[104:107], v[158:161], v[190:193], v[104:107]
	v_mfma_f32_16x16x32_bf16 v[96:99], v[150:153], v[198:201], v[96:99]
	v_mfma_f32_16x16x32_bf16 v[88:91], v[158:161], v[198:201], v[88:91]
	v_mfma_f32_16x16x32_bf16 v[80:83], v[150:153], v[206:209], v[80:83]
	v_mfma_f32_16x16x32_bf16 v[72:75], v[158:161], v[206:209], v[72:75]
	v_mfma_f32_16x16x32_bf16 v[124:127], v[154:157], v[186:189], v[124:127]
	v_mfma_f32_16x16x32_bf16 v[120:123], v[162:165], v[186:189], v[120:123]
	v_mfma_f32_16x16x32_bf16 v[112:115], v[154:157], v[194:197], v[112:115]
	v_mfma_f32_16x16x32_bf16 v[104:107], v[162:165], v[194:197], v[104:107]
	v_mfma_f32_16x16x32_bf16 v[96:99], v[154:157], v[202:205], v[96:99]
	v_mfma_f32_16x16x32_bf16 v[88:91], v[162:165], v[202:205], v[88:91]
	v_mfma_f32_16x16x32_bf16 v[80:83], v[154:157], v[210:213], v[80:83]
	v_mfma_f32_16x16x32_bf16 v[72:75], v[162:165], v[210:213], v[72:75]
	v_mfma_f32_16x16x32_bf16 v[116:119], v[166:169], v[182:185], v[116:119]
	v_mfma_f32_16x16x32_bf16 v[108:111], v[174:177], v[182:185], v[108:111]
	v_mfma_f32_16x16x32_bf16 v[100:103], v[166:169], v[190:193], v[100:103]
	v_mfma_f32_16x16x32_bf16 v[92:95], v[174:177], v[190:193], v[92:95]
	v_mfma_f32_16x16x32_bf16 v[84:87], v[166:169], v[198:201], v[84:87]
	v_mfma_f32_16x16x32_bf16 v[76:79], v[174:177], v[198:201], v[76:79]
	v_mfma_f32_16x16x32_bf16 v[68:71], v[166:169], v[206:209], v[68:71]
	v_mfma_f32_16x16x32_bf16 v[64:67], v[174:177], v[206:209], v[64:67]
	v_mfma_f32_16x16x32_bf16 v[116:119], v[170:173], v[186:189], v[116:119]
	v_mfma_f32_16x16x32_bf16 v[108:111], v[178:181], v[186:189], v[108:111]
	v_mfma_f32_16x16x32_bf16 v[100:103], v[170:173], v[194:197], v[100:103]
	v_mfma_f32_16x16x32_bf16 v[92:95], v[178:181], v[194:197], v[92:95]
	v_mfma_f32_16x16x32_bf16 v[84:87], v[170:173], v[202:205], v[84:87]
	v_mfma_f32_16x16x32_bf16 v[76:79], v[178:181], v[202:205], v[76:79]
	v_mfma_f32_16x16x32_bf16 v[68:71], v[170:173], v[210:213], v[68:71]
	v_mfma_f32_16x16x32_bf16 v[64:67], v[178:181], v[210:213], v[64:67]
	s_setprio 0
	s_barrier
	s_add_u32 s98, s52, s14
	s_addc_u32 s99, s53, s15
	s_add_u32 s100, s54, s14
	s_addc_u32 s101, s55, s15
	s_add_i32 s48, s71, s59
	s_mov_b32 m0, s48
	ds_read_b128 v[182:185], v148 offset:16384
	ds_read_b128 v[186:189], v148 offset:17408
	ds_read_b128 v[190:193], v148 offset:18432
	ds_read_b128 v[194:197], v148 offset:19456
	ds_read_b128 v[198:201], v148 offset:20480
	ds_read_b128 v[202:205], v148 offset:21504
	ds_read_b128 v[206:209], v148 offset:22528
	ds_read_b128 v[210:213], v148 offset:23552
	global_load_lds_dwordx4 v128, s[52:53]
	s_add_i32 m0, s48, 0x2000
	s_add_u32 s48, s52, 0x160000
	s_addc_u32 s49, s53, 0
	s_add_i32 s78, s72, s59
	global_load_lds_dwordx4 v130, s[52:53]
	s_mov_b32 m0, s78
	s_nop 0
	global_load_lds_dwordx4 v128, s[48:49]
	s_add_i32 m0, s78, 0x2000
	s_nop 0
	global_load_lds_dwordx4 v130, s[48:49]
	s_mov_b32 m0, s60
	s_nop 0
	global_load_lds_dwordx4 v128, s[54:55]
	s_mov_b32 m0, s61
	s_nop 0
	global_load_lds_dwordx4 v130, s[54:55]
	s_waitcnt vmcnt(8)
	s_waitcnt lgkmcnt(0)
	s_setprio 1
	s_barrier
	v_mfma_f32_16x16x32_bf16 v[60:63], v[150:153], v[182:185], v[60:63]
	v_mfma_f32_16x16x32_bf16 v[56:59], v[158:161], v[182:185], v[56:59]
	v_mfma_f32_16x16x32_bf16 v[48:51], v[150:153], v[190:193], v[48:51]
	v_mfma_f32_16x16x32_bf16 v[40:43], v[158:161], v[190:193], v[40:43]
	v_mfma_f32_16x16x32_bf16 v[32:35], v[150:153], v[198:201], v[32:35]
	v_mfma_f32_16x16x32_bf16 v[24:27], v[158:161], v[198:201], v[24:27]
	v_mfma_f32_16x16x32_bf16 v[16:19], v[150:153], v[206:209], v[16:19]
	v_mfma_f32_16x16x32_bf16 v[8:11], v[158:161], v[206:209], v[8:11]
	v_mfma_f32_16x16x32_bf16 v[60:63], v[154:157], v[186:189], v[60:63]
	v_mfma_f32_16x16x32_bf16 v[56:59], v[162:165], v[186:189], v[56:59]
	v_mfma_f32_16x16x32_bf16 v[48:51], v[154:157], v[194:197], v[48:51]
	v_mfma_f32_16x16x32_bf16 v[40:43], v[162:165], v[194:197], v[40:43]
	v_mfma_f32_16x16x32_bf16 v[32:35], v[154:157], v[202:205], v[32:35]
	v_mfma_f32_16x16x32_bf16 v[24:27], v[162:165], v[202:205], v[24:27]
	v_mfma_f32_16x16x32_bf16 v[16:19], v[154:157], v[210:213], v[16:19]
	v_mfma_f32_16x16x32_bf16 v[8:11], v[162:165], v[210:213], v[8:11]
	v_mfma_f32_16x16x32_bf16 v[52:55], v[166:169], v[182:185], v[52:55]
	v_mfma_f32_16x16x32_bf16 v[44:47], v[174:177], v[182:185], v[44:47]
	v_mfma_f32_16x16x32_bf16 v[36:39], v[166:169], v[190:193], v[36:39]
	v_mfma_f32_16x16x32_bf16 v[28:31], v[174:177], v[190:193], v[28:31]
	v_mfma_f32_16x16x32_bf16 v[20:23], v[166:169], v[198:201], v[20:23]
	v_mfma_f32_16x16x32_bf16 v[12:15], v[174:177], v[198:201], v[12:15]
	v_mfma_f32_16x16x32_bf16 v[4:7], v[166:169], v[206:209], v[4:7]
	v_mfma_f32_16x16x32_bf16 v[0:3], v[174:177], v[206:209], v[0:3]
	v_mfma_f32_16x16x32_bf16 v[52:55], v[170:173], v[186:189], v[52:55]
	v_mfma_f32_16x16x32_bf16 v[44:47], v[178:181], v[186:189], v[44:47]
	v_mfma_f32_16x16x32_bf16 v[36:39], v[170:173], v[194:197], v[36:39]
	v_mfma_f32_16x16x32_bf16 v[28:31], v[178:181], v[194:197], v[28:31]
	v_mfma_f32_16x16x32_bf16 v[20:23], v[170:173], v[202:205], v[20:23]
	v_mfma_f32_16x16x32_bf16 v[12:15], v[178:181], v[202:205], v[12:15]
	v_mfma_f32_16x16x32_bf16 v[4:7], v[170:173], v[210:213], v[4:7]
	v_mfma_f32_16x16x32_bf16 v[0:3], v[178:181], v[210:213], v[0:3]
	s_setprio 0
	s_barrier
; #define PG8_STAGE(bufoff, gbase, voff) do { _Pragma("unroll") for (int _i = 0; _i < 2; ++_i) \
;         __builtin_amdgcn_global_load_lds((const unsigned*)((const char*)(gbase) + (voff)[_i]), (LAS unsigned*)(lds + (bufoff) + ldsw + _i * 8192), 16, 0, 0); } while (0)
; #define PG8_LDA(dst, b, h) do { _Pragma("unroll") for (int m = 0; m < 4; ++m) _Pragma("unroll") for (int k = 0; k < 2; ++k) dst[m][k] = *(const LAS bf16x8*)(lds + PG8_SA(b, h) + aoff + m * 2048 + k * 1024); } while (0)
; #define PG8_LDB(dst, b, h) do { _Pragma("unroll") for (int n = 0; n < 2; ++n) _Pragma("unroll") for (int k = 0; k < 2; ++k) dst[n][k] = *(const LAS bf16x8*)(lds + PG8_SB(b, h) + boff + n * 2048 + k * 1024); } while (0)
; #define PG8_WAIT_V(n) asm volatile("s_waitcnt vmcnt(" #n ")" ::: "memory")
; #define PG8_WAIT_L(n) asm volatile("s_waitcnt lgkmcnt(" #n ")" ::: "memory")
; #define PG8_BAR __builtin_amdgcn_s_barrier()
; #define PG8_SCHED __builtin_amdgcn_sched_barrier(0)
; template <class Epi, bool FP8 = false>
; __device__ __forceinline__ void gemm_phase(LAS unsigned char* lds, const Gemm g, const StaticOrder& S_, const Epi& E, const int tid) {
;     ...
;             PG8_LDB(B0, 1, 0); PG8_LDB(B1, 1, 1); PG8_SCHED; PG8_LDA(At, 1, 0); PG8_STAGE(PG8_SA(0, 1), a2 + hstepA, voffA);
;             PG8_WAIT_V(8); PG8_WAIT_L(0); PG8_BAR; PG8_MMA(0, 0, At, B0); PG8_MMA(0, 1, At, B1); PG8_BAR; PG8_SCHED;
;             PG8_LDA(At, 1, 1); PG8_STAGE(PG8_SB(1, 0), b3, voffB); PG8_STAGE(PG8_SB(1, 1), b3 + hstepB, voffB); PG8_STAGE(PG8_SA(1, 0), a3, voffA);
;             PG8_WAIT_V(8); PG8_WAIT_L(0); PG8_BAR; PG8_MMA(1, 0, At, B0); PG8_MMA(1, 1, At, B1); PG8_BAR; PG8_SCHED;
;         }
;         if (wr == 0) PG8_BAR;
	s_add_i32 s78, 0, 0x18000
	v_add_u32_e32 v149, s78, v144
	s_add_i32 s79, 0, 0x1c000
	ds_read_b128 v[150:153], v149
	ds_read_b128 v[154:157], v149 offset:1024
	ds_read_b128 v[158:161], v149 offset:2048
	ds_read_b128 v[162:165], v149 offset:3072
	v_add_u32_e32 v149, s79, v144
	ds_read_b128 v[166:169], v149
	ds_read_b128 v[170:173], v149 offset:1024
	ds_read_b128 v[174:177], v149 offset:2048
	ds_read_b128 v[178:181], v149 offset:3072
	s_add_u32 s48, s54, 0x160000
	s_addc_u32 s49, s55, 0
	s_mov_b32 m0, s62
	ds_read_b128 v[182:185], v148 offset:32768
	ds_read_b128 v[186:189], v148 offset:33792
	ds_read_b128 v[190:193], v148 offset:34816
	ds_read_b128 v[194:197], v148 offset:35840
	ds_read_b128 v[198:201], v148 offset:36864
	ds_read_b128 v[202:205], v148 offset:37888
	ds_read_b128 v[206:209], v148 offset:38912
	ds_read_b128 v[210:213], v148 offset:39936
	global_load_lds_dwordx4 v128, s[48:49]
	s_mov_b32 m0, s63
	s_nop 0
	global_load_lds_dwordx4 v130, s[48:49]
	s_waitcnt vmcnt(8)
	s_waitcnt lgkmcnt(0)
	s_setprio 1
	s_barrier
	v_mfma_f32_16x16x32_bf16 v[124:127], v[150:153], v[182:185], v[124:127]
	v_mfma_f32_16x16x32_bf16 v[120:123], v[158:161], v[182:185], v[120:123]
	v_mfma_f32_16x16x32_bf16 v[112:115], v[150:153], v[190:193], v[112:115]
	v_mfma_f32_16x16x32_bf16 v[104:107], v[158:161], v[190:193], v[104:107]
	v_mfma_f32_16x16x32_bf16 v[96:99], v[150:153], v[198:201], v[96:99]
	v_mfma_f32_16x16x32_bf16 v[88:91], v[158:161], v[198:201], v[88:91]
	v_mfma_f32_16x16x32_bf16 v[80:83], v[150:153], v[206:209], v[80:83]
	v_mfma_f32_16x16x32_bf16 v[72:75], v[158:161], v[206:209], v[72:75]
	v_mfma_f32_16x16x32_bf16 v[124:127], v[154:157], v[186:189], v[124:127]
	v_mfma_f32_16x16x32_bf16 v[120:123], v[162:165], v[186:189], v[120:123]
	v_mfma_f32_16x16x32_bf16 v[112:115], v[154:157], v[194:197], v[112:115]
	v_mfma_f32_16x16x32_bf16 v[104:107], v[162:165], v[194:197], v[104:107]
	v_mfma_f32_16x16x32_bf16 v[96:99], v[154:157], v[202:205], v[96:99]
	v_mfma_f32_16x16x32_bf16 v[88:91], v[162:165], v[202:205], v[88:91]
	v_mfma_f32_16x16x32_bf16 v[80:83], v[154:157], v[210:213], v[80:83]
	v_mfma_f32_16x16x32_bf16 v[72:75], v[162:165], v[210:213], v[72:75]
	v_mfma_f32_16x16x32_bf16 v[116:119], v[166:169], v[182:185], v[116:119]
	v_mfma_f32_16x16x32_bf16 v[108:111], v[174:177], v[182:185], v[108:111]
	v_mfma_f32_16x16x32_bf16 v[100:103], v[166:169], v[190:193], v[100:103]
	v_mfma_f32_16x16x32_bf16 v[92:95], v[174:177], v[190:193], v[92:95]
	v_mfma_f32_16x16x32_bf16 v[84:87], v[166:169], v[198:201], v[84:87]
	v_mfma_f32_16x16x32_bf16 v[76:79], v[174:177], v[198:201], v[76:79]
	v_mfma_f32_16x16x32_bf16 v[68:71], v[166:169], v[206:209], v[68:71]
	v_mfma_f32_16x16x32_bf16 v[64:67], v[174:177], v[206:209], v[64:67]
	v_mfma_f32_16x16x32_bf16 v[116:119], v[170:173], v[186:189], v[116:119]
	v_mfma_f32_16x16x32_bf16 v[108:111], v[178:181], v[186:189], v[108:111]
	v_mfma_f32_16x16x32_bf16 v[100:103], v[170:173], v[194:197], v[100:103]
	v_mfma_f32_16x16x32_bf16 v[92:95], v[178:181], v[194:197], v[92:95]
	v_mfma_f32_16x16x32_bf16 v[84:87], v[170:173], v[202:205], v[84:87]
	v_mfma_f32_16x16x32_bf16 v[76:79], v[178:181], v[202:205], v[76:79]
	v_mfma_f32_16x16x32_bf16 v[68:71], v[170:173], v[210:213], v[68:71]
	v_mfma_f32_16x16x32_bf16 v[64:67], v[178:181], v[210:213], v[64:67]
	s_setprio 0
	s_barrier
	s_add_i32 s48, s78, s59
	s_mov_b32 m0, s48
	ds_read_b128 v[182:185], v148 offset:49152
	ds_read_b128 v[186:189], v148 offset:50176
	ds_read_b128 v[190:193], v148 offset:51200
	ds_read_b128 v[194:197], v148 offset:52224
	ds_read_b128 v[198:201], v148 offset:53248
	ds_read_b128 v[202:205], v148 offset:54272
	ds_read_b128 v[206:209], v148 offset:55296
	ds_read_b128 v[210:213], v148 offset:56320
	global_load_lds_dwordx4 v128, s[98:99]
	s_add_i32 m0, s48, 0x2000
	s_add_u32 s48, s52, 0x160080
	s_addc_u32 s49, s53, 0
	s_add_i32 s52, s79, s59
	global_load_lds_dwordx4 v130, s[98:99]
	s_mov_b32 m0, s52
	s_nop 0
	global_load_lds_dwordx4 v128, s[48:49]
	s_add_i32 m0, s52, 0x2000
	s_nop 0
	global_load_lds_dwordx4 v130, s[48:49]
	s_mov_b32 m0, s68
	s_nop 0
	global_load_lds_dwordx4 v128, s[100:101]
	s_mov_b32 m0, s69
	s_nop 0
	global_load_lds_dwordx4 v130, s[100:101]
	s_waitcnt vmcnt(8)
	s_waitcnt lgkmcnt(0)
	s_setprio 1
	s_barrier
	v_mfma_f32_16x16x32_bf16 v[60:63], v[150:153], v[182:185], v[60:63]
	v_mfma_f32_16x16x32_bf16 v[56:59], v[158:161], v[182:185], v[56:59]
	v_mfma_f32_16x16x32_bf16 v[48:51], v[150:153], v[190:193], v[48:51]
	v_mfma_f32_16x16x32_bf16 v[40:43], v[158:161], v[190:193], v[40:43]
	v_mfma_f32_16x16x32_bf16 v[32:35], v[150:153], v[198:201], v[32:35]
	v_mfma_f32_16x16x32_bf16 v[24:27], v[158:161], v[198:201], v[24:27]
	v_mfma_f32_16x16x32_bf16 v[16:19], v[150:153], v[206:209], v[16:19]
	v_mfma_f32_16x16x32_bf16 v[8:11], v[158:161], v[206:209], v[8:11]
	v_mfma_f32_16x16x32_bf16 v[60:63], v[154:157], v[186:189], v[60:63]
	v_mfma_f32_16x16x32_bf16 v[56:59], v[162:165], v[186:189], v[56:59]
	v_mfma_f32_16x16x32_bf16 v[48:51], v[154:157], v[194:197], v[48:51]
	v_mfma_f32_16x16x32_bf16 v[40:43], v[162:165], v[194:197], v[40:43]
	v_mfma_f32_16x16x32_bf16 v[32:35], v[154:157], v[202:205], v[32:35]
	v_mfma_f32_16x16x32_bf16 v[24:27], v[162:165], v[202:205], v[24:27]
	v_mfma_f32_16x16x32_bf16 v[16:19], v[154:157], v[210:213], v[16:19]
	v_mfma_f32_16x16x32_bf16 v[8:11], v[162:165], v[210:213], v[8:11]
	v_mfma_f32_16x16x32_bf16 v[52:55], v[166:169], v[182:185], v[52:55]
	v_mfma_f32_16x16x32_bf16 v[44:47], v[174:177], v[182:185], v[44:47]
	v_mfma_f32_16x16x32_bf16 v[36:39], v[166:169], v[190:193], v[36:39]
	v_mfma_f32_16x16x32_bf16 v[28:31], v[174:177], v[190:193], v[28:31]
	v_mfma_f32_16x16x32_bf16 v[20:23], v[166:169], v[198:201], v[20:23]
	v_mfma_f32_16x16x32_bf16 v[12:15], v[174:177], v[198:201], v[12:15]
	v_mfma_f32_16x16x32_bf16 v[4:7], v[166:169], v[206:209], v[4:7]
	v_mfma_f32_16x16x32_bf16 v[0:3], v[174:177], v[206:209], v[0:3]
	v_mfma_f32_16x16x32_bf16 v[52:55], v[170:173], v[186:189], v[52:55]
	v_mfma_f32_16x16x32_bf16 v[44:47], v[178:181], v[186:189], v[44:47]
	v_mfma_f32_16x16x32_bf16 v[36:39], v[170:173], v[194:197], v[36:39]
	v_mfma_f32_16x16x32_bf16 v[28:31], v[178:181], v[194:197], v[28:31]
	v_mfma_f32_16x16x32_bf16 v[20:23], v[170:173], v[202:205], v[20:23]
	v_mfma_f32_16x16x32_bf16 v[12:15], v[178:181], v[202:205], v[12:15]
	v_mfma_f32_16x16x32_bf16 v[4:7], v[170:173], v[210:213], v[4:7]
	v_mfma_f32_16x16x32_bf16 v[0:3], v[178:181], v[210:213], v[0:3]
	s_setprio 0
	s_barrier
	s_add_i32 s77, s77, 2
	s_add_u32 s75, s75, 0x100
	s_addc_u32 s76, s76, 0
	s_cmpk_gt_u32 s77, 0x55
	s_mov_b64 s[48:49], s[50:51]
	s_cbranch_scc0 .LBB0_319
	s_and_b64 vcc, exec, s[16:17]
	s_cbranch_vccz .LBB0_322
	s_barrier

; #define PG8_STAGE(bufoff, gbase, voff) do { _Pragma("unroll") for (int _i = 0; _i < 2; ++_i) \
;         __builtin_amdgcn_global_load_lds((const unsigned*)((const char*)(gbase) + (voff)[_i]), (LAS unsigned*)(lds + (bufoff) + ldsw + _i * 8192), 16, 0, 0); } while (0)
; #define PG8_LDA(dst, b, h) do { _Pragma("unroll") for (int m = 0; m < 4; ++m) _Pragma("unroll") for (int k = 0; k < 2; ++k) dst[m][k] = *(const LAS bf16x8*)(lds + PG8_SA(b, h) + aoff + m * 2048 + k * 1024); } while (0)
; #define PG8_LDB(dst, b, h) do { _Pragma("unroll") for (int n = 0; n < 2; ++n) _Pragma("unroll") for (int k = 0; k < 2; ++k) dst[n][k] = *(const LAS bf16x8*)(lds + PG8_SB(b, h) + boff + n * 2048 + k * 1024); } while (0)
; #define PG8_WAIT_V(n) asm volatile("s_waitcnt vmcnt(" #n ")" ::: "memory")
; #define PG8_WAIT_L(n) asm volatile("s_waitcnt lgkmcnt(" #n ")" ::: "memory")
; #define PG8_BAR __builtin_amdgcn_s_barrier()
; #define PG8_SCHED __builtin_amdgcn_sched_barrier(0)
; template <class Epi, bool FP8 = false>
; __device__ __forceinline__ void gemm_phase(LAS unsigned char* lds, const Gemm g, const StaticOrder& S_, const Epi& E, const int tid) {
;     ...
;             const bool last = (t == nt - 2);
;             const char* a1 = cA + (size_t)(t + 1) * kstep;
;             const char* a2 = last ? nA : cA + (size_t)(t + 2) * kstep; const char* b2 = last ? nB : cB + (size_t)(t + 2) * kstep;
;             const char* a3 = a2 + kstep; const char* b3 = b2 + kstep;
;             PG8_LDB(B0, 0, 0); PG8_LDB(B1, 0, 1); PG8_SCHED; PG8_LDA(At, 0, 0); PG8_STAGE(PG8_SA(1, 1), a1 + hstepA, voffA);
;             PG8_WAIT_V(8); PG8_WAIT_L(0); PG8_BAR; PG8_MMA(0, 0, At, B0); PG8_MMA(0, 1, At, B1); PG8_BAR; PG8_SCHED;
;             PG8_LDA(At, 0, 1); PG8_STAGE(PG8_SB(0, 0), b2, voffB); PG8_STAGE(PG8_SB(0, 1), b2 + hstepB, voffB); PG8_STAGE(PG8_SA(0, 0), a2, voffA);
;             PG8_WAIT_V(8); PG8_WAIT_L(0); PG8_BAR; PG8_MMA(1, 0, At, B0); PG8_MMA(1, 1, At, B1); PG8_BAR; PG8_SCHED;
.LBB0_457:
	ds_read_b128 v[128:131], v190
	ds_read_b128 v[132:135], v190 offset:1024
	ds_read_b128 v[136:139], v190 offset:2048
	ds_read_b128 v[140:143], v190 offset:3072
	ds_read_b128 v[182:185], v192
	ds_read_b128 v[194:197], v192 offset:1024
	ds_read_b128 v[198:201], v192 offset:2048
	ds_read_b128 v[202:205], v192 offset:3072
	s_add_u32 s56, s54, 0xfff80080
	s_addc_u32 s57, s55, -1
	s_cmp_eq_u32 s61, 28
	s_cselect_b32 s59, s7, s57
	s_cselect_b32 s58, s42, s56
	s_cselect_b32 s57, s27, s60
	s_cselect_b32 s56, s43, s49
	s_add_i32 m0, s71, 0xc000
	ds_read_b128 v[206:209], v191
	ds_read_b128 v[210:213], v191 offset:1024
	ds_read_b128 v[214:217], v191 offset:2048
	ds_read_b128 v[218:221], v191 offset:3072
	ds_read_b128 v[222:225], v191 offset:4096
	ds_read_b128 v[226:229], v191 offset:5120
	ds_read_b128 v[230:233], v191 offset:6144
	ds_read_b128 v[234:237], v191 offset:7168
	global_load_lds_dwordx4 v174, s[54:55]
	s_add_i32 m0, s71, 0xe000
	s_nop 0
	global_load_lds_dwordx4 v176, s[54:55]
	s_waitcnt vmcnt(8)
	s_waitcnt lgkmcnt(0)
	s_setprio 1
	s_barrier
	v_mfma_f32_16x16x32_bf16 v[124:127], v[128:131], v[206:209], v[124:127]
	v_mfma_f32_16x16x32_bf16 v[120:123], v[136:139], v[206:209], v[120:123]
	v_mfma_f32_16x16x32_bf16 v[108:111], v[128:131], v[214:217], v[108:111]
	v_mfma_f32_16x16x32_bf16 v[104:107], v[136:139], v[214:217], v[104:107]
	v_mfma_f32_16x16x32_bf16 v[92:95], v[128:131], v[222:225], v[92:95]
	v_mfma_f32_16x16x32_bf16 v[88:91], v[136:139], v[222:225], v[88:91]
	v_mfma_f32_16x16x32_bf16 v[76:79], v[128:131], v[230:233], v[76:79]
	v_mfma_f32_16x16x32_bf16 v[72:75], v[136:139], v[230:233], v[72:75]
	v_mfma_f32_16x16x32_bf16 v[124:127], v[132:135], v[210:213], v[124:127]
	v_mfma_f32_16x16x32_bf16 v[120:123], v[140:143], v[210:213], v[120:123]
	v_mfma_f32_16x16x32_bf16 v[108:111], v[132:135], v[218:221], v[108:111]
	v_mfma_f32_16x16x32_bf16 v[104:107], v[140:143], v[218:221], v[104:107]
	v_mfma_f32_16x16x32_bf16 v[92:95], v[132:135], v[226:229], v[92:95]
	v_mfma_f32_16x16x32_bf16 v[88:91], v[140:143], v[226:229], v[88:91]
	v_mfma_f32_16x16x32_bf16 v[76:79], v[132:135], v[234:237], v[76:79]
	v_mfma_f32_16x16x32_bf16 v[72:75], v[140:143], v[234:237], v[72:75]
	v_mfma_f32_16x16x32_bf16 v[116:119], v[182:185], v[206:209], v[116:119]
	v_mfma_f32_16x16x32_bf16 v[112:115], v[198:201], v[206:209], v[112:115]
	v_mfma_f32_16x16x32_bf16 v[100:103], v[182:185], v[214:217], v[100:103]
	v_mfma_f32_16x16x32_bf16 v[96:99], v[198:201], v[214:217], v[96:99]
	v_mfma_f32_16x16x32_bf16 v[84:87], v[182:185], v[222:225], v[84:87]
	v_mfma_f32_16x16x32_bf16 v[80:83], v[198:201], v[222:225], v[80:83]
	v_mfma_f32_16x16x32_bf16 v[68:71], v[182:185], v[230:233], v[68:71]
	v_mfma_f32_16x16x32_bf16 v[64:67], v[198:201], v[230:233], v[64:67]
	v_mfma_f32_16x16x32_bf16 v[116:119], v[194:197], v[210:213], v[116:119]
	v_mfma_f32_16x16x32_bf16 v[112:115], v[202:205], v[210:213], v[112:115]
	v_mfma_f32_16x16x32_bf16 v[100:103], v[194:197], v[218:221], v[100:103]
	v_mfma_f32_16x16x32_bf16 v[96:99], v[202:205], v[218:221], v[96:99]
	v_mfma_f32_16x16x32_bf16 v[84:87], v[194:197], v[226:229], v[84:87]
	v_mfma_f32_16x16x32_bf16 v[80:83], v[202:205], v[226:229], v[80:83]
	v_mfma_f32_16x16x32_bf16 v[68:71], v[194:197], v[234:237], v[68:71]
	v_mfma_f32_16x16x32_bf16 v[64:67], v[202:205], v[234:237], v[64:67]
	s_setprio 0
	s_barrier
	s_add_u32 s98, s56, s14
	s_addc_u32 s99, s57, s15
	s_add_u32 s100, s58, s14
	s_addc_u32 s101, s59, s15
	s_add_i32 s62, s85, s70
	s_mov_b32 m0, s62
	ds_read_b128 v[206:209], v191 offset:16384
	ds_read_b128 v[210:213], v191 offset:17408
	ds_read_b128 v[214:217], v191 offset:18432
	ds_read_b128 v[218:221], v191 offset:19456
	ds_read_b128 v[222:225], v191 offset:20480
	ds_read_b128 v[226:229], v191 offset:21504
	ds_read_b128 v[230:233], v191 offset:22528
	ds_read_b128 v[234:237], v191 offset:23552
	global_load_lds_dwordx4 v146, s[56:57]
	s_add_i32 m0, s62, 0x2000
	s_add_u32 s62, s56, 0x80000
	s_addc_u32 s63, s57, 0
	s_add_i32 s66, s86, s70
	global_load_lds_dwordx4 v150, s[56:57]
	s_mov_b32 m0, s66
	s_nop 0
	global_load_lds_dwordx4 v146, s[62:63]
	s_add_i32 m0, s66, 0x2000
	s_nop 0
	global_load_lds_dwordx4 v150, s[62:63]
	s_mov_b32 m0, s71
	s_nop 0
	global_load_lds_dwordx4 v144, s[58:59]
	s_mov_b32 m0, s72
	s_nop 0
	global_load_lds_dwordx4 v148, s[58:59]
	s_waitcnt vmcnt(8)
	s_waitcnt lgkmcnt(0)
	s_setprio 1
	s_barrier
	v_mfma_f32_16x16x32_bf16 v[60:63], v[128:131], v[206:209], v[60:63]
	v_mfma_f32_16x16x32_bf16 v[56:59], v[136:139], v[206:209], v[56:59]
	v_mfma_f32_16x16x32_bf16 v[44:47], v[128:131], v[214:217], v[44:47]
	v_mfma_f32_16x16x32_bf16 v[40:43], v[136:139], v[214:217], v[40:43]
	v_mfma_f32_16x16x32_bf16 v[28:31], v[128:131], v[222:225], v[28:31]
	v_mfma_f32_16x16x32_bf16 v[24:27], v[136:139], v[222:225], v[24:27]
	v_mfma_f32_16x16x32_bf16 v[12:15], v[128:131], v[230:233], v[12:15]
	v_mfma_f32_16x16x32_bf16 v[8:11], v[136:139], v[230:233], v[8:11]
	v_mfma_f32_16x16x32_bf16 v[60:63], v[132:135], v[210:213], v[60:63]
	v_mfma_f32_16x16x32_bf16 v[56:59], v[140:143], v[210:213], v[56:59]
	v_mfma_f32_16x16x32_bf16 v[44:47], v[132:135], v[218:221], v[44:47]
	v_mfma_f32_16x16x32_bf16 v[40:43], v[140:143], v[218:221], v[40:43]
	v_mfma_f32_16x16x32_bf16 v[28:31], v[132:135], v[226:229], v[28:31]
	v_mfma_f32_16x16x32_bf16 v[24:27], v[140:143], v[226:229], v[24:27]
	v_mfma_f32_16x16x32_bf16 v[12:15], v[132:135], v[234:237], v[12:15]
	v_mfma_f32_16x16x32_bf16 v[8:11], v[140:143], v[234:237], v[8:11]
	v_mfma_f32_16x16x32_bf16 v[52:55], v[182:185], v[206:209], v[52:55]
	v_mfma_f32_16x16x32_bf16 v[48:51], v[198:201], v[206:209], v[48:51]
	v_mfma_f32_16x16x32_bf16 v[36:39], v[182:185], v[214:217], v[36:39]
	v_mfma_f32_16x16x32_bf16 v[32:35], v[198:201], v[214:217], v[32:35]
	v_mfma_f32_16x16x32_bf16 v[20:23], v[182:185], v[222:225], v[20:23]
	v_mfma_f32_16x16x32_bf16 v[16:19], v[198:201], v[222:225], v[16:19]
	v_mfma_f32_16x16x32_bf16 v[4:7], v[182:185], v[230:233], v[4:7]
	v_mfma_f32_16x16x32_bf16 v[0:3], v[198:201], v[230:233], v[0:3]
	v_mfma_f32_16x16x32_bf16 v[52:55], v[194:197], v[210:213], v[52:55]
	v_mfma_f32_16x16x32_bf16 v[48:51], v[202:205], v[210:213], v[48:51]
	v_mfma_f32_16x16x32_bf16 v[36:39], v[194:197], v[218:221], v[36:39]
	v_mfma_f32_16x16x32_bf16 v[32:35], v[202:205], v[218:221], v[32:35]
	v_mfma_f32_16x16x32_bf16 v[20:23], v[194:197], v[226:229], v[20:23]
	v_mfma_f32_16x16x32_bf16 v[16:19], v[202:205], v[226:229], v[16:19]
	v_mfma_f32_16x16x32_bf16 v[4:7], v[194:197], v[234:237], v[4:7]
	v_mfma_f32_16x16x32_bf16 v[0:3], v[202:205], v[234:237], v[0:3]
	s_setprio 0
	s_barrier
; #define PG8_STAGE(bufoff, gbase, voff) do { _Pragma("unroll") for (int _i = 0; _i < 2; ++_i) \
;         __builtin_amdgcn_global_load_lds((const unsigned*)((const char*)(gbase) + (voff)[_i]), (LAS unsigned*)(lds + (bufoff) + ldsw + _i * 8192), 16, 0, 0); } while (0)
; #define PG8_LDA(dst, b, h) do { _Pragma("unroll") for (int m = 0; m < 4; ++m) _Pragma("unroll") for (int k = 0; k < 2; ++k) dst[m][k] = *(const LAS bf16x8*)(lds + PG8_SA(b, h) + aoff + m * 2048 + k * 1024); } while (0)
; #define PG8_LDB(dst, b, h) do { _Pragma("unroll") for (int n = 0; n < 2; ++n) _Pragma("unroll") for (int k = 0; k < 2; ++k) dst[n][k] = *(const LAS bf16x8*)(lds + PG8_SB(b, h) + boff + n * 2048 + k * 1024); } while (0)
; #define PG8_WAIT_V(n) asm volatile("s_waitcnt vmcnt(" #n ")" ::: "memory")
; #define PG8_WAIT_L(n) asm volatile("s_waitcnt lgkmcnt(" #n ")" ::: "memory")
; #define PG8_BAR __builtin_amdgcn_s_barrier()
; #define PG8_SCHED __builtin_amdgcn_sched_barrier(0)
; template <class Epi, bool FP8 = false>
; __device__ __forceinline__ void gemm_phase(LAS unsigned char* lds, const Gemm g, const StaticOrder& S_, const Epi& E, const int tid) {
;     ...
;             PG8_LDB(B0, 1, 0); PG8_LDB(B1, 1, 1); PG8_SCHED; PG8_LDA(At, 1, 0); PG8_STAGE(PG8_SA(0, 1), a2 + hstepA, voffA);
;             PG8_WAIT_V(8); PG8_WAIT_L(0); PG8_BAR; PG8_MMA(0, 0, At, B0); PG8_MMA(0, 1, At, B1); PG8_BAR; PG8_SCHED;
;             PG8_LDA(At, 1, 1); PG8_STAGE(PG8_SB(1, 0), b3, voffB); PG8_STAGE(PG8_SB(1, 1), b3 + hstepB, voffB); PG8_STAGE(PG8_SA(1, 0), a3, voffA);
;             PG8_WAIT_V(8); PG8_WAIT_L(0); PG8_BAR; PG8_MMA(1, 0, At, B0); PG8_MMA(1, 1, At, B1); PG8_BAR; PG8_SCHED;
;         }
;         if (wr == 0) PG8_BAR;
	s_add_i32 s62, 0, 0x18000
	s_add_i32 s63, 0, 0x1c000
	v_add_u32_e32 v140, s62, v163
	v_add_u32_e32 v152, s63, v163
	ds_read_b128 v[128:131], v140
	ds_read_b128 v[132:135], v140 offset:1024
	ds_read_b128 v[136:139], v140 offset:2048
	ds_read_b128 v[140:143], v140 offset:3072
	ds_read_b128 v[182:185], v152
	ds_read_b128 v[194:197], v152 offset:1024
	ds_read_b128 v[198:201], v152 offset:2048
	ds_read_b128 v[202:205], v152 offset:3072
	s_add_u32 s58, s58, 0x80000
	s_addc_u32 s59, s59, 0
	s_mov_b32 m0, s73
	ds_read_b128 v[206:209], v191 offset:32768
	ds_read_b128 v[210:213], v191 offset:33792
	ds_read_b128 v[214:217], v191 offset:34816
	ds_read_b128 v[218:221], v191 offset:35840
	ds_read_b128 v[222:225], v191 offset:36864
	ds_read_b128 v[226:229], v191 offset:37888
	ds_read_b128 v[230:233], v191 offset:38912
	ds_read_b128 v[234:237], v191 offset:39936
	global_load_lds_dwordx4 v144, s[58:59]
	s_mov_b32 m0, s74
	s_nop 0
	global_load_lds_dwordx4 v148, s[58:59]
	s_waitcnt vmcnt(8)
	s_waitcnt lgkmcnt(0)
	s_setprio 1
	s_barrier
	v_mfma_f32_16x16x32_bf16 v[124:127], v[128:131], v[206:209], v[124:127]
	v_mfma_f32_16x16x32_bf16 v[120:123], v[136:139], v[206:209], v[120:123]
	v_mfma_f32_16x16x32_bf16 v[108:111], v[128:131], v[214:217], v[108:111]
	v_mfma_f32_16x16x32_bf16 v[104:107], v[136:139], v[214:217], v[104:107]
	v_mfma_f32_16x16x32_bf16 v[92:95], v[128:131], v[222:225], v[92:95]
	v_mfma_f32_16x16x32_bf16 v[88:91], v[136:139], v[222:225], v[88:91]
	v_mfma_f32_16x16x32_bf16 v[76:79], v[128:131], v[230:233], v[76:79]
	v_mfma_f32_16x16x32_bf16 v[72:75], v[136:139], v[230:233], v[72:75]
	v_mfma_f32_16x16x32_bf16 v[124:127], v[132:135], v[210:213], v[124:127]
	v_mfma_f32_16x16x32_bf16 v[120:123], v[140:143], v[210:213], v[120:123]
	v_mfma_f32_16x16x32_bf16 v[108:111], v[132:135], v[218:221], v[108:111]
	v_mfma_f32_16x16x32_bf16 v[104:107], v[140:143], v[218:221], v[104:107]
	v_mfma_f32_16x16x32_bf16 v[92:95], v[132:135], v[226:229], v[92:95]
	v_mfma_f32_16x16x32_bf16 v[88:91], v[140:143], v[226:229], v[88:91]
	v_mfma_f32_16x16x32_bf16 v[76:79], v[132:135], v[234:237], v[76:79]
	v_mfma_f32_16x16x32_bf16 v[72:75], v[140:143], v[234:237], v[72:75]
	v_mfma_f32_16x16x32_bf16 v[116:119], v[182:185], v[206:209], v[116:119]
	v_mfma_f32_16x16x32_bf16 v[112:115], v[198:201], v[206:209], v[112:115]
	v_mfma_f32_16x16x32_bf16 v[100:103], v[182:185], v[214:217], v[100:103]
	v_mfma_f32_16x16x32_bf16 v[96:99], v[198:201], v[214:217], v[96:99]
	v_mfma_f32_16x16x32_bf16 v[84:87], v[182:185], v[222:225], v[84:87]
	v_mfma_f32_16x16x32_bf16 v[80:83], v[198:201], v[222:225], v[80:83]
	v_mfma_f32_16x16x32_bf16 v[68:71], v[182:185], v[230:233], v[68:71]
	v_mfma_f32_16x16x32_bf16 v[64:67], v[198:201], v[230:233], v[64:67]
	v_mfma_f32_16x16x32_bf16 v[116:119], v[194:197], v[210:213], v[116:119]
	v_mfma_f32_16x16x32_bf16 v[112:115], v[202:205], v[210:213], v[112:115]
	v_mfma_f32_16x16x32_bf16 v[100:103], v[194:197], v[218:221], v[100:103]
	v_mfma_f32_16x16x32_bf16 v[96:99], v[202:205], v[218:221], v[96:99]
	v_mfma_f32_16x16x32_bf16 v[84:87], v[194:197], v[226:229], v[84:87]
	v_mfma_f32_16x16x32_bf16 v[80:83], v[202:205], v[226:229], v[80:83]
	v_mfma_f32_16x16x32_bf16 v[68:71], v[194:197], v[234:237], v[68:71]
	v_mfma_f32_16x16x32_bf16 v[64:67], v[202:205], v[234:237], v[64:67]
	s_setprio 0
	s_barrier
	s_add_i32 s58, s62, s70
	s_mov_b32 m0, s58
	ds_read_b128 v[206:209], v191 offset:49152
	ds_read_b128 v[210:213], v191 offset:50176
	ds_read_b128 v[214:217], v191 offset:51200
	ds_read_b128 v[218:221], v191 offset:52224
	ds_read_b128 v[222:225], v191 offset:53248
	ds_read_b128 v[226:229], v191 offset:54272
	ds_read_b128 v[230:233], v191 offset:55296
	ds_read_b128 v[234:237], v191 offset:56320
	global_load_lds_dwordx4 v146, s[98:99]
	s_add_i32 m0, s58, 0x2000
	s_add_u32 s56, s56, 0x80080
	s_addc_u32 s57, s57, 0
	s_add_i32 s58, s63, s70
	global_load_lds_dwordx4 v150, s[98:99]
	s_mov_b32 m0, s58
	s_nop 0
	global_load_lds_dwordx4 v146, s[56:57]
	s_add_i32 m0, s58, 0x2000
	s_nop 0
	global_load_lds_dwordx4 v150, s[56:57]
	s_mov_b32 m0, s79
	s_nop 0
	global_load_lds_dwordx4 v144, s[100:101]
	s_mov_b32 m0, s80
	s_nop 0
	global_load_lds_dwordx4 v148, s[100:101]
	s_waitcnt vmcnt(8)
	s_waitcnt lgkmcnt(0)
	s_setprio 1
	s_barrier
	v_mfma_f32_16x16x32_bf16 v[60:63], v[128:131], v[206:209], v[60:63]
	v_mfma_f32_16x16x32_bf16 v[56:59], v[136:139], v[206:209], v[56:59]
	v_mfma_f32_16x16x32_bf16 v[44:47], v[128:131], v[214:217], v[44:47]
	v_mfma_f32_16x16x32_bf16 v[40:43], v[136:139], v[214:217], v[40:43]
	v_mfma_f32_16x16x32_bf16 v[28:31], v[128:131], v[222:225], v[28:31]
	v_mfma_f32_16x16x32_bf16 v[24:27], v[136:139], v[222:225], v[24:27]
	v_mfma_f32_16x16x32_bf16 v[12:15], v[128:131], v[230:233], v[12:15]
	v_mfma_f32_16x16x32_bf16 v[8:11], v[136:139], v[230:233], v[8:11]
	v_mfma_f32_16x16x32_bf16 v[60:63], v[132:135], v[210:213], v[60:63]
	v_mfma_f32_16x16x32_bf16 v[56:59], v[140:143], v[210:213], v[56:59]
	v_mfma_f32_16x16x32_bf16 v[44:47], v[132:135], v[218:221], v[44:47]
	v_mfma_f32_16x16x32_bf16 v[40:43], v[140:143], v[218:221], v[40:43]
	v_mfma_f32_16x16x32_bf16 v[28:31], v[132:135], v[226:229], v[28:31]
	v_mfma_f32_16x16x32_bf16 v[24:27], v[140:143], v[226:229], v[24:27]
	v_mfma_f32_16x16x32_bf16 v[12:15], v[132:135], v[234:237], v[12:15]
	v_mfma_f32_16x16x32_bf16 v[8:11], v[140:143], v[234:237], v[8:11]
	v_mfma_f32_16x16x32_bf16 v[52:55], v[182:185], v[206:209], v[52:55]
	v_mfma_f32_16x16x32_bf16 v[48:51], v[198:201], v[206:209], v[48:51]
	v_mfma_f32_16x16x32_bf16 v[36:39], v[182:185], v[214:217], v[36:39]
	v_mfma_f32_16x16x32_bf16 v[32:35], v[198:201], v[214:217], v[32:35]
	v_mfma_f32_16x16x32_bf16 v[20:23], v[182:185], v[222:225], v[20:23]
	v_mfma_f32_16x16x32_bf16 v[16:19], v[198:201], v[222:225], v[16:19]
	v_mfma_f32_16x16x32_bf16 v[4:7], v[182:185], v[230:233], v[4:7]
	v_mfma_f32_16x16x32_bf16 v[0:3], v[198:201], v[230:233], v[0:3]
	v_mfma_f32_16x16x32_bf16 v[52:55], v[194:197], v[210:213], v[52:55]
	v_mfma_f32_16x16x32_bf16 v[48:51], v[202:205], v[210:213], v[48:51]
	v_mfma_f32_16x16x32_bf16 v[36:39], v[194:197], v[218:221], v[36:39]
	v_mfma_f32_16x16x32_bf16 v[32:35], v[202:205], v[218:221], v[32:35]
	v_mfma_f32_16x16x32_bf16 v[20:23], v[194:197], v[226:229], v[20:23]
	v_mfma_f32_16x16x32_bf16 v[16:19], v[202:205], v[226:229], v[16:19]
	v_mfma_f32_16x16x32_bf16 v[4:7], v[194:197], v[234:237], v[4:7]
	v_mfma_f32_16x16x32_bf16 v[0:3], v[202:205], v[234:237], v[0:3]
	s_setprio 0
	s_barrier
	s_add_i32 s61, s61, 2
	s_add_u32 s54, s54, 0x100
	s_addc_u32 s55, s55, 0
	s_add_u32 s49, s49, 0x100
	s_addc_u32 s60, s60, 0
	s_cmp_gt_u32 s61, 29
	s_cbranch_scc0 .LBB0_457
	s_and_b64 vcc, exec, s[16:17]
	s_cbranch_vccz .LBB0_460
	s_barrier

; #define PG8_STAGE(bufoff, gbase, voff) do { _Pragma("unroll") for (int _i = 0; _i < 2; ++_i) \
;         __builtin_amdgcn_global_load_lds((const unsigned*)((const char*)(gbase) + (voff)[_i]), (LAS unsigned*)(lds + (bufoff) + ldsw + _i * 8192), 16, 0, 0); } while (0)
; #define PG8_LDA(dst, b, h) do { _Pragma("unroll") for (int m = 0; m < 4; ++m) _Pragma("unroll") for (int k = 0; k < 2; ++k) dst[m][k] = *(const LAS bf16x8*)(lds + PG8_SA(b, h) + aoff + m * 2048 + k * 1024); } while (0)
; #define PG8_LDB(dst, b, h) do { _Pragma("unroll") for (int n = 0; n < 2; ++n) _Pragma("unroll") for (int k = 0; k < 2; ++k) dst[n][k] = *(const LAS bf16x8*)(lds + PG8_SB(b, h) + boff + n * 2048 + k * 1024); } while (0)
; #define PG8_WAIT_V(n) asm volatile("s_waitcnt vmcnt(" #n ")" ::: "memory")
; #define PG8_WAIT_L(n) asm volatile("s_waitcnt lgkmcnt(" #n ")" ::: "memory")
; #define PG8_BAR __builtin_amdgcn_s_barrier()
; #define PG8_SCHED __builtin_amdgcn_sched_barrier(0)
; template <class Epi, bool FP8 = false>
; __device__ __forceinline__ void gemm_phase(LAS unsigned char* lds, const Gemm g, const StaticOrder& S_, const Epi& E, const int tid) {
;     ...
;             const bool last = (t == nt - 2);
;             const char* a1 = cA + (size_t)(t + 1) * kstep;
;             const char* a2 = last ? nA : cA + (size_t)(t + 2) * kstep; const char* b2 = last ? nB : cB + (size_t)(t + 2) * kstep;
;             const char* a3 = a2 + kstep; const char* b3 = b2 + kstep;
;             PG8_LDB(B0, 0, 0); PG8_LDB(B1, 0, 1); PG8_SCHED; PG8_LDA(At, 0, 0); PG8_STAGE(PG8_SA(1, 1), a1 + hstepA, voffA);
;             PG8_WAIT_V(8); PG8_WAIT_L(0); PG8_BAR; PG8_MMA(0, 0, At, B0); PG8_MMA(0, 1, At, B1); PG8_BAR; PG8_SCHED;
;             PG8_LDA(At, 0, 1); PG8_STAGE(PG8_SB(0, 0), b2, voffB); PG8_STAGE(PG8_SB(0, 1), b2 + hstepB, voffB); PG8_STAGE(PG8_SA(0, 0), a2, voffA);
;             PG8_WAIT_V(8); PG8_WAIT_L(0); PG8_BAR; PG8_MMA(1, 0, At, B0); PG8_MMA(1, 1, At, B1); PG8_BAR; PG8_SCHED;
.LBB0_596:
	ds_read_b128 v[156:159], v197 offset:1024
	ds_read_b128 v[152:155], v197
	ds_read_b128 v[148:151], v197 offset:3072
	ds_read_b128 v[144:147], v197 offset:2048
	ds_read_b128 v[140:143], v198 offset:1024
	ds_read_b128 v[136:139], v198
	ds_read_b128 v[132:135], v198 offset:3072
	ds_read_b128 v[128:131], v198 offset:2048
	s_add_u32 s54, s52, 0xfffc0080
	s_addc_u32 s55, s53, -1
	s_cmp_eq_u32 s85, 12
	s_cselect_b32 s57, s27, s55
	s_cselect_b32 s56, s42, s54
	s_cselect_b32 s55, s25, s84
	s_cselect_b32 s54, s43, s66
	s_add_i32 m0, s63, 0xc000
	ds_read_b128 v[186:189], v199
	ds_read_b128 v[190:193], v199 offset:1024
	ds_read_b128 v[200:203], v199 offset:2048
	ds_read_b128 v[204:207], v199 offset:3072
	ds_read_b128 v[208:211], v199 offset:4096
	ds_read_b128 v[212:215], v199 offset:5120
	ds_read_b128 v[216:219], v199 offset:6144
	ds_read_b128 v[220:223], v199 offset:7168
	global_load_lds_dwordx4 v178, s[52:53]
	s_add_i32 m0, s63, 0xe000
	s_nop 0
	global_load_lds_dwordx4 v180, s[52:53]
	s_waitcnt vmcnt(8)
	s_waitcnt lgkmcnt(0)
	s_setprio 1
	s_barrier
	v_mfma_f32_16x16x128_f8f6f4 v[124:127], v[152:159], v[186:193], v[124:127]
	v_mfma_f32_16x16x128_f8f6f4 v[120:123], v[144:151], v[186:193], v[120:123]
	v_mfma_f32_16x16x128_f8f6f4 v[112:115], v[152:159], v[200:207], v[112:115]
	v_mfma_f32_16x16x128_f8f6f4 v[104:107], v[144:151], v[200:207], v[104:107]
	v_mfma_f32_16x16x128_f8f6f4 v[96:99], v[152:159], v[208:215], v[96:99]
	v_mfma_f32_16x16x128_f8f6f4 v[88:91], v[144:151], v[208:215], v[88:91]
	v_mfma_f32_16x16x128_f8f6f4 v[84:87], v[152:159], v[216:223], v[84:87]
	v_mfma_f32_16x16x128_f8f6f4 v[72:75], v[144:151], v[216:223], v[72:75]
	v_mfma_f32_16x16x128_f8f6f4 v[116:119], v[136:143], v[186:193], v[116:119]
	v_mfma_f32_16x16x128_f8f6f4 v[108:111], v[128:135], v[186:193], v[108:111]
	v_mfma_f32_16x16x128_f8f6f4 v[100:103], v[136:143], v[200:207], v[100:103]
	v_mfma_f32_16x16x128_f8f6f4 v[92:95], v[128:135], v[200:207], v[92:95]
	v_mfma_f32_16x16x128_f8f6f4 v[80:83], v[136:143], v[208:215], v[80:83]
	v_mfma_f32_16x16x128_f8f6f4 v[76:79], v[128:135], v[208:215], v[76:79]
	v_mfma_f32_16x16x128_f8f6f4 v[68:71], v[136:143], v[216:223], v[68:71]
	v_mfma_f32_16x16x128_f8f6f4 v[64:67], v[128:135], v[216:223], v[64:67]
	s_setprio 0
	s_barrier
	s_add_u32 s98, s54, s10
	s_addc_u32 s99, s55, s11
	s_add_u32 s100, s56, s10
	s_addc_u32 s101, s57, s11
	s_add_i32 s86, s74, s60
	s_mov_b32 m0, s86
	ds_read_b128 v[200:203], v199 offset:16384
	ds_read_b128 v[204:207], v199 offset:17408
	ds_read_b128 v[208:211], v199 offset:18432
	ds_read_b128 v[212:215], v199 offset:19456
	ds_read_b128 v[216:219], v199 offset:20480
	ds_read_b128 v[220:223], v199 offset:21504
	ds_read_b128 v[224:227], v199 offset:22528
	ds_read_b128 v[228:231], v199 offset:23552
	global_load_lds_dwordx4 v160, s[54:55]
	s_add_i32 m0, s86, 0x2000
	s_add_u32 s86, s54, 0x40000
	s_addc_u32 s87, s55, 0
	s_add_i32 s88, s75, s60
	global_load_lds_dwordx4 v162, s[54:55]
	s_mov_b32 m0, s88
	s_nop 0
	global_load_lds_dwordx4 v160, s[86:87]
	s_add_i32 m0, s88, 0x2000
	s_nop 0
	global_load_lds_dwordx4 v162, s[86:87]
	s_mov_b32 m0, s63
	s_nop 0
	global_load_lds_dwordx4 v166, s[56:57]
	s_mov_b32 m0, s68
	s_nop 0
	global_load_lds_dwordx4 v164, s[56:57]
	s_waitcnt vmcnt(8)
	s_waitcnt lgkmcnt(0)
	s_setprio 1
	s_barrier
	v_mfma_f32_16x16x128_f8f6f4 v[60:63], v[152:159], v[200:207], v[60:63]
	v_mfma_f32_16x16x128_f8f6f4 v[56:59], v[144:151], v[200:207], v[56:59]
	v_mfma_f32_16x16x128_f8f6f4 v[48:51], v[152:159], v[208:215], v[48:51]
	v_mfma_f32_16x16x128_f8f6f4 v[40:43], v[144:151], v[208:215], v[40:43]
	v_mfma_f32_16x16x128_f8f6f4 v[32:35], v[152:159], v[216:223], v[32:35]
	v_mfma_f32_16x16x128_f8f6f4 v[24:27], v[144:151], v[216:223], v[24:27]
	v_mfma_f32_16x16x128_f8f6f4 v[16:19], v[152:159], v[224:231], v[16:19]
	v_mfma_f32_16x16x128_f8f6f4 v[8:11], v[144:151], v[224:231], v[8:11]
	v_mfma_f32_16x16x128_f8f6f4 v[52:55], v[136:143], v[200:207], v[52:55]
	v_mfma_f32_16x16x128_f8f6f4 v[44:47], v[128:135], v[200:207], v[44:47]
	v_mfma_f32_16x16x128_f8f6f4 v[36:39], v[136:143], v[208:215], v[36:39]
	v_mfma_f32_16x16x128_f8f6f4 v[28:31], v[128:135], v[208:215], v[28:31]
	v_mfma_f32_16x16x128_f8f6f4 v[20:23], v[136:143], v[216:223], v[20:23]
	v_mfma_f32_16x16x128_f8f6f4 v[12:15], v[128:135], v[216:223], v[12:15]
	v_mfma_f32_16x16x128_f8f6f4 v[4:7], v[136:143], v[224:231], v[4:7]
	v_mfma_f32_16x16x128_f8f6f4 v[0:3], v[128:135], v[224:231], v[0:3]
	s_setprio 0
	s_barrier
; #define PG8_STAGE(bufoff, gbase, voff) do { _Pragma("unroll") for (int _i = 0; _i < 2; ++_i) \
;         __builtin_amdgcn_global_load_lds((const unsigned*)((const char*)(gbase) + (voff)[_i]), (LAS unsigned*)(lds + (bufoff) + ldsw + _i * 8192), 16, 0, 0); } while (0)
; #define PG8_LDA(dst, b, h) do { _Pragma("unroll") for (int m = 0; m < 4; ++m) _Pragma("unroll") for (int k = 0; k < 2; ++k) dst[m][k] = *(const LAS bf16x8*)(lds + PG8_SA(b, h) + aoff + m * 2048 + k * 1024); } while (0)
; #define PG8_LDB(dst, b, h) do { _Pragma("unroll") for (int n = 0; n < 2; ++n) _Pragma("unroll") for (int k = 0; k < 2; ++k) dst[n][k] = *(const LAS bf16x8*)(lds + PG8_SB(b, h) + boff + n * 2048 + k * 1024); } while (0)
; #define PG8_WAIT_V(n) asm volatile("s_waitcnt vmcnt(" #n ")" ::: "memory")
; #define PG8_WAIT_L(n) asm volatile("s_waitcnt lgkmcnt(" #n ")" ::: "memory")
; #define PG8_BAR __builtin_amdgcn_s_barrier()
; #define PG8_SCHED __builtin_amdgcn_sched_barrier(0)
; template <class Epi, bool FP8 = false>
; __device__ __forceinline__ void gemm_phase(LAS unsigned char* lds, const Gemm g, const StaticOrder& S_, const Epi& E, const int tid) {
;     ...
;             PG8_LDB(B0, 1, 0); PG8_LDB(B1, 1, 1); PG8_SCHED; PG8_LDA(At, 1, 0); PG8_STAGE(PG8_SA(0, 1), a2 + hstepA, voffA);
;             PG8_WAIT_V(8); PG8_WAIT_L(0); PG8_BAR; PG8_MMA(0, 0, At, B0); PG8_MMA(0, 1, At, B1); PG8_BAR; PG8_SCHED;
;             PG8_LDA(At, 1, 1); PG8_STAGE(PG8_SB(1, 0), b3, voffB); PG8_STAGE(PG8_SB(1, 1), b3 + hstepB, voffB); PG8_STAGE(PG8_SA(1, 0), a3, voffA);
;             PG8_WAIT_V(8); PG8_WAIT_L(0); PG8_BAR; PG8_MMA(1, 0, At, B0); PG8_MMA(1, 1, At, B1); PG8_BAR; PG8_SCHED;
;         }
;         if (wr == 0) PG8_BAR;
	s_add_i32 s86, 0, 0x18000
	v_add_u32_e32 v128, s86, v195
	s_add_i32 s87, 0, 0x1c000
	ds_read_b128 v[156:159], v128 offset:1024
	ds_read_b128 v[152:155], v128
	ds_read_b128 v[148:151], v128 offset:3072
	ds_read_b128 v[144:147], v128 offset:2048
	v_add_u32_e32 v128, s87, v195
	ds_read_b128 v[140:143], v128 offset:1024
	ds_read_b128 v[136:139], v128
	ds_read_b128 v[132:135], v128 offset:3072
	ds_read_b128 v[128:131], v128 offset:2048
	s_add_u32 s56, s56, 0x40000
	s_addc_u32 s57, s57, 0
	s_mov_b32 m0, s69
	ds_read_b128 v[200:203], v199 offset:32768
	ds_read_b128 v[204:207], v199 offset:33792
	ds_read_b128 v[208:211], v199 offset:34816
	ds_read_b128 v[212:215], v199 offset:35840
	ds_read_b128 v[216:219], v199 offset:36864
	ds_read_b128 v[220:223], v199 offset:37888
	ds_read_b128 v[224:227], v199 offset:38912
	ds_read_b128 v[228:231], v199 offset:39936
	global_load_lds_dwordx4 v166, s[56:57]
	s_mov_b32 m0, s70
	s_nop 0
	global_load_lds_dwordx4 v164, s[56:57]
	s_waitcnt vmcnt(8)
	s_waitcnt lgkmcnt(0)
	s_setprio 1
	s_barrier
	v_mfma_f32_16x16x128_f8f6f4 v[124:127], v[152:159], v[200:207], v[124:127]
	v_mfma_f32_16x16x128_f8f6f4 v[120:123], v[144:151], v[200:207], v[120:123]
	v_mfma_f32_16x16x128_f8f6f4 v[112:115], v[152:159], v[208:215], v[112:115]
	v_mfma_f32_16x16x128_f8f6f4 v[104:107], v[144:151], v[208:215], v[104:107]
	v_mfma_f32_16x16x128_f8f6f4 v[96:99], v[152:159], v[216:223], v[96:99]
	v_mfma_f32_16x16x128_f8f6f4 v[88:91], v[144:151], v[216:223], v[88:91]
	v_mfma_f32_16x16x128_f8f6f4 v[84:87], v[152:159], v[224:231], v[84:87]
	v_mfma_f32_16x16x128_f8f6f4 v[72:75], v[144:151], v[224:231], v[72:75]
	v_mfma_f32_16x16x128_f8f6f4 v[116:119], v[136:143], v[200:207], v[116:119]
	v_mfma_f32_16x16x128_f8f6f4 v[108:111], v[128:135], v[200:207], v[108:111]
	v_mfma_f32_16x16x128_f8f6f4 v[100:103], v[136:143], v[208:215], v[100:103]
	v_mfma_f32_16x16x128_f8f6f4 v[92:95], v[128:135], v[208:215], v[92:95]
	v_mfma_f32_16x16x128_f8f6f4 v[80:83], v[136:143], v[216:223], v[80:83]
	v_mfma_f32_16x16x128_f8f6f4 v[76:79], v[128:135], v[216:223], v[76:79]
	v_mfma_f32_16x16x128_f8f6f4 v[68:71], v[136:143], v[224:231], v[68:71]
	v_mfma_f32_16x16x128_f8f6f4 v[64:67], v[128:135], v[224:231], v[64:67]
	s_setprio 0
	s_barrier
	s_add_i32 s56, s86, s60
	s_mov_b32 m0, s56
	ds_read_b128 v[200:203], v199 offset:49152
	ds_read_b128 v[204:207], v199 offset:50176
	ds_read_b128 v[208:211], v199 offset:51200
	ds_read_b128 v[212:215], v199 offset:52224
	ds_read_b128 v[216:219], v199 offset:53248
	ds_read_b128 v[220:223], v199 offset:54272
	ds_read_b128 v[224:227], v199 offset:55296
	ds_read_b128 v[228:231], v199 offset:56320
	global_load_lds_dwordx4 v160, s[98:99]
	s_add_i32 m0, s56, 0x2000
	s_add_u32 s54, s54, 0x40080
	s_addc_u32 s55, s55, 0
	s_add_i32 s56, s87, s60
	global_load_lds_dwordx4 v162, s[98:99]
	s_mov_b32 m0, s56
	s_nop 0
	global_load_lds_dwordx4 v160, s[54:55]
	s_add_i32 m0, s56, 0x2000
	s_nop 0
	global_load_lds_dwordx4 v162, s[54:55]
	s_mov_b32 m0, s72
	s_nop 0
	global_load_lds_dwordx4 v166, s[100:101]
	s_mov_b32 m0, s73
	s_nop 0
	global_load_lds_dwordx4 v164, s[100:101]
	s_waitcnt vmcnt(8)
	s_waitcnt lgkmcnt(0)
	s_setprio 1
	s_barrier
	v_mfma_f32_16x16x128_f8f6f4 v[60:63], v[152:159], v[200:207], v[60:63]
	v_mfma_f32_16x16x128_f8f6f4 v[56:59], v[144:151], v[200:207], v[56:59]
	v_mfma_f32_16x16x128_f8f6f4 v[48:51], v[152:159], v[208:215], v[48:51]
	v_mfma_f32_16x16x128_f8f6f4 v[40:43], v[144:151], v[208:215], v[40:43]
	v_mfma_f32_16x16x128_f8f6f4 v[32:35], v[152:159], v[216:223], v[32:35]
	v_mfma_f32_16x16x128_f8f6f4 v[24:27], v[144:151], v[216:223], v[24:27]
	v_mfma_f32_16x16x128_f8f6f4 v[16:19], v[152:159], v[224:231], v[16:19]
	v_mfma_f32_16x16x128_f8f6f4 v[8:11], v[144:151], v[224:231], v[8:11]
	v_mfma_f32_16x16x128_f8f6f4 v[52:55], v[136:143], v[200:207], v[52:55]
	v_mfma_f32_16x16x128_f8f6f4 v[44:47], v[128:135], v[200:207], v[44:47]
	v_mfma_f32_16x16x128_f8f6f4 v[36:39], v[136:143], v[208:215], v[36:39]
	v_mfma_f32_16x16x128_f8f6f4 v[28:31], v[128:135], v[208:215], v[28:31]
	v_mfma_f32_16x16x128_f8f6f4 v[20:23], v[136:143], v[216:223], v[20:23]
	v_mfma_f32_16x16x128_f8f6f4 v[12:15], v[128:135], v[216:223], v[12:15]
	v_mfma_f32_16x16x128_f8f6f4 v[4:7], v[136:143], v[224:231], v[4:7]
	v_mfma_f32_16x16x128_f8f6f4 v[0:3], v[128:135], v[224:231], v[0:3]
	s_setprio 0
	s_barrier
	s_add_i32 s85, s85, 2
	s_add_u32 s52, s52, 0x100
	s_addc_u32 s53, s53, 0
	s_add_u32 s66, s66, 0x100
	s_addc_u32 s84, s84, 0
	s_cmp_gt_u32 s85, 13
	s_cbranch_scc0 .LBB0_596
	s_and_b64 vcc, exec, s[12:13]
	s_cbranch_vccz .LBB0_599
	s_barrier

; #define PG8_STAGE(bufoff, gbase, voff) do { _Pragma("unroll") for (int _i = 0; _i < 2; ++_i) \
;         __builtin_amdgcn_global_load_lds((const unsigned*)((const char*)(gbase) + (voff)[_i]), (LAS unsigned*)(lds + (bufoff) + ldsw + _i * 8192), 16, 0, 0); } while (0)
; #define PG8_LDA(dst, b, h) do { _Pragma("unroll") for (int m = 0; m < 4; ++m) _Pragma("unroll") for (int k = 0; k < 2; ++k) dst[m][k] = *(const LAS bf16x8*)(lds + PG8_SA(b, h) + aoff + m * 2048 + k * 1024); } while (0)
; #define PG8_LDB(dst, b, h) do { _Pragma("unroll") for (int n = 0; n < 2; ++n) _Pragma("unroll") for (int k = 0; k < 2; ++k) dst[n][k] = *(const LAS bf16x8*)(lds + PG8_SB(b, h) + boff + n * 2048 + k * 1024); } while (0)
; #define PG8_WAIT_V(n) asm volatile("s_waitcnt vmcnt(" #n ")" ::: "memory")
; #define PG8_WAIT_L(n) asm volatile("s_waitcnt lgkmcnt(" #n ")" ::: "memory")
; #define PG8_BAR __builtin_amdgcn_s_barrier()
; #define PG8_SCHED __builtin_amdgcn_sched_barrier(0)
; template <class Epi, bool FP8 = false>
; __device__ __forceinline__ void gemm_phase(LAS unsigned char* lds, const Gemm g, const StaticOrder& S_, const Epi& E, const int tid) {
;     ...
;             const bool last = (t == nt - 2);
;             const char* a1 = cA + (size_t)(t + 1) * kstep;
;             const char* a2 = last ? nA : cA + (size_t)(t + 2) * kstep; const char* b2 = last ? nB : cB + (size_t)(t + 2) * kstep;
;             const char* a3 = a2 + kstep; const char* b3 = b2 + kstep;
;             PG8_LDB(B0, 0, 0); PG8_LDB(B1, 0, 1); PG8_SCHED; PG8_LDA(At, 0, 0); PG8_STAGE(PG8_SA(1, 1), a1 + hstepA, voffA);
;             PG8_WAIT_V(8); PG8_WAIT_L(0); PG8_BAR; PG8_MMA(0, 0, At, B0); PG8_MMA(0, 1, At, B1); PG8_BAR; PG8_SCHED;
;             PG8_LDA(At, 0, 1); PG8_STAGE(PG8_SB(0, 0), b2, voffB); PG8_STAGE(PG8_SB(0, 1), b2 + hstepB, voffB); PG8_STAGE(PG8_SA(0, 0), a2, voffA);
;             PG8_WAIT_V(8); PG8_WAIT_L(0); PG8_BAR; PG8_MMA(1, 0, At, B0); PG8_MMA(1, 1, At, B1); PG8_BAR; PG8_SCHED;
.LBB0_1095:
	ds_read_b128 v[144:147], v174
	ds_read_b128 v[178:181], v174 offset:1024
	ds_read_b128 v[182:185], v174 offset:2048
	ds_read_b128 v[186:189], v174 offset:3072
	ds_read_b128 v[190:193], v175
	ds_read_b128 v[194:197], v175 offset:1024
	ds_read_b128 v[198:201], v175 offset:2048
	ds_read_b128 v[202:205], v175 offset:3072
	s_add_u32 s8, s26, 0x100
	s_addc_u32 s9, s27, 0
	s_cmp_eq_u32 s69, 12
	s_cselect_b32 s49, s23, s9
	s_cselect_b32 s48, s22, s8
	s_cselect_b32 s47, s21, s68
	s_cselect_b32 s46, s66, s67
	s_add_i32 m0, s54, 0xc000
	ds_read_b128 v[206:209], v176
	ds_read_b128 v[210:213], v176 offset:1024
	ds_read_b128 v[214:217], v176 offset:2048
	ds_read_b128 v[218:221], v176 offset:3072
	ds_read_b128 v[222:225], v176 offset:4096
	ds_read_b128 v[226:229], v176 offset:5120
	ds_read_b128 v[230:233], v176 offset:6144
	ds_read_b128 v[234:237], v176 offset:7168
	global_load_lds_dwordx4 v136, s[26:27]
	s_add_i32 m0, s54, 0xe000
	s_nop 0
	global_load_lds_dwordx4 v138, s[26:27]
	s_waitcnt vmcnt(8)
	s_waitcnt lgkmcnt(0)
	s_setprio 1
	s_barrier
	v_mfma_f32_16x16x32_bf16 v[124:127], v[144:147], v[206:209], v[124:127]
	v_mfma_f32_16x16x32_bf16 v[120:123], v[182:185], v[206:209], v[120:123]
	v_mfma_f32_16x16x32_bf16 v[108:111], v[144:147], v[214:217], v[108:111]
	v_mfma_f32_16x16x32_bf16 v[104:107], v[182:185], v[214:217], v[104:107]
	v_mfma_f32_16x16x32_bf16 v[92:95], v[144:147], v[222:225], v[92:95]
	v_mfma_f32_16x16x32_bf16 v[88:91], v[182:185], v[222:225], v[88:91]
	v_mfma_f32_16x16x32_bf16 v[76:79], v[144:147], v[230:233], v[76:79]
	v_mfma_f32_16x16x32_bf16 v[72:75], v[182:185], v[230:233], v[72:75]
	v_mfma_f32_16x16x32_bf16 v[124:127], v[178:181], v[210:213], v[124:127]
	v_mfma_f32_16x16x32_bf16 v[120:123], v[186:189], v[210:213], v[120:123]
	v_mfma_f32_16x16x32_bf16 v[108:111], v[178:181], v[218:221], v[108:111]
	v_mfma_f32_16x16x32_bf16 v[104:107], v[186:189], v[218:221], v[104:107]
	v_mfma_f32_16x16x32_bf16 v[92:95], v[178:181], v[226:229], v[92:95]
	v_mfma_f32_16x16x32_bf16 v[88:91], v[186:189], v[226:229], v[88:91]
	v_mfma_f32_16x16x32_bf16 v[76:79], v[178:181], v[234:237], v[76:79]
	v_mfma_f32_16x16x32_bf16 v[72:75], v[186:189], v[234:237], v[72:75]
	v_mfma_f32_16x16x32_bf16 v[116:119], v[190:193], v[206:209], v[116:119]
	v_mfma_f32_16x16x32_bf16 v[112:115], v[198:201], v[206:209], v[112:115]
	v_mfma_f32_16x16x32_bf16 v[100:103], v[190:193], v[214:217], v[100:103]
	v_mfma_f32_16x16x32_bf16 v[96:99], v[198:201], v[214:217], v[96:99]
	v_mfma_f32_16x16x32_bf16 v[84:87], v[190:193], v[222:225], v[84:87]
	v_mfma_f32_16x16x32_bf16 v[80:83], v[198:201], v[222:225], v[80:83]
	v_mfma_f32_16x16x32_bf16 v[68:71], v[190:193], v[230:233], v[68:71]
	v_mfma_f32_16x16x32_bf16 v[64:67], v[198:201], v[230:233], v[64:67]
	v_mfma_f32_16x16x32_bf16 v[116:119], v[194:197], v[210:213], v[116:119]
	v_mfma_f32_16x16x32_bf16 v[112:115], v[202:205], v[210:213], v[112:115]
	v_mfma_f32_16x16x32_bf16 v[100:103], v[194:197], v[218:221], v[100:103]
	v_mfma_f32_16x16x32_bf16 v[96:99], v[202:205], v[218:221], v[96:99]
	v_mfma_f32_16x16x32_bf16 v[84:87], v[194:197], v[226:229], v[84:87]
	v_mfma_f32_16x16x32_bf16 v[80:83], v[202:205], v[226:229], v[80:83]
	v_mfma_f32_16x16x32_bf16 v[68:71], v[194:197], v[234:237], v[68:71]
	v_mfma_f32_16x16x32_bf16 v[64:67], v[202:205], v[234:237], v[64:67]
	s_setprio 0
	s_barrier
	s_add_u32 s98, s46, s16
	s_addc_u32 s99, s47, s17
	s_add_u32 s100, s48, s16
	s_addc_u32 s101, s49, s17
	s_add_i32 s26, s61, s53
	s_mov_b32 m0, s26
	ds_read_b128 v[206:209], v176 offset:16384
	ds_read_b128 v[210:213], v176 offset:17408
	ds_read_b128 v[214:217], v176 offset:18432
	ds_read_b128 v[218:221], v176 offset:19456
	ds_read_b128 v[222:225], v176 offset:20480
	ds_read_b128 v[226:229], v176 offset:21504
	ds_read_b128 v[230:233], v176 offset:22528
	ds_read_b128 v[234:237], v176 offset:23552
	global_load_lds_dwordx4 v132, s[46:47]
	s_add_i32 m0, s26, 0x2000
	s_add_u32 s26, s46, 0x40000
	s_addc_u32 s27, s47, 0
	s_add_i32 s70, s62, s53
	global_load_lds_dwordx4 v134, s[46:47]
	s_mov_b32 m0, s70
	s_nop 0
	global_load_lds_dwordx4 v132, s[26:27]
	s_add_i32 m0, s70, 0x2000
	s_nop 0
	global_load_lds_dwordx4 v134, s[26:27]
	s_mov_b32 m0, s54
	s_nop 0
	global_load_lds_dwordx4 v128, s[48:49]
	s_mov_b32 m0, s55
	s_nop 0
	global_load_lds_dwordx4 v130, s[48:49]
	s_waitcnt vmcnt(8)
	s_waitcnt lgkmcnt(0)
	s_setprio 1
	s_barrier
	v_mfma_f32_16x16x32_bf16 v[60:63], v[144:147], v[206:209], v[60:63]
	v_mfma_f32_16x16x32_bf16 v[56:59], v[182:185], v[206:209], v[56:59]
	v_mfma_f32_16x16x32_bf16 v[44:47], v[144:147], v[214:217], v[44:47]
	v_mfma_f32_16x16x32_bf16 v[40:43], v[182:185], v[214:217], v[40:43]
	v_mfma_f32_16x16x32_bf16 v[28:31], v[144:147], v[222:225], v[28:31]
	v_mfma_f32_16x16x32_bf16 v[24:27], v[182:185], v[222:225], v[24:27]
	v_mfma_f32_16x16x32_bf16 v[12:15], v[144:147], v[230:233], v[12:15]
	v_mfma_f32_16x16x32_bf16 v[8:11], v[182:185], v[230:233], v[8:11]
	v_mfma_f32_16x16x32_bf16 v[60:63], v[178:181], v[210:213], v[60:63]
	v_mfma_f32_16x16x32_bf16 v[56:59], v[186:189], v[210:213], v[56:59]
	v_mfma_f32_16x16x32_bf16 v[44:47], v[178:181], v[218:221], v[44:47]
	v_mfma_f32_16x16x32_bf16 v[40:43], v[186:189], v[218:221], v[40:43]
	v_mfma_f32_16x16x32_bf16 v[28:31], v[178:181], v[226:229], v[28:31]
	v_mfma_f32_16x16x32_bf16 v[24:27], v[186:189], v[226:229], v[24:27]
	v_mfma_f32_16x16x32_bf16 v[12:15], v[178:181], v[234:237], v[12:15]
	v_mfma_f32_16x16x32_bf16 v[8:11], v[186:189], v[234:237], v[8:11]
	v_mfma_f32_16x16x32_bf16 v[52:55], v[190:193], v[206:209], v[52:55]
	v_mfma_f32_16x16x32_bf16 v[48:51], v[198:201], v[206:209], v[48:51]
	v_mfma_f32_16x16x32_bf16 v[36:39], v[190:193], v[214:217], v[36:39]
	v_mfma_f32_16x16x32_bf16 v[32:35], v[198:201], v[214:217], v[32:35]
	v_mfma_f32_16x16x32_bf16 v[20:23], v[190:193], v[222:225], v[20:23]
	v_mfma_f32_16x16x32_bf16 v[16:19], v[198:201], v[222:225], v[16:19]
	v_mfma_f32_16x16x32_bf16 v[4:7], v[190:193], v[230:233], v[4:7]
	v_mfma_f32_16x16x32_bf16 v[0:3], v[198:201], v[230:233], v[0:3]
	v_mfma_f32_16x16x32_bf16 v[52:55], v[194:197], v[210:213], v[52:55]
	v_mfma_f32_16x16x32_bf16 v[48:51], v[202:205], v[210:213], v[48:51]
	v_mfma_f32_16x16x32_bf16 v[36:39], v[194:197], v[218:221], v[36:39]
	v_mfma_f32_16x16x32_bf16 v[32:35], v[202:205], v[218:221], v[32:35]
	v_mfma_f32_16x16x32_bf16 v[20:23], v[194:197], v[226:229], v[20:23]
	v_mfma_f32_16x16x32_bf16 v[16:19], v[202:205], v[226:229], v[16:19]
	v_mfma_f32_16x16x32_bf16 v[4:7], v[194:197], v[234:237], v[4:7]
	v_mfma_f32_16x16x32_bf16 v[0:3], v[202:205], v[234:237], v[0:3]
	s_setprio 0
	s_barrier
; #define PG8_STAGE(bufoff, gbase, voff) do { _Pragma("unroll") for (int _i = 0; _i < 2; ++_i) \
;         __builtin_amdgcn_global_load_lds((const unsigned*)((const char*)(gbase) + (voff)[_i]), (LAS unsigned*)(lds + (bufoff) + ldsw + _i * 8192), 16, 0, 0); } while (0)
; #define PG8_LDA(dst, b, h) do { _Pragma("unroll") for (int m = 0; m < 4; ++m) _Pragma("unroll") for (int k = 0; k < 2; ++k) dst[m][k] = *(const LAS bf16x8*)(lds + PG8_SA(b, h) + aoff + m * 2048 + k * 1024); } while (0)
; #define PG8_LDB(dst, b, h) do { _Pragma("unroll") for (int n = 0; n < 2; ++n) _Pragma("unroll") for (int k = 0; k < 2; ++k) dst[n][k] = *(const LAS bf16x8*)(lds + PG8_SB(b, h) + boff + n * 2048 + k * 1024); } while (0)
; #define PG8_WAIT_V(n) asm volatile("s_waitcnt vmcnt(" #n ")" ::: "memory")
; #define PG8_WAIT_L(n) asm volatile("s_waitcnt lgkmcnt(" #n ")" ::: "memory")
; #define PG8_BAR __builtin_amdgcn_s_barrier()
; #define PG8_SCHED __builtin_amdgcn_sched_barrier(0)
; template <class Epi, bool FP8 = false>
; __device__ __forceinline__ void gemm_phase(LAS unsigned char* lds, const Gemm g, const StaticOrder& S_, const Epi& E, const int tid) {
;     ...
;             PG8_LDB(B0, 1, 0); PG8_LDB(B1, 1, 1); PG8_SCHED; PG8_LDA(At, 1, 0); PG8_STAGE(PG8_SA(0, 1), a2 + hstepA, voffA);
;             PG8_WAIT_V(8); PG8_WAIT_L(0); PG8_BAR; PG8_MMA(0, 0, At, B0); PG8_MMA(0, 1, At, B1); PG8_BAR; PG8_SCHED;
;             PG8_LDA(At, 1, 1); PG8_STAGE(PG8_SB(1, 0), b3, voffB); PG8_STAGE(PG8_SB(1, 1), b3 + hstepB, voffB); PG8_STAGE(PG8_SA(1, 0), a3, voffA);
;             PG8_WAIT_V(8); PG8_WAIT_L(0); PG8_BAR; PG8_MMA(1, 0, At, B0); PG8_MMA(1, 1, At, B1); PG8_BAR; PG8_SCHED;
;         }
;         if (wr == 0) PG8_BAR;
	s_add_i32 s70, 0, 0x18000
	v_add_u32_e32 v177, s70, v172
	s_add_i32 s71, 0, 0x1c000
	ds_read_b128 v[144:147], v177
	ds_read_b128 v[178:181], v177 offset:1024
	ds_read_b128 v[182:185], v177 offset:2048
	ds_read_b128 v[186:189], v177 offset:3072
	v_add_u32_e32 v177, s71, v172
	ds_read_b128 v[190:193], v177
	ds_read_b128 v[194:197], v177 offset:1024
	ds_read_b128 v[198:201], v177 offset:2048
	ds_read_b128 v[202:205], v177 offset:3072
	s_add_u32 s26, s48, 0x60000
	s_addc_u32 s27, s49, 0
	s_mov_b32 m0, s56
	ds_read_b128 v[206:209], v176 offset:32768
	ds_read_b128 v[210:213], v176 offset:33792
	ds_read_b128 v[214:217], v176 offset:34816
	ds_read_b128 v[218:221], v176 offset:35840
	ds_read_b128 v[222:225], v176 offset:36864
	ds_read_b128 v[226:229], v176 offset:37888
	ds_read_b128 v[230:233], v176 offset:38912
	ds_read_b128 v[234:237], v176 offset:39936
	global_load_lds_dwordx4 v128, s[26:27]
	s_mov_b32 m0, s57
	s_nop 0
	global_load_lds_dwordx4 v130, s[26:27]
	s_waitcnt vmcnt(8)
	s_waitcnt lgkmcnt(0)
	s_setprio 1
	s_barrier
	v_mfma_f32_16x16x32_bf16 v[124:127], v[144:147], v[206:209], v[124:127]
	v_mfma_f32_16x16x32_bf16 v[120:123], v[182:185], v[206:209], v[120:123]
	v_mfma_f32_16x16x32_bf16 v[108:111], v[144:147], v[214:217], v[108:111]
	v_mfma_f32_16x16x32_bf16 v[104:107], v[182:185], v[214:217], v[104:107]
	v_mfma_f32_16x16x32_bf16 v[92:95], v[144:147], v[222:225], v[92:95]
	v_mfma_f32_16x16x32_bf16 v[88:91], v[182:185], v[222:225], v[88:91]
	v_mfma_f32_16x16x32_bf16 v[76:79], v[144:147], v[230:233], v[76:79]
	v_mfma_f32_16x16x32_bf16 v[72:75], v[182:185], v[230:233], v[72:75]
	v_mfma_f32_16x16x32_bf16 v[124:127], v[178:181], v[210:213], v[124:127]
	v_mfma_f32_16x16x32_bf16 v[120:123], v[186:189], v[210:213], v[120:123]
	v_mfma_f32_16x16x32_bf16 v[108:111], v[178:181], v[218:221], v[108:111]
	v_mfma_f32_16x16x32_bf16 v[104:107], v[186:189], v[218:221], v[104:107]
	v_mfma_f32_16x16x32_bf16 v[92:95], v[178:181], v[226:229], v[92:95]
	v_mfma_f32_16x16x32_bf16 v[88:91], v[186:189], v[226:229], v[88:91]
	v_mfma_f32_16x16x32_bf16 v[76:79], v[178:181], v[234:237], v[76:79]
	v_mfma_f32_16x16x32_bf16 v[72:75], v[186:189], v[234:237], v[72:75]
	v_mfma_f32_16x16x32_bf16 v[116:119], v[190:193], v[206:209], v[116:119]
	v_mfma_f32_16x16x32_bf16 v[112:115], v[198:201], v[206:209], v[112:115]
	v_mfma_f32_16x16x32_bf16 v[100:103], v[190:193], v[214:217], v[100:103]
	v_mfma_f32_16x16x32_bf16 v[96:99], v[198:201], v[214:217], v[96:99]
	v_mfma_f32_16x16x32_bf16 v[84:87], v[190:193], v[222:225], v[84:87]
	v_mfma_f32_16x16x32_bf16 v[80:83], v[198:201], v[222:225], v[80:83]
	v_mfma_f32_16x16x32_bf16 v[68:71], v[190:193], v[230:233], v[68:71]
	v_mfma_f32_16x16x32_bf16 v[64:67], v[198:201], v[230:233], v[64:67]
	v_mfma_f32_16x16x32_bf16 v[116:119], v[194:197], v[210:213], v[116:119]
	v_mfma_f32_16x16x32_bf16 v[112:115], v[202:205], v[210:213], v[112:115]
	v_mfma_f32_16x16x32_bf16 v[100:103], v[194:197], v[218:221], v[100:103]
	v_mfma_f32_16x16x32_bf16 v[96:99], v[202:205], v[218:221], v[96:99]
	v_mfma_f32_16x16x32_bf16 v[84:87], v[194:197], v[226:229], v[84:87]
	v_mfma_f32_16x16x32_bf16 v[80:83], v[202:205], v[226:229], v[80:83]
	v_mfma_f32_16x16x32_bf16 v[68:71], v[194:197], v[234:237], v[68:71]
	v_mfma_f32_16x16x32_bf16 v[64:67], v[202:205], v[234:237], v[64:67]
	s_setprio 0
	s_barrier
	s_add_i32 s26, s70, s53
	s_mov_b32 m0, s26
	ds_read_b128 v[206:209], v176 offset:49152
	ds_read_b128 v[210:213], v176 offset:50176
	ds_read_b128 v[214:217], v176 offset:51200
	ds_read_b128 v[218:221], v176 offset:52224
	ds_read_b128 v[222:225], v176 offset:53248
	ds_read_b128 v[226:229], v176 offset:54272
	ds_read_b128 v[230:233], v176 offset:55296
	ds_read_b128 v[234:237], v176 offset:56320
	global_load_lds_dwordx4 v132, s[98:99]
	s_add_i32 m0, s26, 0x2000
	s_add_u32 s26, s46, 0x40080
	s_addc_u32 s27, s47, 0
	s_add_i32 s46, s71, s53
	global_load_lds_dwordx4 v134, s[98:99]
	s_mov_b32 m0, s46
	s_nop 0
	global_load_lds_dwordx4 v132, s[26:27]
	s_add_i32 m0, s46, 0x2000
	s_nop 0
	global_load_lds_dwordx4 v134, s[26:27]
	s_mov_b32 m0, s59
	s_nop 0
	global_load_lds_dwordx4 v128, s[100:101]
	s_mov_b32 m0, s60
	s_nop 0
	global_load_lds_dwordx4 v130, s[100:101]
	s_waitcnt vmcnt(8)
	s_waitcnt lgkmcnt(0)
	s_setprio 1
	s_barrier
	v_mfma_f32_16x16x32_bf16 v[60:63], v[144:147], v[206:209], v[60:63]
	v_mfma_f32_16x16x32_bf16 v[56:59], v[182:185], v[206:209], v[56:59]
	v_mfma_f32_16x16x32_bf16 v[44:47], v[144:147], v[214:217], v[44:47]
	v_mfma_f32_16x16x32_bf16 v[40:43], v[182:185], v[214:217], v[40:43]
	v_mfma_f32_16x16x32_bf16 v[28:31], v[144:147], v[222:225], v[28:31]
	v_mfma_f32_16x16x32_bf16 v[24:27], v[182:185], v[222:225], v[24:27]
	v_mfma_f32_16x16x32_bf16 v[12:15], v[144:147], v[230:233], v[12:15]
	v_mfma_f32_16x16x32_bf16 v[8:11], v[182:185], v[230:233], v[8:11]
	v_mfma_f32_16x16x32_bf16 v[60:63], v[178:181], v[210:213], v[60:63]
	v_mfma_f32_16x16x32_bf16 v[56:59], v[186:189], v[210:213], v[56:59]
	v_mfma_f32_16x16x32_bf16 v[44:47], v[178:181], v[218:221], v[44:47]
	v_mfma_f32_16x16x32_bf16 v[40:43], v[186:189], v[218:221], v[40:43]
	v_mfma_f32_16x16x32_bf16 v[28:31], v[178:181], v[226:229], v[28:31]
	v_mfma_f32_16x16x32_bf16 v[24:27], v[186:189], v[226:229], v[24:27]
	v_mfma_f32_16x16x32_bf16 v[12:15], v[178:181], v[234:237], v[12:15]
	v_mfma_f32_16x16x32_bf16 v[8:11], v[186:189], v[234:237], v[8:11]
	v_mfma_f32_16x16x32_bf16 v[52:55], v[190:193], v[206:209], v[52:55]
	v_mfma_f32_16x16x32_bf16 v[48:51], v[198:201], v[206:209], v[48:51]
	v_mfma_f32_16x16x32_bf16 v[36:39], v[190:193], v[214:217], v[36:39]
	v_mfma_f32_16x16x32_bf16 v[32:35], v[198:201], v[214:217], v[32:35]
	v_mfma_f32_16x16x32_bf16 v[20:23], v[190:193], v[222:225], v[20:23]
	v_mfma_f32_16x16x32_bf16 v[16:19], v[198:201], v[222:225], v[16:19]
	v_mfma_f32_16x16x32_bf16 v[4:7], v[190:193], v[230:233], v[4:7]
	v_mfma_f32_16x16x32_bf16 v[0:3], v[198:201], v[230:233], v[0:3]
	v_mfma_f32_16x16x32_bf16 v[52:55], v[194:197], v[210:213], v[52:55]
	v_mfma_f32_16x16x32_bf16 v[48:51], v[202:205], v[210:213], v[48:51]
	v_mfma_f32_16x16x32_bf16 v[36:39], v[194:197], v[218:221], v[36:39]
	v_mfma_f32_16x16x32_bf16 v[32:35], v[202:205], v[218:221], v[32:35]
	v_mfma_f32_16x16x32_bf16 v[20:23], v[194:197], v[226:229], v[20:23]
	v_mfma_f32_16x16x32_bf16 v[16:19], v[202:205], v[226:229], v[16:19]
	v_mfma_f32_16x16x32_bf16 v[4:7], v[194:197], v[234:237], v[4:7]
	v_mfma_f32_16x16x32_bf16 v[0:3], v[202:205], v[234:237], v[0:3]
	s_setprio 0
	s_barrier
	s_add_i32 s69, s69, 2
	s_add_u32 s67, s67, 0x100
	s_addc_u32 s68, s68, 0
	s_cmp_gt_u32 s69, 13
	s_mov_b64 s[26:27], s[8:9]
	s_cbranch_scc0 .LBB0_1095
	s_and_b64 vcc, exec, s[18:19]
	s_cbranch_vccz .LBB0_1098
	s_barrier

; #define PG8_STAGE(bufoff, gbase, voff) do { _Pragma("unroll") for (int _i = 0; _i < 2; ++_i) \
;         __builtin_amdgcn_global_load_lds((const unsigned*)((const char*)(gbase) + (voff)[_i]), (LAS unsigned*)(lds + (bufoff) + ldsw + _i * 8192), 16, 0, 0); } while (0)
; #define PG8_LDA(dst, b, h) do { _Pragma("unroll") for (int m = 0; m < 4; ++m) _Pragma("unroll") for (int k = 0; k < 2; ++k) dst[m][k] = *(const LAS bf16x8*)(lds + PG8_SA(b, h) + aoff + m * 2048 + k * 1024); } while (0)
; #define PG8_LDB(dst, b, h) do { _Pragma("unroll") for (int n = 0; n < 2; ++n) _Pragma("unroll") for (int k = 0; k < 2; ++k) dst[n][k] = *(const LAS bf16x8*)(lds + PG8_SB(b, h) + boff + n * 2048 + k * 1024); } while (0)
; #define PG8_WAIT_V(n) asm volatile("s_waitcnt vmcnt(" #n ")" ::: "memory")
; #define PG8_WAIT_L(n) asm volatile("s_waitcnt lgkmcnt(" #n ")" ::: "memory")
; #define PG8_BAR __builtin_amdgcn_s_barrier()
; #define PG8_SCHED __builtin_amdgcn_sched_barrier(0)
; template <class Epi, bool FP8 = false>
; __device__ __forceinline__ void gemm_phase(LAS unsigned char* lds, const Gemm g, const StaticOrder& S_, const Epi& E, const int tid) {
;     ...
;             const bool last = (t == nt - 2);
;             const char* a1 = cA + (size_t)(t + 1) * kstep;
;             const char* a2 = last ? nA : cA + (size_t)(t + 2) * kstep; const char* b2 = last ? nB : cB + (size_t)(t + 2) * kstep;
;             const char* a3 = a2 + kstep; const char* b3 = b2 + kstep;
;             PG8_LDB(B0, 0, 0); PG8_LDB(B1, 0, 1); PG8_SCHED; PG8_LDA(At, 0, 0); PG8_STAGE(PG8_SA(1, 1), a1 + hstepA, voffA);
;             PG8_WAIT_V(8); PG8_WAIT_L(0); PG8_BAR; PG8_MMA(0, 0, At, B0); PG8_MMA(0, 1, At, B1); PG8_BAR; PG8_SCHED;
;             PG8_LDA(At, 0, 1); PG8_STAGE(PG8_SB(0, 0), b2, voffB); PG8_STAGE(PG8_SB(0, 1), b2 + hstepB, voffB); PG8_STAGE(PG8_SA(0, 0), a2, voffA);
;             PG8_WAIT_V(8); PG8_WAIT_L(0); PG8_BAR; PG8_MMA(1, 0, At, B0); PG8_MMA(1, 1, At, B1); PG8_BAR; PG8_SCHED;
.LBB0_1121:
	ds_read_b128 v[144:147], v148
	ds_read_b128 v[152:155], v148 offset:1024
	ds_read_b128 v[160:163], v148 offset:2048
	ds_read_b128 v[164:167], v148 offset:3072
	ds_read_b128 v[168:171], v149
	ds_read_b128 v[172:175], v149 offset:1024
	ds_read_b128 v[176:179], v149 offset:2048
	ds_read_b128 v[180:183], v149 offset:3072
	s_add_u32 s8, s26, 0x100
	s_addc_u32 s9, s27, 0
	s_cmp_eq_u32 s69, 4
	s_cselect_b32 s49, s23, s9
	s_cselect_b32 s48, s22, s8
	s_cselect_b32 s47, s21, s68
	s_cselect_b32 s46, s66, s67
	s_add_i32 m0, s54, 0xc000
	ds_read_b128 v[184:187], v150
	ds_read_b128 v[188:191], v150 offset:1024
	ds_read_b128 v[192:195], v150 offset:2048
	ds_read_b128 v[196:199], v150 offset:3072
	ds_read_b128 v[200:203], v150 offset:4096
	ds_read_b128 v[204:207], v150 offset:5120
	ds_read_b128 v[208:211], v150 offset:6144
	ds_read_b128 v[212:215], v150 offset:7168
	global_load_lds_dwordx4 v136, s[26:27]
	s_add_i32 m0, s54, 0xe000
	s_nop 0
	global_load_lds_dwordx4 v138, s[26:27]
	s_waitcnt vmcnt(8)
	s_waitcnt lgkmcnt(0)
	s_setprio 1
	s_barrier
	v_mfma_f32_16x16x32_bf16 v[124:127], v[144:147], v[184:187], v[124:127]
	v_mfma_f32_16x16x32_bf16 v[120:123], v[160:163], v[184:187], v[120:123]
	v_mfma_f32_16x16x32_bf16 v[108:111], v[144:147], v[192:195], v[108:111]
	v_mfma_f32_16x16x32_bf16 v[104:107], v[160:163], v[192:195], v[104:107]
	v_mfma_f32_16x16x32_bf16 v[92:95], v[144:147], v[200:203], v[92:95]
	v_mfma_f32_16x16x32_bf16 v[88:91], v[160:163], v[200:203], v[88:91]
	v_mfma_f32_16x16x32_bf16 v[76:79], v[144:147], v[208:211], v[76:79]
	v_mfma_f32_16x16x32_bf16 v[72:75], v[160:163], v[208:211], v[72:75]
	v_mfma_f32_16x16x32_bf16 v[124:127], v[152:155], v[188:191], v[124:127]
	v_mfma_f32_16x16x32_bf16 v[120:123], v[164:167], v[188:191], v[120:123]
	v_mfma_f32_16x16x32_bf16 v[108:111], v[152:155], v[196:199], v[108:111]
	v_mfma_f32_16x16x32_bf16 v[104:107], v[164:167], v[196:199], v[104:107]
	v_mfma_f32_16x16x32_bf16 v[92:95], v[152:155], v[204:207], v[92:95]
	v_mfma_f32_16x16x32_bf16 v[88:91], v[164:167], v[204:207], v[88:91]
	v_mfma_f32_16x16x32_bf16 v[76:79], v[152:155], v[212:215], v[76:79]
	v_mfma_f32_16x16x32_bf16 v[72:75], v[164:167], v[212:215], v[72:75]
	v_mfma_f32_16x16x32_bf16 v[116:119], v[168:171], v[184:187], v[116:119]
	v_mfma_f32_16x16x32_bf16 v[112:115], v[176:179], v[184:187], v[112:115]
	v_mfma_f32_16x16x32_bf16 v[100:103], v[168:171], v[192:195], v[100:103]
	v_mfma_f32_16x16x32_bf16 v[96:99], v[176:179], v[192:195], v[96:99]
	v_mfma_f32_16x16x32_bf16 v[84:87], v[168:171], v[200:203], v[84:87]
	v_mfma_f32_16x16x32_bf16 v[80:83], v[176:179], v[200:203], v[80:83]
	v_mfma_f32_16x16x32_bf16 v[68:71], v[168:171], v[208:211], v[68:71]
	v_mfma_f32_16x16x32_bf16 v[64:67], v[176:179], v[208:211], v[64:67]
	v_mfma_f32_16x16x32_bf16 v[116:119], v[172:175], v[188:191], v[116:119]
	v_mfma_f32_16x16x32_bf16 v[112:115], v[180:183], v[188:191], v[112:115]
	v_mfma_f32_16x16x32_bf16 v[100:103], v[172:175], v[196:199], v[100:103]
	v_mfma_f32_16x16x32_bf16 v[96:99], v[180:183], v[196:199], v[96:99]
	v_mfma_f32_16x16x32_bf16 v[84:87], v[172:175], v[204:207], v[84:87]
	v_mfma_f32_16x16x32_bf16 v[80:83], v[180:183], v[204:207], v[80:83]
	v_mfma_f32_16x16x32_bf16 v[68:71], v[172:175], v[212:215], v[68:71]
	v_mfma_f32_16x16x32_bf16 v[64:67], v[180:183], v[212:215], v[64:67]
	s_setprio 0
	s_barrier
	s_add_u32 s98, s46, s16
	s_addc_u32 s99, s47, s17
	s_add_u32 s100, s48, s16
	s_addc_u32 s101, s49, s17
	s_add_i32 s26, s61, s53
	s_mov_b32 m0, s26
	ds_read_b128 v[184:187], v150 offset:16384
	ds_read_b128 v[188:191], v150 offset:17408
	ds_read_b128 v[192:195], v150 offset:18432
	ds_read_b128 v[196:199], v150 offset:19456
	ds_read_b128 v[200:203], v150 offset:20480
	ds_read_b128 v[204:207], v150 offset:21504
	ds_read_b128 v[208:211], v150 offset:22528
	ds_read_b128 v[212:215], v150 offset:23552
	global_load_lds_dwordx4 v132, s[46:47]
	s_add_i32 m0, s26, 0x2000
	s_add_u32 s26, s46, 0x20000
	s_addc_u32 s27, s47, 0
	s_add_i32 s70, s62, s53
	global_load_lds_dwordx4 v134, s[46:47]
	s_mov_b32 m0, s70
	s_nop 0
	global_load_lds_dwordx4 v132, s[26:27]
	s_add_i32 m0, s70, 0x2000
	s_nop 0
	global_load_lds_dwordx4 v134, s[26:27]
	s_mov_b32 m0, s54
	s_nop 0
	global_load_lds_dwordx4 v128, s[48:49]
	s_mov_b32 m0, s55
	s_nop 0
	global_load_lds_dwordx4 v130, s[48:49]
	s_waitcnt vmcnt(8)
	s_waitcnt lgkmcnt(0)
	s_setprio 1
	s_barrier
	v_mfma_f32_16x16x32_bf16 v[60:63], v[144:147], v[184:187], v[60:63]
	v_mfma_f32_16x16x32_bf16 v[56:59], v[160:163], v[184:187], v[56:59]
	v_mfma_f32_16x16x32_bf16 v[44:47], v[144:147], v[192:195], v[44:47]
	v_mfma_f32_16x16x32_bf16 v[40:43], v[160:163], v[192:195], v[40:43]
	v_mfma_f32_16x16x32_bf16 v[28:31], v[144:147], v[200:203], v[28:31]
	v_mfma_f32_16x16x32_bf16 v[24:27], v[160:163], v[200:203], v[24:27]
	v_mfma_f32_16x16x32_bf16 v[12:15], v[144:147], v[208:211], v[12:15]
	v_mfma_f32_16x16x32_bf16 v[8:11], v[160:163], v[208:211], v[8:11]
	v_mfma_f32_16x16x32_bf16 v[60:63], v[152:155], v[188:191], v[60:63]
	v_mfma_f32_16x16x32_bf16 v[56:59], v[164:167], v[188:191], v[56:59]
	v_mfma_f32_16x16x32_bf16 v[44:47], v[152:155], v[196:199], v[44:47]
	v_mfma_f32_16x16x32_bf16 v[40:43], v[164:167], v[196:199], v[40:43]
	v_mfma_f32_16x16x32_bf16 v[28:31], v[152:155], v[204:207], v[28:31]
	v_mfma_f32_16x16x32_bf16 v[24:27], v[164:167], v[204:207], v[24:27]
	v_mfma_f32_16x16x32_bf16 v[12:15], v[152:155], v[212:215], v[12:15]
	v_mfma_f32_16x16x32_bf16 v[8:11], v[164:167], v[212:215], v[8:11]
	v_mfma_f32_16x16x32_bf16 v[52:55], v[168:171], v[184:187], v[52:55]
	v_mfma_f32_16x16x32_bf16 v[48:51], v[176:179], v[184:187], v[48:51]
	v_mfma_f32_16x16x32_bf16 v[36:39], v[168:171], v[192:195], v[36:39]
	v_mfma_f32_16x16x32_bf16 v[32:35], v[176:179], v[192:195], v[32:35]
	v_mfma_f32_16x16x32_bf16 v[20:23], v[168:171], v[200:203], v[20:23]
	v_mfma_f32_16x16x32_bf16 v[16:19], v[176:179], v[200:203], v[16:19]
	v_mfma_f32_16x16x32_bf16 v[4:7], v[168:171], v[208:211], v[4:7]
	v_mfma_f32_16x16x32_bf16 v[0:3], v[176:179], v[208:211], v[0:3]
	v_mfma_f32_16x16x32_bf16 v[52:55], v[172:175], v[188:191], v[52:55]
	v_mfma_f32_16x16x32_bf16 v[48:51], v[180:183], v[188:191], v[48:51]
	v_mfma_f32_16x16x32_bf16 v[36:39], v[172:175], v[196:199], v[36:39]
	v_mfma_f32_16x16x32_bf16 v[32:35], v[180:183], v[196:199], v[32:35]
	v_mfma_f32_16x16x32_bf16 v[20:23], v[172:175], v[204:207], v[20:23]
	v_mfma_f32_16x16x32_bf16 v[16:19], v[180:183], v[204:207], v[16:19]
	v_mfma_f32_16x16x32_bf16 v[4:7], v[172:175], v[212:215], v[4:7]
	v_mfma_f32_16x16x32_bf16 v[0:3], v[180:183], v[212:215], v[0:3]
	s_setprio 0
	s_barrier
; #define PG8_STAGE(bufoff, gbase, voff) do { _Pragma("unroll") for (int _i = 0; _i < 2; ++_i) \
;         __builtin_amdgcn_global_load_lds((const unsigned*)((const char*)(gbase) + (voff)[_i]), (LAS unsigned*)(lds + (bufoff) + ldsw + _i * 8192), 16, 0, 0); } while (0)
; #define PG8_LDA(dst, b, h) do { _Pragma("unroll") for (int m = 0; m < 4; ++m) _Pragma("unroll") for (int k = 0; k < 2; ++k) dst[m][k] = *(const LAS bf16x8*)(lds + PG8_SA(b, h) + aoff + m * 2048 + k * 1024); } while (0)
; #define PG8_LDB(dst, b, h) do { _Pragma("unroll") for (int n = 0; n < 2; ++n) _Pragma("unroll") for (int k = 0; k < 2; ++k) dst[n][k] = *(const LAS bf16x8*)(lds + PG8_SB(b, h) + boff + n * 2048 + k * 1024); } while (0)
; #define PG8_WAIT_V(n) asm volatile("s_waitcnt vmcnt(" #n ")" ::: "memory")
; #define PG8_WAIT_L(n) asm volatile("s_waitcnt lgkmcnt(" #n ")" ::: "memory")
; #define PG8_BAR __builtin_amdgcn_s_barrier()
; #define PG8_SCHED __builtin_amdgcn_sched_barrier(0)
; template <class Epi, bool FP8 = false>
; __device__ __forceinline__ void gemm_phase(LAS unsigned char* lds, const Gemm g, const StaticOrder& S_, const Epi& E, const int tid) {
;     ...
;             PG8_LDB(B0, 1, 0); PG8_LDB(B1, 1, 1); PG8_SCHED; PG8_LDA(At, 1, 0); PG8_STAGE(PG8_SA(0, 1), a2 + hstepA, voffA);
;             PG8_WAIT_V(8); PG8_WAIT_L(0); PG8_BAR; PG8_MMA(0, 0, At, B0); PG8_MMA(0, 1, At, B1); PG8_BAR; PG8_SCHED;
;             PG8_LDA(At, 1, 1); PG8_STAGE(PG8_SB(1, 0), b3, voffB); PG8_STAGE(PG8_SB(1, 1), b3 + hstepB, voffB); PG8_STAGE(PG8_SA(1, 0), a3, voffA);
;             PG8_WAIT_V(8); PG8_WAIT_L(0); PG8_BAR; PG8_MMA(1, 0, At, B0); PG8_MMA(1, 1, At, B1); PG8_BAR; PG8_SCHED;
;         }
;         if (wr == 0) PG8_BAR;
	s_add_i32 s70, 0, 0x18000
	v_add_u32_e32 v151, s70, v157
	s_add_i32 s71, 0, 0x1c000
	ds_read_b128 v[144:147], v151
	ds_read_b128 v[152:155], v151 offset:1024
	ds_read_b128 v[160:163], v151 offset:2048
	ds_read_b128 v[164:167], v151 offset:3072
	v_add_u32_e32 v151, s71, v157
	ds_read_b128 v[168:171], v151
	ds_read_b128 v[172:175], v151 offset:1024
	ds_read_b128 v[176:179], v151 offset:2048
	ds_read_b128 v[180:183], v151 offset:3072
	s_add_u32 s26, s48, 0x60000
	s_addc_u32 s27, s49, 0
	s_mov_b32 m0, s56
	ds_read_b128 v[184:187], v150 offset:32768
	ds_read_b128 v[188:191], v150 offset:33792
	ds_read_b128 v[192:195], v150 offset:34816
	ds_read_b128 v[196:199], v150 offset:35840
	ds_read_b128 v[200:203], v150 offset:36864
	ds_read_b128 v[204:207], v150 offset:37888
	ds_read_b128 v[208:211], v150 offset:38912
	ds_read_b128 v[212:215], v150 offset:39936
	global_load_lds_dwordx4 v128, s[26:27]
	s_mov_b32 m0, s57
	s_nop 0
	global_load_lds_dwordx4 v130, s[26:27]
	s_waitcnt vmcnt(8)
	s_waitcnt lgkmcnt(0)
	s_setprio 1
	s_barrier
	v_mfma_f32_16x16x32_bf16 v[124:127], v[144:147], v[184:187], v[124:127]
	v_mfma_f32_16x16x32_bf16 v[120:123], v[160:163], v[184:187], v[120:123]
	v_mfma_f32_16x16x32_bf16 v[108:111], v[144:147], v[192:195], v[108:111]
	v_mfma_f32_16x16x32_bf16 v[104:107], v[160:163], v[192:195], v[104:107]
	v_mfma_f32_16x16x32_bf16 v[92:95], v[144:147], v[200:203], v[92:95]
	v_mfma_f32_16x16x32_bf16 v[88:91], v[160:163], v[200:203], v[88:91]
	v_mfma_f32_16x16x32_bf16 v[76:79], v[144:147], v[208:211], v[76:79]
	v_mfma_f32_16x16x32_bf16 v[72:75], v[160:163], v[208:211], v[72:75]
	v_mfma_f32_16x16x32_bf16 v[124:127], v[152:155], v[188:191], v[124:127]
	v_mfma_f32_16x16x32_bf16 v[120:123], v[164:167], v[188:191], v[120:123]
	v_mfma_f32_16x16x32_bf16 v[108:111], v[152:155], v[196:199], v[108:111]
	v_mfma_f32_16x16x32_bf16 v[104:107], v[164:167], v[196:199], v[104:107]
	v_mfma_f32_16x16x32_bf16 v[92:95], v[152:155], v[204:207], v[92:95]
	v_mfma_f32_16x16x32_bf16 v[88:91], v[164:167], v[204:207], v[88:91]
	v_mfma_f32_16x16x32_bf16 v[76:79], v[152:155], v[212:215], v[76:79]
	v_mfma_f32_16x16x32_bf16 v[72:75], v[164:167], v[212:215], v[72:75]
	v_mfma_f32_16x16x32_bf16 v[116:119], v[168:171], v[184:187], v[116:119]
	v_mfma_f32_16x16x32_bf16 v[112:115], v[176:179], v[184:187], v[112:115]
	v_mfma_f32_16x16x32_bf16 v[100:103], v[168:171], v[192:195], v[100:103]
	v_mfma_f32_16x16x32_bf16 v[96:99], v[176:179], v[192:195], v[96:99]
	v_mfma_f32_16x16x32_bf16 v[84:87], v[168:171], v[200:203], v[84:87]
	v_mfma_f32_16x16x32_bf16 v[80:83], v[176:179], v[200:203], v[80:83]
	v_mfma_f32_16x16x32_bf16 v[68:71], v[168:171], v[208:211], v[68:71]
	v_mfma_f32_16x16x32_bf16 v[64:67], v[176:179], v[208:211], v[64:67]
	v_mfma_f32_16x16x32_bf16 v[116:119], v[172:175], v[188:191], v[116:119]
	v_mfma_f32_16x16x32_bf16 v[112:115], v[180:183], v[188:191], v[112:115]
	v_mfma_f32_16x16x32_bf16 v[100:103], v[172:175], v[196:199], v[100:103]
	v_mfma_f32_16x16x32_bf16 v[96:99], v[180:183], v[196:199], v[96:99]
	v_mfma_f32_16x16x32_bf16 v[84:87], v[172:175], v[204:207], v[84:87]
	v_mfma_f32_16x16x32_bf16 v[80:83], v[180:183], v[204:207], v[80:83]
	v_mfma_f32_16x16x32_bf16 v[68:71], v[172:175], v[212:215], v[68:71]
	v_mfma_f32_16x16x32_bf16 v[64:67], v[180:183], v[212:215], v[64:67]
	s_setprio 0
	s_barrier
	s_add_i32 s26, s70, s53
	s_mov_b32 m0, s26
	ds_read_b128 v[184:187], v150 offset:49152
	ds_read_b128 v[188:191], v150 offset:50176
	ds_read_b128 v[192:195], v150 offset:51200
	ds_read_b128 v[196:199], v150 offset:52224
	ds_read_b128 v[200:203], v150 offset:53248
	ds_read_b128 v[204:207], v150 offset:54272
	ds_read_b128 v[208:211], v150 offset:55296
	ds_read_b128 v[212:215], v150 offset:56320
	global_load_lds_dwordx4 v132, s[98:99]
	s_add_i32 m0, s26, 0x2000
	s_add_u32 s26, s46, 0x20080
	s_addc_u32 s27, s47, 0
	s_add_i32 s46, s71, s53
	global_load_lds_dwordx4 v134, s[98:99]
	s_mov_b32 m0, s46
	s_nop 0
	global_load_lds_dwordx4 v132, s[26:27]
	s_add_i32 m0, s46, 0x2000
	s_nop 0
	global_load_lds_dwordx4 v134, s[26:27]
	s_mov_b32 m0, s59
	s_nop 0
	global_load_lds_dwordx4 v128, s[100:101]
	s_mov_b32 m0, s60
	s_nop 0
	global_load_lds_dwordx4 v130, s[100:101]
	s_waitcnt vmcnt(8)
	s_waitcnt lgkmcnt(0)
	s_setprio 1
	s_barrier
	v_mfma_f32_16x16x32_bf16 v[60:63], v[144:147], v[184:187], v[60:63]
	v_mfma_f32_16x16x32_bf16 v[56:59], v[160:163], v[184:187], v[56:59]
	v_mfma_f32_16x16x32_bf16 v[44:47], v[144:147], v[192:195], v[44:47]
	v_mfma_f32_16x16x32_bf16 v[40:43], v[160:163], v[192:195], v[40:43]
	v_mfma_f32_16x16x32_bf16 v[28:31], v[144:147], v[200:203], v[28:31]
	v_mfma_f32_16x16x32_bf16 v[24:27], v[160:163], v[200:203], v[24:27]
	v_mfma_f32_16x16x32_bf16 v[12:15], v[144:147], v[208:211], v[12:15]
	v_mfma_f32_16x16x32_bf16 v[8:11], v[160:163], v[208:211], v[8:11]
	v_mfma_f32_16x16x32_bf16 v[60:63], v[152:155], v[188:191], v[60:63]
	v_mfma_f32_16x16x32_bf16 v[56:59], v[164:167], v[188:191], v[56:59]
	v_mfma_f32_16x16x32_bf16 v[44:47], v[152:155], v[196:199], v[44:47]
	v_mfma_f32_16x16x32_bf16 v[40:43], v[164:167], v[196:199], v[40:43]
	v_mfma_f32_16x16x32_bf16 v[28:31], v[152:155], v[204:207], v[28:31]
	v_mfma_f32_16x16x32_bf16 v[24:27], v[164:167], v[204:207], v[24:27]
	v_mfma_f32_16x16x32_bf16 v[12:15], v[152:155], v[212:215], v[12:15]
	v_mfma_f32_16x16x32_bf16 v[8:11], v[164:167], v[212:215], v[8:11]
	v_mfma_f32_16x16x32_bf16 v[52:55], v[168:171], v[184:187], v[52:55]
	v_mfma_f32_16x16x32_bf16 v[48:51], v[176:179], v[184:187], v[48:51]
	v_mfma_f32_16x16x32_bf16 v[36:39], v[168:171], v[192:195], v[36:39]
	v_mfma_f32_16x16x32_bf16 v[32:35], v[176:179], v[192:195], v[32:35]
	v_mfma_f32_16x16x32_bf16 v[20:23], v[168:171], v[200:203], v[20:23]
	v_mfma_f32_16x16x32_bf16 v[16:19], v[176:179], v[200:203], v[16:19]
	v_mfma_f32_16x16x32_bf16 v[4:7], v[168:171], v[208:211], v[4:7]
	v_mfma_f32_16x16x32_bf16 v[0:3], v[176:179], v[208:211], v[0:3]
	v_mfma_f32_16x16x32_bf16 v[52:55], v[172:175], v[188:191], v[52:55]
	v_mfma_f32_16x16x32_bf16 v[48:51], v[180:183], v[188:191], v[48:51]
	v_mfma_f32_16x16x32_bf16 v[36:39], v[172:175], v[196:199], v[36:39]
	v_mfma_f32_16x16x32_bf16 v[32:35], v[180:183], v[196:199], v[32:35]
	v_mfma_f32_16x16x32_bf16 v[20:23], v[172:175], v[204:207], v[20:23]
	v_mfma_f32_16x16x32_bf16 v[16:19], v[180:183], v[204:207], v[16:19]
	v_mfma_f32_16x16x32_bf16 v[4:7], v[172:175], v[212:215], v[4:7]
	v_mfma_f32_16x16x32_bf16 v[0:3], v[180:183], v[212:215], v[0:3]
	s_setprio 0
	s_barrier
	s_add_i32 s69, s69, 2
	s_add_u32 s67, s67, 0x100
	s_addc_u32 s68, s68, 0
	s_cmp_gt_u32 s69, 5
	s_mov_b64 s[26:27], s[8:9]
	s_cbranch_scc0 .LBB0_1121
	s_and_b64 vcc, exec, s[18:19]
	s_cbranch_vccz .LBB0_1124
	s_barrier

; #define PG8_STAGE(bufoff, gbase, voff) do { _Pragma("unroll") for (int _i = 0; _i < 2; ++_i) \
;         __builtin_amdgcn_global_load_lds((const unsigned*)((const char*)(gbase) + (voff)[_i]), (LAS unsigned*)(lds + (bufoff) + ldsw + _i * 8192), 16, 0, 0); } while (0)
; #define PG8_LDA(dst, b, h) do { _Pragma("unroll") for (int m = 0; m < 4; ++m) _Pragma("unroll") for (int k = 0; k < 2; ++k) dst[m][k] = *(const LAS bf16x8*)(lds + PG8_SA(b, h) + aoff + m * 2048 + k * 1024); } while (0)
; #define PG8_LDB(dst, b, h) do { _Pragma("unroll") for (int n = 0; n < 2; ++n) _Pragma("unroll") for (int k = 0; k < 2; ++k) dst[n][k] = *(const LAS bf16x8*)(lds + PG8_SB(b, h) + boff + n * 2048 + k * 1024); } while (0)
; #define PG8_WAIT_V(n) asm volatile("s_waitcnt vmcnt(" #n ")" ::: "memory")
; #define PG8_WAIT_L(n) asm volatile("s_waitcnt lgkmcnt(" #n ")" ::: "memory")
; #define PG8_BAR __builtin_amdgcn_s_barrier()
; #define PG8_SCHED __builtin_amdgcn_sched_barrier(0)
; template <class Epi, bool FP8 = false>
; __device__ __forceinline__ void gemm_phase(LAS unsigned char* lds, const Gemm g, const StaticOrder& S_, const Epi& E, const int tid) {
;     ...
;             const bool last = (t == nt - 2);
;             const char* a1 = cA + (size_t)(t + 1) * kstep;
;             const char* a2 = last ? nA : cA + (size_t)(t + 2) * kstep; const char* b2 = last ? nB : cB + (size_t)(t + 2) * kstep;
;             const char* a3 = a2 + kstep; const char* b3 = b2 + kstep;
;             PG8_LDB(B0, 0, 0); PG8_LDB(B1, 0, 1); PG8_SCHED; PG8_LDA(At, 0, 0); PG8_STAGE(PG8_SA(1, 1), a1 + hstepA, voffA);
;             PG8_WAIT_V(8); PG8_WAIT_L(0); PG8_BAR; PG8_MMA(0, 0, At, B0); PG8_MMA(0, 1, At, B1); PG8_BAR; PG8_SCHED;
;             PG8_LDA(At, 0, 1); PG8_STAGE(PG8_SB(0, 0), b2, voffB); PG8_STAGE(PG8_SB(0, 1), b2 + hstepB, voffB); PG8_STAGE(PG8_SA(0, 0), a2, voffA);
;             PG8_WAIT_V(8); PG8_WAIT_L(0); PG8_BAR; PG8_MMA(1, 0, At, B0); PG8_MMA(1, 1, At, B1); PG8_BAR; PG8_SCHED;
.LBB0_1197:
	ds_read_b128 v[140:143], v152
	ds_read_b128 v[144:147], v152 offset:1024
	ds_read_b128 v[156:159], v152 offset:2048
	ds_read_b128 v[160:163], v152 offset:3072
	ds_read_b128 v[164:167], v153
	ds_read_b128 v[168:171], v153 offset:1024
	ds_read_b128 v[172:175], v153 offset:2048
	ds_read_b128 v[176:179], v153 offset:3072
	s_add_u32 s50, s48, 0xfff80080
	s_addc_u32 s51, s49, -1
	s_cmp_eq_u32 s70, 28
	s_cselect_b32 s53, s23, s51
	s_cselect_b32 s52, s43, s50
	s_cselect_b32 s51, s21, s69
	s_cselect_b32 s50, s66, s68
	s_add_i32 m0, s47, 0xc000
	ds_read_b128 v[180:183], v154
	ds_read_b128 v[184:187], v154 offset:1024
	ds_read_b128 v[188:191], v154 offset:2048
	ds_read_b128 v[192:195], v154 offset:3072
	ds_read_b128 v[196:199], v154 offset:4096
	ds_read_b128 v[200:203], v154 offset:5120
	ds_read_b128 v[204:207], v154 offset:6144
	ds_read_b128 v[208:211], v154 offset:7168
	global_load_lds_dwordx4 v132, s[48:49]
	s_add_i32 m0, s47, 0xe000
	s_nop 0
	global_load_lds_dwordx4 v134, s[48:49]
	s_waitcnt vmcnt(8)
	s_waitcnt lgkmcnt(0)
	s_setprio 1
	s_barrier
	v_mfma_f32_16x16x32_bf16 v[124:127], v[140:143], v[180:183], v[124:127]
	v_mfma_f32_16x16x32_bf16 v[120:123], v[156:159], v[180:183], v[120:123]
	v_mfma_f32_16x16x32_bf16 v[108:111], v[140:143], v[188:191], v[108:111]
	v_mfma_f32_16x16x32_bf16 v[104:107], v[156:159], v[188:191], v[104:107]
	v_mfma_f32_16x16x32_bf16 v[92:95], v[140:143], v[196:199], v[92:95]
	v_mfma_f32_16x16x32_bf16 v[88:91], v[156:159], v[196:199], v[88:91]
	v_mfma_f32_16x16x32_bf16 v[76:79], v[140:143], v[204:207], v[76:79]
	v_mfma_f32_16x16x32_bf16 v[72:75], v[156:159], v[204:207], v[72:75]
	v_mfma_f32_16x16x32_bf16 v[124:127], v[144:147], v[184:187], v[124:127]
	v_mfma_f32_16x16x32_bf16 v[120:123], v[160:163], v[184:187], v[120:123]
	v_mfma_f32_16x16x32_bf16 v[108:111], v[144:147], v[192:195], v[108:111]
	v_mfma_f32_16x16x32_bf16 v[104:107], v[160:163], v[192:195], v[104:107]
	v_mfma_f32_16x16x32_bf16 v[92:95], v[144:147], v[200:203], v[92:95]
	v_mfma_f32_16x16x32_bf16 v[88:91], v[160:163], v[200:203], v[88:91]
	v_mfma_f32_16x16x32_bf16 v[76:79], v[144:147], v[208:211], v[76:79]
	v_mfma_f32_16x16x32_bf16 v[72:75], v[160:163], v[208:211], v[72:75]
	v_mfma_f32_16x16x32_bf16 v[116:119], v[164:167], v[180:183], v[116:119]
	v_mfma_f32_16x16x32_bf16 v[112:115], v[172:175], v[180:183], v[112:115]
	v_mfma_f32_16x16x32_bf16 v[100:103], v[164:167], v[188:191], v[100:103]
	v_mfma_f32_16x16x32_bf16 v[96:99], v[172:175], v[188:191], v[96:99]
	v_mfma_f32_16x16x32_bf16 v[84:87], v[164:167], v[196:199], v[84:87]
	v_mfma_f32_16x16x32_bf16 v[80:83], v[172:175], v[196:199], v[80:83]
	v_mfma_f32_16x16x32_bf16 v[68:71], v[164:167], v[204:207], v[68:71]
	v_mfma_f32_16x16x32_bf16 v[64:67], v[172:175], v[204:207], v[64:67]
	v_mfma_f32_16x16x32_bf16 v[116:119], v[168:171], v[184:187], v[116:119]
	v_mfma_f32_16x16x32_bf16 v[112:115], v[176:179], v[184:187], v[112:115]
	v_mfma_f32_16x16x32_bf16 v[100:103], v[168:171], v[192:195], v[100:103]
	v_mfma_f32_16x16x32_bf16 v[96:99], v[176:179], v[192:195], v[96:99]
	v_mfma_f32_16x16x32_bf16 v[84:87], v[168:171], v[200:203], v[84:87]
	v_mfma_f32_16x16x32_bf16 v[80:83], v[176:179], v[200:203], v[80:83]
	v_mfma_f32_16x16x32_bf16 v[68:71], v[168:171], v[208:211], v[68:71]
	v_mfma_f32_16x16x32_bf16 v[64:67], v[176:179], v[208:211], v[64:67]
	s_setprio 0
	s_barrier
	s_add_u32 s98, s50, s14
	s_addc_u32 s99, s51, s15
	s_add_u32 s100, s52, s14
	s_addc_u32 s101, s53, s15
	s_add_i32 s71, s63, s56
	s_mov_b32 m0, s71
	ds_read_b128 v[180:183], v154 offset:16384
	ds_read_b128 v[184:187], v154 offset:17408
	ds_read_b128 v[188:191], v154 offset:18432
	ds_read_b128 v[192:195], v154 offset:19456
	ds_read_b128 v[196:199], v154 offset:20480
	ds_read_b128 v[200:203], v154 offset:21504
	ds_read_b128 v[204:207], v154 offset:22528
	ds_read_b128 v[208:211], v154 offset:23552
	global_load_lds_dwordx4 v128, s[50:51]
	s_add_i32 m0, s71, 0x2000
	s_add_u32 s72, s50, 0x80000
	s_addc_u32 s73, s51, 0
	s_add_i32 s71, s67, s56
	global_load_lds_dwordx4 v130, s[50:51]
	s_mov_b32 m0, s71
	s_nop 0
	global_load_lds_dwordx4 v128, s[72:73]
	s_add_i32 m0, s71, 0x2000
	s_nop 0
	global_load_lds_dwordx4 v130, s[72:73]
	s_mov_b32 m0, s47
	s_nop 0
	global_load_lds_dwordx4 v128, s[52:53]
	s_mov_b32 m0, s57
	s_nop 0
	global_load_lds_dwordx4 v130, s[52:53]
	s_waitcnt vmcnt(8)
	s_waitcnt lgkmcnt(0)
	s_setprio 1
	s_barrier
	v_mfma_f32_16x16x32_bf16 v[60:63], v[140:143], v[180:183], v[60:63]
	v_mfma_f32_16x16x32_bf16 v[56:59], v[156:159], v[180:183], v[56:59]
	v_mfma_f32_16x16x32_bf16 v[44:47], v[140:143], v[188:191], v[44:47]
	v_mfma_f32_16x16x32_bf16 v[40:43], v[156:159], v[188:191], v[40:43]
	v_mfma_f32_16x16x32_bf16 v[28:31], v[140:143], v[196:199], v[28:31]
	v_mfma_f32_16x16x32_bf16 v[24:27], v[156:159], v[196:199], v[24:27]
	v_mfma_f32_16x16x32_bf16 v[12:15], v[140:143], v[204:207], v[12:15]
	v_mfma_f32_16x16x32_bf16 v[8:11], v[156:159], v[204:207], v[8:11]
	v_mfma_f32_16x16x32_bf16 v[60:63], v[144:147], v[184:187], v[60:63]
	v_mfma_f32_16x16x32_bf16 v[56:59], v[160:163], v[184:187], v[56:59]
	v_mfma_f32_16x16x32_bf16 v[44:47], v[144:147], v[192:195], v[44:47]
	v_mfma_f32_16x16x32_bf16 v[40:43], v[160:163], v[192:195], v[40:43]
	v_mfma_f32_16x16x32_bf16 v[28:31], v[144:147], v[200:203], v[28:31]
	v_mfma_f32_16x16x32_bf16 v[24:27], v[160:163], v[200:203], v[24:27]
	v_mfma_f32_16x16x32_bf16 v[12:15], v[144:147], v[208:211], v[12:15]
	v_mfma_f32_16x16x32_bf16 v[8:11], v[160:163], v[208:211], v[8:11]
	v_mfma_f32_16x16x32_bf16 v[52:55], v[164:167], v[180:183], v[52:55]
	v_mfma_f32_16x16x32_bf16 v[48:51], v[172:175], v[180:183], v[48:51]
	v_mfma_f32_16x16x32_bf16 v[36:39], v[164:167], v[188:191], v[36:39]
	v_mfma_f32_16x16x32_bf16 v[32:35], v[172:175], v[188:191], v[32:35]
	v_mfma_f32_16x16x32_bf16 v[20:23], v[164:167], v[196:199], v[20:23]
	v_mfma_f32_16x16x32_bf16 v[16:19], v[172:175], v[196:199], v[16:19]
	v_mfma_f32_16x16x32_bf16 v[4:7], v[164:167], v[204:207], v[4:7]
	v_mfma_f32_16x16x32_bf16 v[0:3], v[172:175], v[204:207], v[0:3]
	v_mfma_f32_16x16x32_bf16 v[52:55], v[168:171], v[184:187], v[52:55]
	v_mfma_f32_16x16x32_bf16 v[48:51], v[176:179], v[184:187], v[48:51]
	v_mfma_f32_16x16x32_bf16 v[36:39], v[168:171], v[192:195], v[36:39]
	v_mfma_f32_16x16x32_bf16 v[32:35], v[176:179], v[192:195], v[32:35]
	v_mfma_f32_16x16x32_bf16 v[20:23], v[168:171], v[200:203], v[20:23]
	v_mfma_f32_16x16x32_bf16 v[16:19], v[176:179], v[200:203], v[16:19]
	v_mfma_f32_16x16x32_bf16 v[4:7], v[168:171], v[208:211], v[4:7]
	v_mfma_f32_16x16x32_bf16 v[0:3], v[176:179], v[208:211], v[0:3]
	s_setprio 0
	s_barrier
; #define PG8_STAGE(bufoff, gbase, voff) do { _Pragma("unroll") for (int _i = 0; _i < 2; ++_i) \
;         __builtin_amdgcn_global_load_lds((const unsigned*)((const char*)(gbase) + (voff)[_i]), (LAS unsigned*)(lds + (bufoff) + ldsw + _i * 8192), 16, 0, 0); } while (0)
; #define PG8_LDA(dst, b, h) do { _Pragma("unroll") for (int m = 0; m < 4; ++m) _Pragma("unroll") for (int k = 0; k < 2; ++k) dst[m][k] = *(const LAS bf16x8*)(lds + PG8_SA(b, h) + aoff + m * 2048 + k * 1024); } while (0)
; #define PG8_LDB(dst, b, h) do { _Pragma("unroll") for (int n = 0; n < 2; ++n) _Pragma("unroll") for (int k = 0; k < 2; ++k) dst[n][k] = *(const LAS bf16x8*)(lds + PG8_SB(b, h) + boff + n * 2048 + k * 1024); } while (0)
; #define PG8_WAIT_V(n) asm volatile("s_waitcnt vmcnt(" #n ")" ::: "memory")
; #define PG8_WAIT_L(n) asm volatile("s_waitcnt lgkmcnt(" #n ")" ::: "memory")
; #define PG8_BAR __builtin_amdgcn_s_barrier()
; #define PG8_SCHED __builtin_amdgcn_sched_barrier(0)
; template <class Epi, bool FP8 = false>
; __device__ __forceinline__ void gemm_phase(LAS unsigned char* lds, const Gemm g, const StaticOrder& S_, const Epi& E, const int tid) {
;     ...
;             PG8_LDB(B0, 1, 0); PG8_LDB(B1, 1, 1); PG8_SCHED; PG8_LDA(At, 1, 0); PG8_STAGE(PG8_SA(0, 1), a2 + hstepA, voffA);
;             PG8_WAIT_V(8); PG8_WAIT_L(0); PG8_BAR; PG8_MMA(0, 0, At, B0); PG8_MMA(0, 1, At, B1); PG8_BAR; PG8_SCHED;
;             PG8_LDA(At, 1, 1); PG8_STAGE(PG8_SB(1, 0), b3, voffB); PG8_STAGE(PG8_SB(1, 1), b3 + hstepB, voffB); PG8_STAGE(PG8_SA(1, 0), a3, voffA);
;             PG8_WAIT_V(8); PG8_WAIT_L(0); PG8_BAR; PG8_MMA(1, 0, At, B0); PG8_MMA(1, 1, At, B1); PG8_BAR; PG8_SCHED;
;         }
;         if (wr == 0) PG8_BAR;
	s_add_i32 s71, 0, 0x18000
	v_add_u32_e32 v155, s71, v150
	s_add_i32 s72, 0, 0x1c000
	ds_read_b128 v[140:143], v155
	ds_read_b128 v[144:147], v155 offset:1024
	ds_read_b128 v[156:159], v155 offset:2048
	ds_read_b128 v[160:163], v155 offset:3072
	v_add_u32_e32 v155, s72, v150
	ds_read_b128 v[164:167], v155
	ds_read_b128 v[168:171], v155 offset:1024
	ds_read_b128 v[172:175], v155 offset:2048
	ds_read_b128 v[176:179], v155 offset:3072
	s_add_u32 s52, s52, 0x80000
	s_addc_u32 s53, s53, 0
	s_mov_b32 m0, s58
	ds_read_b128 v[180:183], v154 offset:32768
	ds_read_b128 v[184:187], v154 offset:33792
	ds_read_b128 v[188:191], v154 offset:34816
	ds_read_b128 v[192:195], v154 offset:35840
	ds_read_b128 v[196:199], v154 offset:36864
	ds_read_b128 v[200:203], v154 offset:37888
	ds_read_b128 v[204:207], v154 offset:38912
	ds_read_b128 v[208:211], v154 offset:39936
	global_load_lds_dwordx4 v128, s[52:53]
	s_mov_b32 m0, s59
	s_nop 0
	global_load_lds_dwordx4 v130, s[52:53]
	s_waitcnt vmcnt(8)
	s_waitcnt lgkmcnt(0)
	s_setprio 1
	s_barrier
	v_mfma_f32_16x16x32_bf16 v[124:127], v[140:143], v[180:183], v[124:127]
	v_mfma_f32_16x16x32_bf16 v[120:123], v[156:159], v[180:183], v[120:123]
	v_mfma_f32_16x16x32_bf16 v[108:111], v[140:143], v[188:191], v[108:111]
	v_mfma_f32_16x16x32_bf16 v[104:107], v[156:159], v[188:191], v[104:107]
	v_mfma_f32_16x16x32_bf16 v[92:95], v[140:143], v[196:199], v[92:95]
	v_mfma_f32_16x16x32_bf16 v[88:91], v[156:159], v[196:199], v[88:91]
	v_mfma_f32_16x16x32_bf16 v[76:79], v[140:143], v[204:207], v[76:79]
	v_mfma_f32_16x16x32_bf16 v[72:75], v[156:159], v[204:207], v[72:75]
	v_mfma_f32_16x16x32_bf16 v[124:127], v[144:147], v[184:187], v[124:127]
	v_mfma_f32_16x16x32_bf16 v[120:123], v[160:163], v[184:187], v[120:123]
	v_mfma_f32_16x16x32_bf16 v[108:111], v[144:147], v[192:195], v[108:111]
	v_mfma_f32_16x16x32_bf16 v[104:107], v[160:163], v[192:195], v[104:107]
	v_mfma_f32_16x16x32_bf16 v[92:95], v[144:147], v[200:203], v[92:95]
	v_mfma_f32_16x16x32_bf16 v[88:91], v[160:163], v[200:203], v[88:91]
	v_mfma_f32_16x16x32_bf16 v[76:79], v[144:147], v[208:211], v[76:79]
	v_mfma_f32_16x16x32_bf16 v[72:75], v[160:163], v[208:211], v[72:75]
	v_mfma_f32_16x16x32_bf16 v[116:119], v[164:167], v[180:183], v[116:119]
	v_mfma_f32_16x16x32_bf16 v[112:115], v[172:175], v[180:183], v[112:115]
	v_mfma_f32_16x16x32_bf16 v[100:103], v[164:167], v[188:191], v[100:103]
	v_mfma_f32_16x16x32_bf16 v[96:99], v[172:175], v[188:191], v[96:99]
	v_mfma_f32_16x16x32_bf16 v[84:87], v[164:167], v[196:199], v[84:87]
	v_mfma_f32_16x16x32_bf16 v[80:83], v[172:175], v[196:199], v[80:83]
	v_mfma_f32_16x16x32_bf16 v[68:71], v[164:167], v[204:207], v[68:71]
	v_mfma_f32_16x16x32_bf16 v[64:67], v[172:175], v[204:207], v[64:67]
	v_mfma_f32_16x16x32_bf16 v[116:119], v[168:171], v[184:187], v[116:119]
	v_mfma_f32_16x16x32_bf16 v[112:115], v[176:179], v[184:187], v[112:115]
	v_mfma_f32_16x16x32_bf16 v[100:103], v[168:171], v[192:195], v[100:103]
	v_mfma_f32_16x16x32_bf16 v[96:99], v[176:179], v[192:195], v[96:99]
	v_mfma_f32_16x16x32_bf16 v[84:87], v[168:171], v[200:203], v[84:87]
	v_mfma_f32_16x16x32_bf16 v[80:83], v[176:179], v[200:203], v[80:83]
	v_mfma_f32_16x16x32_bf16 v[68:71], v[168:171], v[208:211], v[68:71]
	v_mfma_f32_16x16x32_bf16 v[64:67], v[176:179], v[208:211], v[64:67]
	s_setprio 0
	s_barrier
	s_add_i32 s52, s71, s56
	s_mov_b32 m0, s52
	ds_read_b128 v[180:183], v154 offset:49152
	ds_read_b128 v[184:187], v154 offset:50176
	ds_read_b128 v[188:191], v154 offset:51200
	ds_read_b128 v[192:195], v154 offset:52224
	ds_read_b128 v[196:199], v154 offset:53248
	ds_read_b128 v[200:203], v154 offset:54272
	ds_read_b128 v[204:207], v154 offset:55296
	ds_read_b128 v[208:211], v154 offset:56320
	global_load_lds_dwordx4 v128, s[98:99]
	s_add_i32 m0, s52, 0x2000
	s_add_u32 s50, s50, 0x80080
	s_addc_u32 s51, s51, 0
	s_add_i32 s52, s72, s56
	global_load_lds_dwordx4 v130, s[98:99]
	s_mov_b32 m0, s52
	s_nop 0
	global_load_lds_dwordx4 v128, s[50:51]
	s_add_i32 m0, s52, 0x2000
	s_nop 0
	global_load_lds_dwordx4 v130, s[50:51]
	s_mov_b32 m0, s61
	s_nop 0
	global_load_lds_dwordx4 v128, s[100:101]
	s_mov_b32 m0, s62
	s_nop 0
	global_load_lds_dwordx4 v130, s[100:101]
	s_waitcnt vmcnt(8)
	s_waitcnt lgkmcnt(0)
	s_setprio 1
	s_barrier
	v_mfma_f32_16x16x32_bf16 v[60:63], v[140:143], v[180:183], v[60:63]
	v_mfma_f32_16x16x32_bf16 v[56:59], v[156:159], v[180:183], v[56:59]
	v_mfma_f32_16x16x32_bf16 v[44:47], v[140:143], v[188:191], v[44:47]
	v_mfma_f32_16x16x32_bf16 v[40:43], v[156:159], v[188:191], v[40:43]
	v_mfma_f32_16x16x32_bf16 v[28:31], v[140:143], v[196:199], v[28:31]
	v_mfma_f32_16x16x32_bf16 v[24:27], v[156:159], v[196:199], v[24:27]
	v_mfma_f32_16x16x32_bf16 v[12:15], v[140:143], v[204:207], v[12:15]
	v_mfma_f32_16x16x32_bf16 v[8:11], v[156:159], v[204:207], v[8:11]
	v_mfma_f32_16x16x32_bf16 v[60:63], v[144:147], v[184:187], v[60:63]
	v_mfma_f32_16x16x32_bf16 v[56:59], v[160:163], v[184:187], v[56:59]
	v_mfma_f32_16x16x32_bf16 v[44:47], v[144:147], v[192:195], v[44:47]
	v_mfma_f32_16x16x32_bf16 v[40:43], v[160:163], v[192:195], v[40:43]
	v_mfma_f32_16x16x32_bf16 v[28:31], v[144:147], v[200:203], v[28:31]
	v_mfma_f32_16x16x32_bf16 v[24:27], v[160:163], v[200:203], v[24:27]
	v_mfma_f32_16x16x32_bf16 v[12:15], v[144:147], v[208:211], v[12:15]
	v_mfma_f32_16x16x32_bf16 v[8:11], v[160:163], v[208:211], v[8:11]
	v_mfma_f32_16x16x32_bf16 v[52:55], v[164:167], v[180:183], v[52:55]
	v_mfma_f32_16x16x32_bf16 v[48:51], v[172:175], v[180:183], v[48:51]
	v_mfma_f32_16x16x32_bf16 v[36:39], v[164:167], v[188:191], v[36:39]
	v_mfma_f32_16x16x32_bf16 v[32:35], v[172:175], v[188:191], v[32:35]
	v_mfma_f32_16x16x32_bf16 v[20:23], v[164:167], v[196:199], v[20:23]
	v_mfma_f32_16x16x32_bf16 v[16:19], v[172:175], v[196:199], v[16:19]
	v_mfma_f32_16x16x32_bf16 v[4:7], v[164:167], v[204:207], v[4:7]
	v_mfma_f32_16x16x32_bf16 v[0:3], v[172:175], v[204:207], v[0:3]
	v_mfma_f32_16x16x32_bf16 v[52:55], v[168:171], v[184:187], v[52:55]
	v_mfma_f32_16x16x32_bf16 v[48:51], v[176:179], v[184:187], v[48:51]
	v_mfma_f32_16x16x32_bf16 v[36:39], v[168:171], v[192:195], v[36:39]
	v_mfma_f32_16x16x32_bf16 v[32:35], v[176:179], v[192:195], v[32:35]
	v_mfma_f32_16x16x32_bf16 v[20:23], v[168:171], v[200:203], v[20:23]
	v_mfma_f32_16x16x32_bf16 v[16:19], v[176:179], v[200:203], v[16:19]
	v_mfma_f32_16x16x32_bf16 v[4:7], v[168:171], v[208:211], v[4:7]
	v_mfma_f32_16x16x32_bf16 v[0:3], v[176:179], v[208:211], v[0:3]
	s_setprio 0
	s_barrier
	s_add_i32 s70, s70, 2
	s_add_u32 s48, s48, 0x100
	s_addc_u32 s49, s49, 0
	s_add_u32 s68, s68, 0x100
	s_addc_u32 s69, s69, 0
	s_cmp_gt_u32 s70, 29
	s_cbranch_scc0 .LBB0_1197
	s_and_b64 vcc, exec, s[16:17]
	s_cbranch_vccz .LBB0_1200
	s_barrier

; #define PG8_STAGE(bufoff, gbase, voff) do { _Pragma("unroll") for (int _i = 0; _i < 2; ++_i) \
;         __builtin_amdgcn_global_load_lds((const unsigned*)((const char*)(gbase) + (voff)[_i]), (LAS unsigned*)(lds + (bufoff) + ldsw + _i * 8192), 16, 0, 0); } while (0)
; #define PG8_LDA(dst, b, h) do { _Pragma("unroll") for (int m = 0; m < 4; ++m) _Pragma("unroll") for (int k = 0; k < 2; ++k) dst[m][k] = *(const LAS bf16x8*)(lds + PG8_SA(b, h) + aoff + m * 2048 + k * 1024); } while (0)
; #define PG8_LDB(dst, b, h) do { _Pragma("unroll") for (int n = 0; n < 2; ++n) _Pragma("unroll") for (int k = 0; k < 2; ++k) dst[n][k] = *(const LAS bf16x8*)(lds + PG8_SB(b, h) + boff + n * 2048 + k * 1024); } while (0)
; #define PG8_WAIT_V(n) asm volatile("s_waitcnt vmcnt(" #n ")" ::: "memory")
; #define PG8_WAIT_L(n) asm volatile("s_waitcnt lgkmcnt(" #n ")" ::: "memory")
; #define PG8_BAR __builtin_amdgcn_s_barrier()
; #define PG8_SCHED __builtin_amdgcn_sched_barrier(0)
; template <class Epi, bool FP8 = false>
; __device__ __forceinline__ void gemm_phase(LAS unsigned char* lds, const Gemm g, const StaticOrder& S_, const Epi& E, const int tid) {
;     ...
;             const bool last = (t == nt - 2);
;             const char* a1 = cA + (size_t)(t + 1) * kstep;
;             const char* a2 = last ? nA : cA + (size_t)(t + 2) * kstep; const char* b2 = last ? nB : cB + (size_t)(t + 2) * kstep;
;             const char* a3 = a2 + kstep; const char* b3 = b2 + kstep;
;             PG8_LDB(B0, 0, 0); PG8_LDB(B1, 0, 1); PG8_SCHED; PG8_LDA(At, 0, 0); PG8_STAGE(PG8_SA(1, 1), a1 + hstepA, voffA);
;             PG8_WAIT_V(8); PG8_WAIT_L(0); PG8_BAR; PG8_MMA(0, 0, At, B0); PG8_MMA(0, 1, At, B1); PG8_BAR; PG8_SCHED;
;             PG8_LDA(At, 0, 1); PG8_STAGE(PG8_SB(0, 0), b2, voffB); PG8_STAGE(PG8_SB(0, 1), b2 + hstepB, voffB); PG8_STAGE(PG8_SA(0, 0), a2, voffA);
;             PG8_WAIT_V(8); PG8_WAIT_L(0); PG8_BAR; PG8_MMA(1, 0, At, B0); PG8_MMA(1, 1, At, B1); PG8_BAR; PG8_SCHED;
.LBB0_1340:
	ds_read_b128 v[150:153], v147
	ds_read_b128 v[154:157], v147 offset:1024
	ds_read_b128 v[158:161], v147 offset:2048
	ds_read_b128 v[162:165], v147 offset:3072
	ds_read_b128 v[166:169], v148
	ds_read_b128 v[170:173], v148 offset:1024
	ds_read_b128 v[174:177], v148 offset:2048
	ds_read_b128 v[178:181], v148 offset:3072
	s_add_u32 s42, s30, 0xfff80080
	s_addc_u32 s43, s31, -1
	s_cmp_eq_u32 s69, 28
	s_cselect_b32 s47, s23, s43
	s_cselect_b32 s46, s63, s42
	s_cselect_b32 s43, s21, s68
	s_cselect_b32 s42, s66, s67
	s_add_i32 m0, s29, 0xc000
	ds_read_b128 v[182:185], v149
	ds_read_b128 v[186:189], v149 offset:1024
	ds_read_b128 v[190:193], v149 offset:2048
	ds_read_b128 v[194:197], v149 offset:3072
	ds_read_b128 v[198:201], v149 offset:4096
	ds_read_b128 v[202:205], v149 offset:5120
	ds_read_b128 v[206:209], v149 offset:6144
	ds_read_b128 v[210:213], v149 offset:7168
	global_load_lds_dwordx4 v136, s[30:31]
	s_add_i32 m0, s29, 0xe000
	s_nop 0
	global_load_lds_dwordx4 v138, s[30:31]
	s_waitcnt vmcnt(8)
	s_waitcnt lgkmcnt(0)
	s_setprio 1
	s_barrier
	v_mfma_f32_16x16x32_bf16 v[124:127], v[150:153], v[182:185], v[124:127]
	v_mfma_f32_16x16x32_bf16 v[120:123], v[158:161], v[182:185], v[120:123]
	v_mfma_f32_16x16x32_bf16 v[108:111], v[150:153], v[190:193], v[108:111]
	v_mfma_f32_16x16x32_bf16 v[104:107], v[158:161], v[190:193], v[104:107]
	v_mfma_f32_16x16x32_bf16 v[92:95], v[150:153], v[198:201], v[92:95]
	v_mfma_f32_16x16x32_bf16 v[88:91], v[158:161], v[198:201], v[88:91]
	v_mfma_f32_16x16x32_bf16 v[76:79], v[150:153], v[206:209], v[76:79]
	v_mfma_f32_16x16x32_bf16 v[72:75], v[158:161], v[206:209], v[72:75]
	v_mfma_f32_16x16x32_bf16 v[124:127], v[154:157], v[186:189], v[124:127]
	v_mfma_f32_16x16x32_bf16 v[120:123], v[162:165], v[186:189], v[120:123]
	v_mfma_f32_16x16x32_bf16 v[108:111], v[154:157], v[194:197], v[108:111]
	v_mfma_f32_16x16x32_bf16 v[104:107], v[162:165], v[194:197], v[104:107]
	v_mfma_f32_16x16x32_bf16 v[92:95], v[154:157], v[202:205], v[92:95]
	v_mfma_f32_16x16x32_bf16 v[88:91], v[162:165], v[202:205], v[88:91]
	v_mfma_f32_16x16x32_bf16 v[76:79], v[154:157], v[210:213], v[76:79]
	v_mfma_f32_16x16x32_bf16 v[72:75], v[162:165], v[210:213], v[72:75]
	v_mfma_f32_16x16x32_bf16 v[116:119], v[166:169], v[182:185], v[116:119]
	v_mfma_f32_16x16x32_bf16 v[112:115], v[174:177], v[182:185], v[112:115]
	v_mfma_f32_16x16x32_bf16 v[100:103], v[166:169], v[190:193], v[100:103]
	v_mfma_f32_16x16x32_bf16 v[96:99], v[174:177], v[190:193], v[96:99]
	v_mfma_f32_16x16x32_bf16 v[84:87], v[166:169], v[198:201], v[84:87]
	v_mfma_f32_16x16x32_bf16 v[80:83], v[174:177], v[198:201], v[80:83]
	v_mfma_f32_16x16x32_bf16 v[68:71], v[166:169], v[206:209], v[68:71]
	v_mfma_f32_16x16x32_bf16 v[64:67], v[174:177], v[206:209], v[64:67]
	v_mfma_f32_16x16x32_bf16 v[116:119], v[170:173], v[186:189], v[116:119]
	v_mfma_f32_16x16x32_bf16 v[112:115], v[178:181], v[186:189], v[112:115]
	v_mfma_f32_16x16x32_bf16 v[100:103], v[170:173], v[194:197], v[100:103]
	v_mfma_f32_16x16x32_bf16 v[96:99], v[178:181], v[194:197], v[96:99]
	v_mfma_f32_16x16x32_bf16 v[84:87], v[170:173], v[202:205], v[84:87]
	v_mfma_f32_16x16x32_bf16 v[80:83], v[178:181], v[202:205], v[80:83]
	v_mfma_f32_16x16x32_bf16 v[68:71], v[170:173], v[210:213], v[68:71]
	v_mfma_f32_16x16x32_bf16 v[64:67], v[178:181], v[210:213], v[64:67]
	s_setprio 0
	s_barrier
	s_add_u32 s98, s42, s16
	s_addc_u32 s99, s43, s17
	s_add_u32 s100, s46, s16
	s_addc_u32 s101, s47, s17
	s_add_i32 s70, s59, s50
	s_mov_b32 m0, s70
	ds_read_b128 v[182:185], v149 offset:16384
	ds_read_b128 v[186:189], v149 offset:17408
	ds_read_b128 v[190:193], v149 offset:18432
	ds_read_b128 v[194:197], v149 offset:19456
	ds_read_b128 v[198:201], v149 offset:20480
	ds_read_b128 v[202:205], v149 offset:21504
	ds_read_b128 v[206:209], v149 offset:22528
	ds_read_b128 v[210:213], v149 offset:23552
	global_load_lds_dwordx4 v128, s[42:43]
	s_add_i32 m0, s70, 0x2000
	s_add_u32 s70, s42, 0x80000
	s_addc_u32 s71, s43, 0
	s_add_i32 s72, s60, s50
	global_load_lds_dwordx4 v130, s[42:43]
	s_mov_b32 m0, s72
	s_nop 0
	global_load_lds_dwordx4 v128, s[70:71]
	s_add_i32 m0, s72, 0x2000
	s_nop 0
	global_load_lds_dwordx4 v130, s[70:71]
	s_mov_b32 m0, s29
	s_nop 0
	global_load_lds_dwordx4 v134, s[46:47]
	s_mov_b32 m0, s53
	s_nop 0
	global_load_lds_dwordx4 v132, s[46:47]
	s_waitcnt vmcnt(8)
	s_waitcnt lgkmcnt(0)
	s_setprio 1
	s_barrier
	v_mfma_f32_16x16x32_bf16 v[60:63], v[150:153], v[182:185], v[60:63]
	v_mfma_f32_16x16x32_bf16 v[56:59], v[158:161], v[182:185], v[56:59]
	v_mfma_f32_16x16x32_bf16 v[44:47], v[150:153], v[190:193], v[44:47]
	v_mfma_f32_16x16x32_bf16 v[40:43], v[158:161], v[190:193], v[40:43]
	v_mfma_f32_16x16x32_bf16 v[28:31], v[150:153], v[198:201], v[28:31]
	v_mfma_f32_16x16x32_bf16 v[24:27], v[158:161], v[198:201], v[24:27]
	v_mfma_f32_16x16x32_bf16 v[12:15], v[150:153], v[206:209], v[12:15]
	v_mfma_f32_16x16x32_bf16 v[8:11], v[158:161], v[206:209], v[8:11]
	v_mfma_f32_16x16x32_bf16 v[60:63], v[154:157], v[186:189], v[60:63]
	v_mfma_f32_16x16x32_bf16 v[56:59], v[162:165], v[186:189], v[56:59]
	v_mfma_f32_16x16x32_bf16 v[44:47], v[154:157], v[194:197], v[44:47]
	v_mfma_f32_16x16x32_bf16 v[40:43], v[162:165], v[194:197], v[40:43]
	v_mfma_f32_16x16x32_bf16 v[28:31], v[154:157], v[202:205], v[28:31]
	v_mfma_f32_16x16x32_bf16 v[24:27], v[162:165], v[202:205], v[24:27]
	v_mfma_f32_16x16x32_bf16 v[12:15], v[154:157], v[210:213], v[12:15]
	v_mfma_f32_16x16x32_bf16 v[8:11], v[162:165], v[210:213], v[8:11]
	v_mfma_f32_16x16x32_bf16 v[52:55], v[166:169], v[182:185], v[52:55]
	v_mfma_f32_16x16x32_bf16 v[48:51], v[174:177], v[182:185], v[48:51]
	v_mfma_f32_16x16x32_bf16 v[36:39], v[166:169], v[190:193], v[36:39]
	v_mfma_f32_16x16x32_bf16 v[32:35], v[174:177], v[190:193], v[32:35]
	v_mfma_f32_16x16x32_bf16 v[20:23], v[166:169], v[198:201], v[20:23]
	v_mfma_f32_16x16x32_bf16 v[16:19], v[174:177], v[198:201], v[16:19]
	v_mfma_f32_16x16x32_bf16 v[4:7], v[166:169], v[206:209], v[4:7]
	v_mfma_f32_16x16x32_bf16 v[0:3], v[174:177], v[206:209], v[0:3]
	v_mfma_f32_16x16x32_bf16 v[52:55], v[170:173], v[186:189], v[52:55]
	v_mfma_f32_16x16x32_bf16 v[48:51], v[178:181], v[186:189], v[48:51]
	v_mfma_f32_16x16x32_bf16 v[36:39], v[170:173], v[194:197], v[36:39]
	v_mfma_f32_16x16x32_bf16 v[32:35], v[178:181], v[194:197], v[32:35]
	v_mfma_f32_16x16x32_bf16 v[20:23], v[170:173], v[202:205], v[20:23]
	v_mfma_f32_16x16x32_bf16 v[16:19], v[178:181], v[202:205], v[16:19]
	v_mfma_f32_16x16x32_bf16 v[4:7], v[170:173], v[210:213], v[4:7]
	v_mfma_f32_16x16x32_bf16 v[0:3], v[178:181], v[210:213], v[0:3]
	s_setprio 0
	s_barrier
; #define PG8_STAGE(bufoff, gbase, voff) do { _Pragma("unroll") for (int _i = 0; _i < 2; ++_i) \
;         __builtin_amdgcn_global_load_lds((const unsigned*)((const char*)(gbase) + (voff)[_i]), (LAS unsigned*)(lds + (bufoff) + ldsw + _i * 8192), 16, 0, 0); } while (0)
; #define PG8_LDA(dst, b, h) do { _Pragma("unroll") for (int m = 0; m < 4; ++m) _Pragma("unroll") for (int k = 0; k < 2; ++k) dst[m][k] = *(const LAS bf16x8*)(lds + PG8_SA(b, h) + aoff + m * 2048 + k * 1024); } while (0)
; #define PG8_LDB(dst, b, h) do { _Pragma("unroll") for (int n = 0; n < 2; ++n) _Pragma("unroll") for (int k = 0; k < 2; ++k) dst[n][k] = *(const LAS bf16x8*)(lds + PG8_SB(b, h) + boff + n * 2048 + k * 1024); } while (0)
; #define PG8_WAIT_V(n) asm volatile("s_waitcnt vmcnt(" #n ")" ::: "memory")
; #define PG8_WAIT_L(n) asm volatile("s_waitcnt lgkmcnt(" #n ")" ::: "memory")
; #define PG8_BAR __builtin_amdgcn_s_barrier()
; #define PG8_SCHED __builtin_amdgcn_sched_barrier(0)
; template <class Epi, bool FP8 = false>
; __device__ __forceinline__ void gemm_phase(LAS unsigned char* lds, const Gemm g, const StaticOrder& S_, const Epi& E, const int tid) {
;     ...
;             PG8_LDB(B0, 1, 0); PG8_LDB(B1, 1, 1); PG8_SCHED; PG8_LDA(At, 1, 0); PG8_STAGE(PG8_SA(0, 1), a2 + hstepA, voffA);
;             PG8_WAIT_V(8); PG8_WAIT_L(0); PG8_BAR; PG8_MMA(0, 0, At, B0); PG8_MMA(0, 1, At, B1); PG8_BAR; PG8_SCHED;
;             PG8_LDA(At, 1, 1); PG8_STAGE(PG8_SB(1, 0), b3, voffB); PG8_STAGE(PG8_SB(1, 1), b3 + hstepB, voffB); PG8_STAGE(PG8_SA(1, 0), a3, voffA);
;             PG8_WAIT_V(8); PG8_WAIT_L(0); PG8_BAR; PG8_MMA(1, 0, At, B0); PG8_MMA(1, 1, At, B1); PG8_BAR; PG8_SCHED;
;         }
;         if (wr == 0) PG8_BAR;
	s_add_i32 s70, 0, 0x18000
	s_add_i32 s71, 0, 0x1c000
	v_add_u32_e32 v162, s70, v145
	v_add_u32_e32 v178, s71, v145
	ds_read_b128 v[150:153], v162
	ds_read_b128 v[154:157], v162 offset:1024
	ds_read_b128 v[158:161], v162 offset:2048
	ds_read_b128 v[162:165], v162 offset:3072
	ds_read_b128 v[166:169], v178
	ds_read_b128 v[170:173], v178 offset:1024
	ds_read_b128 v[174:177], v178 offset:2048
	ds_read_b128 v[178:181], v178 offset:3072
	s_add_u32 s46, s46, 0x80000
	s_addc_u32 s47, s47, 0
	s_mov_b32 m0, s54
	ds_read_b128 v[182:185], v149 offset:32768
	ds_read_b128 v[186:189], v149 offset:33792
	ds_read_b128 v[190:193], v149 offset:34816
	ds_read_b128 v[194:197], v149 offset:35840
	ds_read_b128 v[198:201], v149 offset:36864
	ds_read_b128 v[202:205], v149 offset:37888
	ds_read_b128 v[206:209], v149 offset:38912
	ds_read_b128 v[210:213], v149 offset:39936
	global_load_lds_dwordx4 v134, s[46:47]
	s_mov_b32 m0, s55
	s_nop 0
	global_load_lds_dwordx4 v132, s[46:47]
	s_waitcnt vmcnt(8)
	s_waitcnt lgkmcnt(0)
	s_setprio 1
	s_barrier
	v_mfma_f32_16x16x32_bf16 v[124:127], v[150:153], v[182:185], v[124:127]
	v_mfma_f32_16x16x32_bf16 v[120:123], v[158:161], v[182:185], v[120:123]
	v_mfma_f32_16x16x32_bf16 v[108:111], v[150:153], v[190:193], v[108:111]
	v_mfma_f32_16x16x32_bf16 v[104:107], v[158:161], v[190:193], v[104:107]
	v_mfma_f32_16x16x32_bf16 v[92:95], v[150:153], v[198:201], v[92:95]
	v_mfma_f32_16x16x32_bf16 v[88:91], v[158:161], v[198:201], v[88:91]
	v_mfma_f32_16x16x32_bf16 v[76:79], v[150:153], v[206:209], v[76:79]
	v_mfma_f32_16x16x32_bf16 v[72:75], v[158:161], v[206:209], v[72:75]
	v_mfma_f32_16x16x32_bf16 v[124:127], v[154:157], v[186:189], v[124:127]
	v_mfma_f32_16x16x32_bf16 v[120:123], v[162:165], v[186:189], v[120:123]
	v_mfma_f32_16x16x32_bf16 v[108:111], v[154:157], v[194:197], v[108:111]
	v_mfma_f32_16x16x32_bf16 v[104:107], v[162:165], v[194:197], v[104:107]
	v_mfma_f32_16x16x32_bf16 v[92:95], v[154:157], v[202:205], v[92:95]
	v_mfma_f32_16x16x32_bf16 v[88:91], v[162:165], v[202:205], v[88:91]
	v_mfma_f32_16x16x32_bf16 v[76:79], v[154:157], v[210:213], v[76:79]
	v_mfma_f32_16x16x32_bf16 v[72:75], v[162:165], v[210:213], v[72:75]
	v_mfma_f32_16x16x32_bf16 v[116:119], v[166:169], v[182:185], v[116:119]
	v_mfma_f32_16x16x32_bf16 v[112:115], v[174:177], v[182:185], v[112:115]
	v_mfma_f32_16x16x32_bf16 v[100:103], v[166:169], v[190:193], v[100:103]
	v_mfma_f32_16x16x32_bf16 v[96:99], v[174:177], v[190:193], v[96:99]
	v_mfma_f32_16x16x32_bf16 v[84:87], v[166:169], v[198:201], v[84:87]
	v_mfma_f32_16x16x32_bf16 v[80:83], v[174:177], v[198:201], v[80:83]
	v_mfma_f32_16x16x32_bf16 v[68:71], v[166:169], v[206:209], v[68:71]
	v_mfma_f32_16x16x32_bf16 v[64:67], v[174:177], v[206:209], v[64:67]
	v_mfma_f32_16x16x32_bf16 v[116:119], v[170:173], v[186:189], v[116:119]
	v_mfma_f32_16x16x32_bf16 v[112:115], v[178:181], v[186:189], v[112:115]
	v_mfma_f32_16x16x32_bf16 v[100:103], v[170:173], v[194:197], v[100:103]
	v_mfma_f32_16x16x32_bf16 v[96:99], v[178:181], v[194:197], v[96:99]
	v_mfma_f32_16x16x32_bf16 v[84:87], v[170:173], v[202:205], v[84:87]
	v_mfma_f32_16x16x32_bf16 v[80:83], v[178:181], v[202:205], v[80:83]
	v_mfma_f32_16x16x32_bf16 v[68:71], v[170:173], v[210:213], v[68:71]
	v_mfma_f32_16x16x32_bf16 v[64:67], v[178:181], v[210:213], v[64:67]
	s_setprio 0
	s_barrier
	s_add_i32 s46, s70, s50
	s_mov_b32 m0, s46
	ds_read_b128 v[182:185], v149 offset:49152
	ds_read_b128 v[186:189], v149 offset:50176
	ds_read_b128 v[190:193], v149 offset:51200
	ds_read_b128 v[194:197], v149 offset:52224
	ds_read_b128 v[198:201], v149 offset:53248
	ds_read_b128 v[202:205], v149 offset:54272
	ds_read_b128 v[206:209], v149 offset:55296
	ds_read_b128 v[210:213], v149 offset:56320
	global_load_lds_dwordx4 v128, s[98:99]
	s_add_i32 m0, s46, 0x2000
	s_add_u32 s42, s42, 0x80080
	s_addc_u32 s43, s43, 0
	s_add_i32 s46, s71, s50
	global_load_lds_dwordx4 v130, s[98:99]
	s_mov_b32 m0, s46
	s_nop 0
	global_load_lds_dwordx4 v128, s[42:43]
	s_add_i32 m0, s46, 0x2000
	s_nop 0
	global_load_lds_dwordx4 v130, s[42:43]
	s_mov_b32 m0, s57
	s_nop 0
	global_load_lds_dwordx4 v134, s[100:101]
	s_mov_b32 m0, s58
	s_nop 0
	global_load_lds_dwordx4 v132, s[100:101]
	s_waitcnt vmcnt(8)
	s_waitcnt lgkmcnt(0)
	s_setprio 1
	s_barrier
	v_mfma_f32_16x16x32_bf16 v[60:63], v[150:153], v[182:185], v[60:63]
	v_mfma_f32_16x16x32_bf16 v[56:59], v[158:161], v[182:185], v[56:59]
	v_mfma_f32_16x16x32_bf16 v[44:47], v[150:153], v[190:193], v[44:47]
	v_mfma_f32_16x16x32_bf16 v[40:43], v[158:161], v[190:193], v[40:43]
	v_mfma_f32_16x16x32_bf16 v[28:31], v[150:153], v[198:201], v[28:31]
	v_mfma_f32_16x16x32_bf16 v[24:27], v[158:161], v[198:201], v[24:27]
	v_mfma_f32_16x16x32_bf16 v[12:15], v[150:153], v[206:209], v[12:15]
	v_mfma_f32_16x16x32_bf16 v[8:11], v[158:161], v[206:209], v[8:11]
	v_mfma_f32_16x16x32_bf16 v[60:63], v[154:157], v[186:189], v[60:63]
	v_mfma_f32_16x16x32_bf16 v[56:59], v[162:165], v[186:189], v[56:59]
	v_mfma_f32_16x16x32_bf16 v[44:47], v[154:157], v[194:197], v[44:47]
	v_mfma_f32_16x16x32_bf16 v[40:43], v[162:165], v[194:197], v[40:43]
	v_mfma_f32_16x16x32_bf16 v[28:31], v[154:157], v[202:205], v[28:31]
	v_mfma_f32_16x16x32_bf16 v[24:27], v[162:165], v[202:205], v[24:27]
	v_mfma_f32_16x16x32_bf16 v[12:15], v[154:157], v[210:213], v[12:15]
	v_mfma_f32_16x16x32_bf16 v[8:11], v[162:165], v[210:213], v[8:11]
	v_mfma_f32_16x16x32_bf16 v[52:55], v[166:169], v[182:185], v[52:55]
	v_mfma_f32_16x16x32_bf16 v[48:51], v[174:177], v[182:185], v[48:51]
	v_mfma_f32_16x16x32_bf16 v[36:39], v[166:169], v[190:193], v[36:39]
	v_mfma_f32_16x16x32_bf16 v[32:35], v[174:177], v[190:193], v[32:35]
	v_mfma_f32_16x16x32_bf16 v[20:23], v[166:169], v[198:201], v[20:23]
	v_mfma_f32_16x16x32_bf16 v[16:19], v[174:177], v[198:201], v[16:19]
	v_mfma_f32_16x16x32_bf16 v[4:7], v[166:169], v[206:209], v[4:7]
	v_mfma_f32_16x16x32_bf16 v[0:3], v[174:177], v[206:209], v[0:3]
	v_mfma_f32_16x16x32_bf16 v[52:55], v[170:173], v[186:189], v[52:55]
	v_mfma_f32_16x16x32_bf16 v[48:51], v[178:181], v[186:189], v[48:51]
	v_mfma_f32_16x16x32_bf16 v[36:39], v[170:173], v[194:197], v[36:39]
	v_mfma_f32_16x16x32_bf16 v[32:35], v[178:181], v[194:197], v[32:35]
	v_mfma_f32_16x16x32_bf16 v[20:23], v[170:173], v[202:205], v[20:23]
	v_mfma_f32_16x16x32_bf16 v[16:19], v[178:181], v[202:205], v[16:19]
	v_mfma_f32_16x16x32_bf16 v[4:7], v[170:173], v[210:213], v[4:7]
	v_mfma_f32_16x16x32_bf16 v[0:3], v[178:181], v[210:213], v[0:3]
	s_setprio 0
	s_barrier
	s_add_i32 s69, s69, 2
	s_add_u32 s30, s30, 0x100
	s_addc_u32 s31, s31, 0
	s_add_u32 s67, s67, 0x100
	s_addc_u32 s68, s68, 0
	s_cmp_gt_u32 s69, 29
	s_cbranch_scc0 .LBB0_1340
	s_and_b64 vcc, exec, s[18:19]
	s_cbranch_vccz .LBB0_1343
	s_barrier

; #define PG8_STAGE(bufoff, gbase, voff) do { _Pragma("unroll") for (int _i = 0; _i < 2; ++_i) \
;         __builtin_amdgcn_global_load_lds((const unsigned*)((const char*)(gbase) + (voff)[_i]), (LAS unsigned*)(lds + (bufoff) + ldsw + _i * 8192), 16, 0, 0); } while (0)
; #define PG8_LDA(dst, b, h) do { _Pragma("unroll") for (int m = 0; m < 4; ++m) _Pragma("unroll") for (int k = 0; k < 2; ++k) dst[m][k] = *(const LAS bf16x8*)(lds + PG8_SA(b, h) + aoff + m * 2048 + k * 1024); } while (0)
; #define PG8_LDB(dst, b, h) do { _Pragma("unroll") for (int n = 0; n < 2; ++n) _Pragma("unroll") for (int k = 0; k < 2; ++k) dst[n][k] = *(const LAS bf16x8*)(lds + PG8_SB(b, h) + boff + n * 2048 + k * 1024); } while (0)
; #define PG8_WAIT_V(n) asm volatile("s_waitcnt vmcnt(" #n ")" ::: "memory")
; #define PG8_WAIT_L(n) asm volatile("s_waitcnt lgkmcnt(" #n ")" ::: "memory")
; #define PG8_BAR __builtin_amdgcn_s_barrier()
; #define PG8_SCHED __builtin_amdgcn_sched_barrier(0)
; template <class Epi, bool FP8 = false>
; __device__ __forceinline__ void gemm_phase(LAS unsigned char* lds, const Gemm g, const StaticOrder& S_, const Epi& E, const int tid) {
;     ...
;             const bool last = (t == nt - 2);
;             const char* a1 = cA + (size_t)(t + 1) * kstep;
;             const char* a2 = last ? nA : cA + (size_t)(t + 2) * kstep; const char* b2 = last ? nB : cB + (size_t)(t + 2) * kstep;
;             const char* a3 = a2 + kstep; const char* b3 = b2 + kstep;
;             PG8_LDB(B0, 0, 0); PG8_LDB(B1, 0, 1); PG8_SCHED; PG8_LDA(At, 0, 0); PG8_STAGE(PG8_SA(1, 1), a1 + hstepA, voffA);
;             PG8_WAIT_V(8); PG8_WAIT_L(0); PG8_BAR; PG8_MMA(0, 0, At, B0); PG8_MMA(0, 1, At, B1); PG8_BAR; PG8_SCHED;
;             PG8_LDA(At, 0, 1); PG8_STAGE(PG8_SB(0, 0), b2, voffB); PG8_STAGE(PG8_SB(0, 1), b2 + hstepB, voffB); PG8_STAGE(PG8_SA(0, 0), a2, voffA);
;             PG8_WAIT_V(8); PG8_WAIT_L(0); PG8_BAR; PG8_MMA(1, 0, At, B0); PG8_MMA(1, 1, At, B1); PG8_BAR; PG8_SCHED;
.LBB0_1420:
	ds_read_b128 v[140:143], v152
	ds_read_b128 v[144:147], v152 offset:1024
	ds_read_b128 v[156:159], v152 offset:2048
	ds_read_b128 v[160:163], v152 offset:3072
	ds_read_b128 v[164:167], v153
	ds_read_b128 v[168:171], v153 offset:1024
	ds_read_b128 v[172:175], v153 offset:2048
	ds_read_b128 v[176:179], v153 offset:3072
	s_add_u32 s28, s26, 0x100
	s_addc_u32 s29, s27, 0
	s_cmpk_eq_i32 s66, 0x54
	s_cselect_b32 s43, s7, s29
	s_cselect_b32 s42, s6, s28
	s_cselect_b32 s31, s25, s63
	s_cselect_b32 s30, s24, s62
	s_add_i32 m0, s49, 0xc000
	ds_read_b128 v[180:183], v154
	ds_read_b128 v[184:187], v154 offset:1024
	ds_read_b128 v[188:191], v154 offset:2048
	ds_read_b128 v[192:195], v154 offset:3072
	ds_read_b128 v[196:199], v154 offset:4096
	ds_read_b128 v[200:203], v154 offset:5120
	ds_read_b128 v[204:207], v154 offset:6144
	ds_read_b128 v[208:211], v154 offset:7168
	global_load_lds_dwordx4 v132, s[26:27]
	s_add_i32 m0, s49, 0xe000
	s_nop 0
	global_load_lds_dwordx4 v134, s[26:27]
	s_waitcnt vmcnt(8)
	s_waitcnt lgkmcnt(0)
	s_setprio 1
	s_barrier
	v_mfma_f32_16x16x32_bf16 v[124:127], v[140:143], v[180:183], v[124:127]
	v_mfma_f32_16x16x32_bf16 v[120:123], v[156:159], v[180:183], v[120:123]
	v_mfma_f32_16x16x32_bf16 v[108:111], v[140:143], v[188:191], v[108:111]
	v_mfma_f32_16x16x32_bf16 v[104:107], v[156:159], v[188:191], v[104:107]
	v_mfma_f32_16x16x32_bf16 v[92:95], v[140:143], v[196:199], v[92:95]
	v_mfma_f32_16x16x32_bf16 v[88:91], v[156:159], v[196:199], v[88:91]
	v_mfma_f32_16x16x32_bf16 v[76:79], v[140:143], v[204:207], v[76:79]
	v_mfma_f32_16x16x32_bf16 v[72:75], v[156:159], v[204:207], v[72:75]
	v_mfma_f32_16x16x32_bf16 v[124:127], v[144:147], v[184:187], v[124:127]
	v_mfma_f32_16x16x32_bf16 v[120:123], v[160:163], v[184:187], v[120:123]
	v_mfma_f32_16x16x32_bf16 v[108:111], v[144:147], v[192:195], v[108:111]
	v_mfma_f32_16x16x32_bf16 v[104:107], v[160:163], v[192:195], v[104:107]
	v_mfma_f32_16x16x32_bf16 v[92:95], v[144:147], v[200:203], v[92:95]
	v_mfma_f32_16x16x32_bf16 v[88:91], v[160:163], v[200:203], v[88:91]
	v_mfma_f32_16x16x32_bf16 v[76:79], v[144:147], v[208:211], v[76:79]
	v_mfma_f32_16x16x32_bf16 v[72:75], v[160:163], v[208:211], v[72:75]
	v_mfma_f32_16x16x32_bf16 v[116:119], v[164:167], v[180:183], v[116:119]
	v_mfma_f32_16x16x32_bf16 v[112:115], v[172:175], v[180:183], v[112:115]
	v_mfma_f32_16x16x32_bf16 v[100:103], v[164:167], v[188:191], v[100:103]
	v_mfma_f32_16x16x32_bf16 v[96:99], v[172:175], v[188:191], v[96:99]
	v_mfma_f32_16x16x32_bf16 v[84:87], v[164:167], v[196:199], v[84:87]
	v_mfma_f32_16x16x32_bf16 v[80:83], v[172:175], v[196:199], v[80:83]
	v_mfma_f32_16x16x32_bf16 v[68:71], v[164:167], v[204:207], v[68:71]
	v_mfma_f32_16x16x32_bf16 v[64:67], v[172:175], v[204:207], v[64:67]
	v_mfma_f32_16x16x32_bf16 v[116:119], v[168:171], v[184:187], v[116:119]
	v_mfma_f32_16x16x32_bf16 v[112:115], v[176:179], v[184:187], v[112:115]
	v_mfma_f32_16x16x32_bf16 v[100:103], v[168:171], v[192:195], v[100:103]
	v_mfma_f32_16x16x32_bf16 v[96:99], v[176:179], v[192:195], v[96:99]
	v_mfma_f32_16x16x32_bf16 v[84:87], v[168:171], v[200:203], v[84:87]
	v_mfma_f32_16x16x32_bf16 v[80:83], v[176:179], v[200:203], v[80:83]
	v_mfma_f32_16x16x32_bf16 v[68:71], v[168:171], v[208:211], v[68:71]
	v_mfma_f32_16x16x32_bf16 v[64:67], v[176:179], v[208:211], v[64:67]
	s_setprio 0
	s_barrier
	s_add_u32 s98, s30, s18
	s_addc_u32 s99, s31, s19
	s_add_u32 s100, s42, s18
	s_addc_u32 s101, s43, s19
	s_add_i32 s26, s56, s48
	s_mov_b32 m0, s26
	ds_read_b128 v[180:183], v154 offset:16384
	ds_read_b128 v[184:187], v154 offset:17408
	ds_read_b128 v[188:191], v154 offset:18432
	ds_read_b128 v[192:195], v154 offset:19456
	ds_read_b128 v[196:199], v154 offset:20480
	ds_read_b128 v[200:203], v154 offset:21504
	ds_read_b128 v[204:207], v154 offset:22528
	ds_read_b128 v[208:211], v154 offset:23552
	global_load_lds_dwordx4 v128, s[30:31]
	s_add_i32 m0, s26, 0x2000
	s_add_u32 s26, s30, 0x160000
	s_addc_u32 s27, s31, 0
	s_add_i32 s67, s57, s48
	global_load_lds_dwordx4 v130, s[30:31]
	s_mov_b32 m0, s67
	s_nop 0
	global_load_lds_dwordx4 v128, s[26:27]
	s_add_i32 m0, s67, 0x2000
	s_nop 0
	global_load_lds_dwordx4 v130, s[26:27]
	s_mov_b32 m0, s49
	s_nop 0
	global_load_lds_dwordx4 v128, s[42:43]
	s_mov_b32 m0, s50
	s_nop 0
	global_load_lds_dwordx4 v130, s[42:43]
	s_waitcnt vmcnt(8)
	s_waitcnt lgkmcnt(0)
	s_setprio 1
	s_barrier
	v_mfma_f32_16x16x32_bf16 v[60:63], v[140:143], v[180:183], v[60:63]
	v_mfma_f32_16x16x32_bf16 v[56:59], v[156:159], v[180:183], v[56:59]
	v_mfma_f32_16x16x32_bf16 v[44:47], v[140:143], v[188:191], v[44:47]
	v_mfma_f32_16x16x32_bf16 v[40:43], v[156:159], v[188:191], v[40:43]
	v_mfma_f32_16x16x32_bf16 v[28:31], v[140:143], v[196:199], v[28:31]
	v_mfma_f32_16x16x32_bf16 v[24:27], v[156:159], v[196:199], v[24:27]
	v_mfma_f32_16x16x32_bf16 v[12:15], v[140:143], v[204:207], v[12:15]
	v_mfma_f32_16x16x32_bf16 v[8:11], v[156:159], v[204:207], v[8:11]
	v_mfma_f32_16x16x32_bf16 v[60:63], v[144:147], v[184:187], v[60:63]
	v_mfma_f32_16x16x32_bf16 v[56:59], v[160:163], v[184:187], v[56:59]
	v_mfma_f32_16x16x32_bf16 v[44:47], v[144:147], v[192:195], v[44:47]
	v_mfma_f32_16x16x32_bf16 v[40:43], v[160:163], v[192:195], v[40:43]
	v_mfma_f32_16x16x32_bf16 v[28:31], v[144:147], v[200:203], v[28:31]
	v_mfma_f32_16x16x32_bf16 v[24:27], v[160:163], v[200:203], v[24:27]
	v_mfma_f32_16x16x32_bf16 v[12:15], v[144:147], v[208:211], v[12:15]
	v_mfma_f32_16x16x32_bf16 v[8:11], v[160:163], v[208:211], v[8:11]
	v_mfma_f32_16x16x32_bf16 v[52:55], v[164:167], v[180:183], v[52:55]
	v_mfma_f32_16x16x32_bf16 v[48:51], v[172:175], v[180:183], v[48:51]
	v_mfma_f32_16x16x32_bf16 v[36:39], v[164:167], v[188:191], v[36:39]
	v_mfma_f32_16x16x32_bf16 v[32:35], v[172:175], v[188:191], v[32:35]
	v_mfma_f32_16x16x32_bf16 v[20:23], v[164:167], v[196:199], v[20:23]
	v_mfma_f32_16x16x32_bf16 v[16:19], v[172:175], v[196:199], v[16:19]
	v_mfma_f32_16x16x32_bf16 v[4:7], v[164:167], v[204:207], v[4:7]
	v_mfma_f32_16x16x32_bf16 v[0:3], v[172:175], v[204:207], v[0:3]
	v_mfma_f32_16x16x32_bf16 v[52:55], v[168:171], v[184:187], v[52:55]
	v_mfma_f32_16x16x32_bf16 v[48:51], v[176:179], v[184:187], v[48:51]
	v_mfma_f32_16x16x32_bf16 v[36:39], v[168:171], v[192:195], v[36:39]
	v_mfma_f32_16x16x32_bf16 v[32:35], v[176:179], v[192:195], v[32:35]
	v_mfma_f32_16x16x32_bf16 v[20:23], v[168:171], v[200:203], v[20:23]
	v_mfma_f32_16x16x32_bf16 v[16:19], v[176:179], v[200:203], v[16:19]
	v_mfma_f32_16x16x32_bf16 v[4:7], v[168:171], v[208:211], v[4:7]
	v_mfma_f32_16x16x32_bf16 v[0:3], v[176:179], v[208:211], v[0:3]
	s_setprio 0
	s_barrier
; #define PG8_STAGE(bufoff, gbase, voff) do { _Pragma("unroll") for (int _i = 0; _i < 2; ++_i) \
;         __builtin_amdgcn_global_load_lds((const unsigned*)((const char*)(gbase) + (voff)[_i]), (LAS unsigned*)(lds + (bufoff) + ldsw + _i * 8192), 16, 0, 0); } while (0)
; #define PG8_LDA(dst, b, h) do { _Pragma("unroll") for (int m = 0; m < 4; ++m) _Pragma("unroll") for (int k = 0; k < 2; ++k) dst[m][k] = *(const LAS bf16x8*)(lds + PG8_SA(b, h) + aoff + m * 2048 + k * 1024); } while (0)
; #define PG8_LDB(dst, b, h) do { _Pragma("unroll") for (int n = 0; n < 2; ++n) _Pragma("unroll") for (int k = 0; k < 2; ++k) dst[n][k] = *(const LAS bf16x8*)(lds + PG8_SB(b, h) + boff + n * 2048 + k * 1024); } while (0)
; #define PG8_WAIT_V(n) asm volatile("s_waitcnt vmcnt(" #n ")" ::: "memory")
; #define PG8_WAIT_L(n) asm volatile("s_waitcnt lgkmcnt(" #n ")" ::: "memory")
; #define PG8_BAR __builtin_amdgcn_s_barrier()
; #define PG8_SCHED __builtin_amdgcn_sched_barrier(0)
; template <class Epi, bool FP8 = false>
; __device__ __forceinline__ void gemm_phase(LAS unsigned char* lds, const Gemm g, const StaticOrder& S_, const Epi& E, const int tid) {
;     ...
;             PG8_LDB(B0, 1, 0); PG8_LDB(B1, 1, 1); PG8_SCHED; PG8_LDA(At, 1, 0); PG8_STAGE(PG8_SA(0, 1), a2 + hstepA, voffA);
;             PG8_WAIT_V(8); PG8_WAIT_L(0); PG8_BAR; PG8_MMA(0, 0, At, B0); PG8_MMA(0, 1, At, B1); PG8_BAR; PG8_SCHED;
;             PG8_LDA(At, 1, 1); PG8_STAGE(PG8_SB(1, 0), b3, voffB); PG8_STAGE(PG8_SB(1, 1), b3 + hstepB, voffB); PG8_STAGE(PG8_SA(1, 0), a3, voffA);
;             PG8_WAIT_V(8); PG8_WAIT_L(0); PG8_BAR; PG8_MMA(1, 0, At, B0); PG8_MMA(1, 1, At, B1); PG8_BAR; PG8_SCHED;
;         }
;         if (wr == 0) PG8_BAR;
	s_add_i32 s67, 0, 0x18000
	v_add_u32_e32 v155, s67, v150
	s_add_i32 s68, 0, 0x1c000
	ds_read_b128 v[140:143], v155
	ds_read_b128 v[144:147], v155 offset:1024
	ds_read_b128 v[156:159], v155 offset:2048
	ds_read_b128 v[160:163], v155 offset:3072
	v_add_u32_e32 v155, s68, v150
	ds_read_b128 v[164:167], v155
	ds_read_b128 v[168:171], v155 offset:1024
	ds_read_b128 v[172:175], v155 offset:2048
	ds_read_b128 v[176:179], v155 offset:3072
	s_add_u32 s26, s42, 0x160000
	s_addc_u32 s27, s43, 0
	s_mov_b32 m0, s51
	ds_read_b128 v[180:183], v154 offset:32768
	ds_read_b128 v[184:187], v154 offset:33792
	ds_read_b128 v[188:191], v154 offset:34816
	ds_read_b128 v[192:195], v154 offset:35840
	ds_read_b128 v[196:199], v154 offset:36864
	ds_read_b128 v[200:203], v154 offset:37888
	ds_read_b128 v[204:207], v154 offset:38912
	ds_read_b128 v[208:211], v154 offset:39936
	global_load_lds_dwordx4 v128, s[26:27]
	s_mov_b32 m0, s52
	s_nop 0
	global_load_lds_dwordx4 v130, s[26:27]
	s_waitcnt vmcnt(8)
	s_waitcnt lgkmcnt(0)
	s_setprio 1
	s_barrier
	v_mfma_f32_16x16x32_bf16 v[124:127], v[140:143], v[180:183], v[124:127]
	v_mfma_f32_16x16x32_bf16 v[120:123], v[156:159], v[180:183], v[120:123]
	v_mfma_f32_16x16x32_bf16 v[108:111], v[140:143], v[188:191], v[108:111]
	v_mfma_f32_16x16x32_bf16 v[104:107], v[156:159], v[188:191], v[104:107]
	v_mfma_f32_16x16x32_bf16 v[92:95], v[140:143], v[196:199], v[92:95]
	v_mfma_f32_16x16x32_bf16 v[88:91], v[156:159], v[196:199], v[88:91]
	v_mfma_f32_16x16x32_bf16 v[76:79], v[140:143], v[204:207], v[76:79]
	v_mfma_f32_16x16x32_bf16 v[72:75], v[156:159], v[204:207], v[72:75]
	v_mfma_f32_16x16x32_bf16 v[124:127], v[144:147], v[184:187], v[124:127]
	v_mfma_f32_16x16x32_bf16 v[120:123], v[160:163], v[184:187], v[120:123]
	v_mfma_f32_16x16x32_bf16 v[108:111], v[144:147], v[192:195], v[108:111]
	v_mfma_f32_16x16x32_bf16 v[104:107], v[160:163], v[192:195], v[104:107]
	v_mfma_f32_16x16x32_bf16 v[92:95], v[144:147], v[200:203], v[92:95]
	v_mfma_f32_16x16x32_bf16 v[88:91], v[160:163], v[200:203], v[88:91]
	v_mfma_f32_16x16x32_bf16 v[76:79], v[144:147], v[208:211], v[76:79]
	v_mfma_f32_16x16x32_bf16 v[72:75], v[160:163], v[208:211], v[72:75]
	v_mfma_f32_16x16x32_bf16 v[116:119], v[164:167], v[180:183], v[116:119]
	v_mfma_f32_16x16x32_bf16 v[112:115], v[172:175], v[180:183], v[112:115]
	v_mfma_f32_16x16x32_bf16 v[100:103], v[164:167], v[188:191], v[100:103]
	v_mfma_f32_16x16x32_bf16 v[96:99], v[172:175], v[188:191], v[96:99]
	v_mfma_f32_16x16x32_bf16 v[84:87], v[164:167], v[196:199], v[84:87]
	v_mfma_f32_16x16x32_bf16 v[80:83], v[172:175], v[196:199], v[80:83]
	v_mfma_f32_16x16x32_bf16 v[68:71], v[164:167], v[204:207], v[68:71]
	v_mfma_f32_16x16x32_bf16 v[64:67], v[172:175], v[204:207], v[64:67]
	v_mfma_f32_16x16x32_bf16 v[116:119], v[168:171], v[184:187], v[116:119]
	v_mfma_f32_16x16x32_bf16 v[112:115], v[176:179], v[184:187], v[112:115]
	v_mfma_f32_16x16x32_bf16 v[100:103], v[168:171], v[192:195], v[100:103]
	v_mfma_f32_16x16x32_bf16 v[96:99], v[176:179], v[192:195], v[96:99]
	v_mfma_f32_16x16x32_bf16 v[84:87], v[168:171], v[200:203], v[84:87]
	v_mfma_f32_16x16x32_bf16 v[80:83], v[176:179], v[200:203], v[80:83]
	v_mfma_f32_16x16x32_bf16 v[68:71], v[168:171], v[208:211], v[68:71]
	v_mfma_f32_16x16x32_bf16 v[64:67], v[176:179], v[208:211], v[64:67]
	s_setprio 0
	s_barrier
	s_add_i32 s26, s67, s48
	s_mov_b32 m0, s26
	ds_read_b128 v[180:183], v154 offset:49152
	ds_read_b128 v[184:187], v154 offset:50176
	ds_read_b128 v[188:191], v154 offset:51200
	ds_read_b128 v[192:195], v154 offset:52224
	ds_read_b128 v[196:199], v154 offset:53248
	ds_read_b128 v[200:203], v154 offset:54272
	ds_read_b128 v[204:207], v154 offset:55296
	ds_read_b128 v[208:211], v154 offset:56320
	global_load_lds_dwordx4 v128, s[98:99]
	s_add_i32 m0, s26, 0x2000
	s_add_u32 s26, s30, 0x160080
	s_addc_u32 s27, s31, 0
	s_add_i32 s30, s68, s48
	global_load_lds_dwordx4 v130, s[98:99]
	s_mov_b32 m0, s30
	s_nop 0
	global_load_lds_dwordx4 v128, s[26:27]
	s_add_i32 m0, s30, 0x2000
	s_nop 0
	global_load_lds_dwordx4 v130, s[26:27]
	s_mov_b32 m0, s54
	s_nop 0
	global_load_lds_dwordx4 v128, s[100:101]
	s_mov_b32 m0, s55
	s_nop 0
	global_load_lds_dwordx4 v130, s[100:101]
	s_waitcnt vmcnt(8)
	s_waitcnt lgkmcnt(0)
	s_setprio 1
	s_barrier
	v_mfma_f32_16x16x32_bf16 v[60:63], v[140:143], v[180:183], v[60:63]
	v_mfma_f32_16x16x32_bf16 v[56:59], v[156:159], v[180:183], v[56:59]
	v_mfma_f32_16x16x32_bf16 v[44:47], v[140:143], v[188:191], v[44:47]
	v_mfma_f32_16x16x32_bf16 v[40:43], v[156:159], v[188:191], v[40:43]
	v_mfma_f32_16x16x32_bf16 v[28:31], v[140:143], v[196:199], v[28:31]
	v_mfma_f32_16x16x32_bf16 v[24:27], v[156:159], v[196:199], v[24:27]
	v_mfma_f32_16x16x32_bf16 v[12:15], v[140:143], v[204:207], v[12:15]
	v_mfma_f32_16x16x32_bf16 v[8:11], v[156:159], v[204:207], v[8:11]
	v_mfma_f32_16x16x32_bf16 v[60:63], v[144:147], v[184:187], v[60:63]
	v_mfma_f32_16x16x32_bf16 v[56:59], v[160:163], v[184:187], v[56:59]
	v_mfma_f32_16x16x32_bf16 v[44:47], v[144:147], v[192:195], v[44:47]
	v_mfma_f32_16x16x32_bf16 v[40:43], v[160:163], v[192:195], v[40:43]
	v_mfma_f32_16x16x32_bf16 v[28:31], v[144:147], v[200:203], v[28:31]
	v_mfma_f32_16x16x32_bf16 v[24:27], v[160:163], v[200:203], v[24:27]
	v_mfma_f32_16x16x32_bf16 v[12:15], v[144:147], v[208:211], v[12:15]
	v_mfma_f32_16x16x32_bf16 v[8:11], v[160:163], v[208:211], v[8:11]
	v_mfma_f32_16x16x32_bf16 v[52:55], v[164:167], v[180:183], v[52:55]
	v_mfma_f32_16x16x32_bf16 v[48:51], v[172:175], v[180:183], v[48:51]
	v_mfma_f32_16x16x32_bf16 v[36:39], v[164:167], v[188:191], v[36:39]
	v_mfma_f32_16x16x32_bf16 v[32:35], v[172:175], v[188:191], v[32:35]
	v_mfma_f32_16x16x32_bf16 v[20:23], v[164:167], v[196:199], v[20:23]
	v_mfma_f32_16x16x32_bf16 v[16:19], v[172:175], v[196:199], v[16:19]
	v_mfma_f32_16x16x32_bf16 v[4:7], v[164:167], v[204:207], v[4:7]
	v_mfma_f32_16x16x32_bf16 v[0:3], v[172:175], v[204:207], v[0:3]
	v_mfma_f32_16x16x32_bf16 v[52:55], v[168:171], v[184:187], v[52:55]
	v_mfma_f32_16x16x32_bf16 v[48:51], v[176:179], v[184:187], v[48:51]
	v_mfma_f32_16x16x32_bf16 v[36:39], v[168:171], v[192:195], v[36:39]
	v_mfma_f32_16x16x32_bf16 v[32:35], v[176:179], v[192:195], v[32:35]
	v_mfma_f32_16x16x32_bf16 v[20:23], v[168:171], v[200:203], v[20:23]
	v_mfma_f32_16x16x32_bf16 v[16:19], v[176:179], v[200:203], v[16:19]
	v_mfma_f32_16x16x32_bf16 v[4:7], v[168:171], v[208:211], v[4:7]
	v_mfma_f32_16x16x32_bf16 v[0:3], v[176:179], v[208:211], v[0:3]
	s_setprio 0
	s_barrier
	s_add_i32 s66, s66, 2
	s_add_u32 s62, s62, 0x100
	s_addc_u32 s63, s63, 0
	s_cmpk_gt_u32 s66, 0x55
	s_mov_b64 s[26:27], s[28:29]
	s_cbranch_scc0 .LBB0_1420
	s_and_b64 vcc, exec, s[20:21]
	s_cbranch_vccz .LBB0_1423
	s_barrier

; __global__ void __launch_bounds__(512, 2) fwd_megakernel(Params P) {
	.amdhsa_kernel _Z14fwd_megakernel6Params
		.amdhsa_group_segment_fixed_size 0
		.amdhsa_private_segment_fixed_size 0
		.amdhsa_kernarg_size 712
		.amdhsa_user_sgpr_count 2
		.amdhsa_user_sgpr_dispatch_ptr 0
		.amdhsa_user_sgpr_queue_ptr 0
		.amdhsa_user_sgpr_kernarg_segment_ptr 1
		.amdhsa_user_sgpr_dispatch_id 0
		.amdhsa_user_sgpr_kernarg_preload_length 0
		.amdhsa_user_sgpr_kernarg_preload_offset 0
		.amdhsa_user_sgpr_private_segment_size 0
		.amdhsa_uses_dynamic_stack 0
		.amdhsa_enable_private_segment 0
		.amdhsa_system_sgpr_workgroup_id_x 1
		.amdhsa_system_sgpr_workgroup_id_y 0
		.amdhsa_system_sgpr_workgroup_id_z 0
		.amdhsa_system_sgpr_workgroup_info 0
		.amdhsa_system_vgpr_workitem_id 2
		.amdhsa_next_free_vgpr 249
		.amdhsa_next_free_sgpr 102
		.amdhsa_accum_offset 252
		.amdhsa_reserve_vcc 1
		.amdhsa_float_round_mode_32 0
		.amdhsa_float_round_mode_16_64 0
		.amdhsa_float_denorm_mode_32 3
		.amdhsa_float_denorm_mode_16_64 3
		.amdhsa_dx10_clamp 1
		.amdhsa_ieee_mode 1
		.amdhsa_fp16_overflow 0
		.amdhsa_tg_split 0
		.amdhsa_exception_fp_ieee_invalid_op 0
		.amdhsa_exception_fp_denorm_src 0
		.amdhsa_exception_fp_ieee_div_zero 0
		.amdhsa_exception_fp_ieee_overflow 0
		.amdhsa_exception_fp_ieee_underflow 0
		.amdhsa_exception_fp_ieee_inexact 0
		.amdhsa_exception_int_div_zero 0
	.end_amdhsa_kernel
